# all 7 GEMM K-loops: LDS-DMA loads use SGPR base + 32-bit lane offset instead of 64-bit per-lane addresses
# speedup vs baseline: 1.0121x; 1.0121x over previous
; #define PG8_STAGE(bufoff, gbase, voff) do { _Pragma("unroll") for (int _i = 0; _i < 2; ++_i) \
;         __builtin_amdgcn_global_load_lds((const unsigned*)((const char*)(gbase) + (voff)[_i]), (LAS unsigned*)(lds + (bufoff) + ldsw + _i * 8192), 16, 0, 0); } while (0)
; #define PG8_LDA(dst, b, h) do { _Pragma("unroll") for (int m = 0; m < 4; ++m) _Pragma("unroll") for (int k = 0; k < 2; ++k) dst[m][k] = *(const LAS bf16x8*)(lds + PG8_SA(b, h) + aoff + m * 2048 + k * 1024); } while (0)
; #define PG8_LDB(dst, b, h) do { _Pragma("unroll") for (int n = 0; n < 2; ++n) _Pragma("unroll") for (int k = 0; k < 2; ++k) dst[n][k] = *(const LAS bf16x8*)(lds + PG8_SB(b, h) + boff + n * 2048 + k * 1024); } while (0)
; template <class Epi, bool ALIGN_EPI, bool SPLITA>
; __device__ __forceinline__ void gemm_phase(LAS unsigned char* lds, const Gemm g, const StaticOrder& S, const Epi& E) {
;     ...
;                 a1 = (t + 1 < g.ksplit) ? cA + (size_t)(t + 1) * kstep : cA2 + (size_t)(t + 1 - g.ksplit) * 2048;
;                 a2 = last ? nA : ((t + 2 < g.ksplit) ? cA + (size_t)(t + 2) * kstep : cA2 + (size_t)(t + 2 - g.ksplit) * 2048);
;             } else { a1 = cA + kofs(t + 1); a2 = last ? nA : cA + kofs(t + 2); }
;             const char* b2 = last ? nB : cB + (size_t)(t + 2) * kstepB;
;             const bool s2a = SPLITA && (t + 1 >= g.ksplit), s2b = SPLITA && !last && (t + 2 >= g.ksplit);
;             const char* a3 = a2 + ((Epi::KSUB || s2b) ? (size_t)2048 : kstep); const char* b3 = b2 + kstepB;
;             const bool m1 = SPLITA && mirC && (t + 1 < g.ksplit), m2 = SPLITA && (last ? mirN : (mirC && (t + 2 < g.ksplit)));
;             const unsigned vo1[2] = {s2a ? voffA2[0] : m1 ? voffAm[0] : voffA[0], s2a ? voffA2[1] : m1 ? voffAm[1] : voffA[1]}, vo2[2] = {s2b ? voffA2[0] : m2 ? voffAm[0] : voffA[0], s2b ? voffA2[1] : m2 ? voffAm[1] : voffA[1]};
;             const char* a1h = m1 ? a1 - hstepA : a1 + hstepA; const char* a2h = m2 ? a2 - hstepA : a2 + hstepA;
;             PG8_LDB(B0, 0, 0); PG8_LDB(B1, 0, 1); PG8_SCHED; PG8_LDA(At, 0, 0); PG8_STAGE(PG8_SA(1, 1), a1h, vo1);
;             PG8_WAIT_V(8); PG8_WAIT_L(0); PG8_BAR; PG8_MMA(0, 0, At, B0); PG8_MMA(0, 1, At, B1); PG8_BAR; PG8_SCHED;
;             PG8_LDA(At, 0, 1); PG8_STAGE(PG8_SB(0, 0), b2, voffB); PG8_STAGE(PG8_SB(0, 1), b2 + hstepB, voffB); PG8_STAGE(PG8_SA(0, 0), a2, vo2);
.LBB0_229:
	ds_read_b128 v[130:133], v191
	ds_read_b128 v[134:137], v191 offset:1024
	ds_read_b128 v[138:141], v191 offset:2048
	ds_read_b128 v[142:145], v191 offset:3072
	ds_read_b128 v[146:149], v192
	ds_read_b128 v[150:153], v192 offset:1024
	ds_read_b128 v[154:157], v192 offset:2048
	ds_read_b128 v[158:161], v192 offset:3072
	s_add_u32 s0, s42, 0xfffc0080
	s_addc_u32 s1, s43, -1
	s_cmp_eq_u32 vcc_hi, 12
	s_cselect_b32 s47, s27, s1
	s_cselect_b32 s46, s33, s0
	s_cselect_b32 s45, s29, vcc_lo
	s_cselect_b32 s44, s60, s61
	s_add_i32 m0, s87, 0xc000
	ds_read_b128 v[198:201], v193
	ds_read_b128 v[202:205], v193 offset:1024
	ds_read_b128 v[206:209], v193 offset:2048
	ds_read_b128 v[210:213], v193 offset:3072
	ds_read_b128 v[214:217], v193 offset:4096
	ds_read_b128 v[218:221], v193 offset:5120
	ds_read_b128 v[222:225], v193 offset:6144
	ds_read_b128 v[226:229], v193 offset:7168
	global_load_lds_dwordx4 v182, s[42:43]
	s_add_i32 m0, s87, 0xe000
	s_nop 0
	global_load_lds_dwordx4 v184, s[42:43]
	s_waitcnt vmcnt(8)
	s_waitcnt lgkmcnt(0)
	s_barrier
	s_setprio 1
	s_waitcnt lgkmcnt(0)
	v_mfma_f32_16x16x32_bf16 v[126:129], v[130:133], v[198:201], v[126:129]
	v_mfma_f32_16x16x32_bf16 v[122:125], v[138:141], v[198:201], v[122:125]
	v_mfma_f32_16x16x32_bf16 v[110:113], v[130:133], v[206:209], v[110:113]
	v_mfma_f32_16x16x32_bf16 v[106:109], v[138:141], v[206:209], v[106:109]
	v_mfma_f32_16x16x32_bf16 v[94:97], v[130:133], v[214:217], v[94:97]
	v_mfma_f32_16x16x32_bf16 v[90:93], v[138:141], v[214:217], v[90:93]
	v_mfma_f32_16x16x32_bf16 v[78:81], v[130:133], v[222:225], v[78:81]
	v_mfma_f32_16x16x32_bf16 v[74:77], v[138:141], v[222:225], v[74:77]
	v_mfma_f32_16x16x32_bf16 v[126:129], v[134:137], v[202:205], v[126:129]
	v_mfma_f32_16x16x32_bf16 v[122:125], v[142:145], v[202:205], v[122:125]
	v_mfma_f32_16x16x32_bf16 v[110:113], v[134:137], v[210:213], v[110:113]
	v_mfma_f32_16x16x32_bf16 v[106:109], v[142:145], v[210:213], v[106:109]
	v_mfma_f32_16x16x32_bf16 v[94:97], v[134:137], v[218:221], v[94:97]
	v_mfma_f32_16x16x32_bf16 v[90:93], v[142:145], v[218:221], v[90:93]
	v_mfma_f32_16x16x32_bf16 v[78:81], v[134:137], v[226:229], v[78:81]
	v_mfma_f32_16x16x32_bf16 v[74:77], v[142:145], v[226:229], v[74:77]
	s_setprio 0
	s_setprio 1
	v_mfma_f32_16x16x32_bf16 v[118:121], v[146:149], v[198:201], v[118:121]
	v_mfma_f32_16x16x32_bf16 v[114:117], v[154:157], v[198:201], v[114:117]
	v_mfma_f32_16x16x32_bf16 v[102:105], v[146:149], v[206:209], v[102:105]
	v_mfma_f32_16x16x32_bf16 v[98:101], v[154:157], v[206:209], v[98:101]
	v_mfma_f32_16x16x32_bf16 v[86:89], v[146:149], v[214:217], v[86:89]
	v_mfma_f32_16x16x32_bf16 v[82:85], v[154:157], v[214:217], v[82:85]
	v_mfma_f32_16x16x32_bf16 v[70:73], v[146:149], v[222:225], v[70:73]
	v_mfma_f32_16x16x32_bf16 v[66:69], v[154:157], v[222:225], v[66:69]
	v_mfma_f32_16x16x32_bf16 v[118:121], v[150:153], v[202:205], v[118:121]
	v_mfma_f32_16x16x32_bf16 v[114:117], v[158:161], v[202:205], v[114:117]
	v_mfma_f32_16x16x32_bf16 v[102:105], v[150:153], v[210:213], v[102:105]
	v_mfma_f32_16x16x32_bf16 v[98:101], v[158:161], v[210:213], v[98:101]
	v_mfma_f32_16x16x32_bf16 v[86:89], v[150:153], v[218:221], v[86:89]
	v_mfma_f32_16x16x32_bf16 v[82:85], v[158:161], v[218:221], v[82:85]
	v_mfma_f32_16x16x32_bf16 v[70:73], v[150:153], v[226:229], v[70:73]
	v_mfma_f32_16x16x32_bf16 v[66:69], v[158:161], v[226:229], v[66:69]
	s_setprio 0
	s_barrier
	s_add_u32 s98, s44, s8
	s_addc_u32 s99, s45, s9
	s_add_u32 s100, s46, s8
	s_addc_u32 s101, s47, s9
	s_add_i32 s0, s97, s80
	s_mov_b32 m0, s0
	ds_read_b128 v[198:201], v193 offset:16384
	ds_read_b128 v[202:205], v193 offset:17408
	ds_read_b128 v[206:209], v193 offset:18432
	ds_read_b128 v[210:213], v193 offset:19456
	ds_read_b128 v[214:217], v193 offset:20480
	ds_read_b128 v[218:221], v193 offset:21504
	ds_read_b128 v[222:225], v193 offset:22528
	ds_read_b128 v[226:229], v193 offset:23552
	global_load_lds_dwordx4 v168, s[44:45]
	s_add_i32 m0, s0, 0x2000
	s_add_u32 s0, s44, 0x40000
	s_addc_u32 s1, s45, 0
	s_add_i32 s78, s64, s80
	global_load_lds_dwordx4 v164, s[44:45]
	s_mov_b32 m0, s78
	s_nop 0
	global_load_lds_dwordx4 v168, s[0:1]
	s_add_i32 m0, s78, 0x2000
	s_nop 0
	global_load_lds_dwordx4 v164, s[0:1]
	s_mov_b32 m0, s87
	s_nop 0
	global_load_lds_dwordx4 v170, s[46:47]
	s_mov_b32 m0, s88
	s_nop 0
	global_load_lds_dwordx4 v166, s[46:47]
	s_waitcnt vmcnt(8)
	s_waitcnt lgkmcnt(0)
	s_barrier
	s_setprio 1
	s_waitcnt lgkmcnt(0)
	v_mfma_f32_16x16x32_bf16 v[62:65], v[130:133], v[198:201], v[62:65]
	v_mfma_f32_16x16x32_bf16 v[58:61], v[138:141], v[198:201], v[58:61]
	v_mfma_f32_16x16x32_bf16 v[38:41], v[130:133], v[206:209], v[38:41]
	v_mfma_f32_16x16x32_bf16 v[34:37], v[138:141], v[206:209], v[34:37]
	v_mfma_f32_16x16x32_bf16 v[22:25], v[130:133], v[214:217], v[22:25]
	v_mfma_f32_16x16x32_bf16 v[18:21], v[138:141], v[214:217], v[18:21]
	v_mfma_f32_16x16x32_bf16 v[6:9], v[130:133], v[222:225], v[6:9]
	v_mfma_f32_16x16x32_bf16 v[2:5], v[138:141], v[222:225], v[2:5]
	v_mfma_f32_16x16x32_bf16 v[62:65], v[134:137], v[202:205], v[62:65]
	v_mfma_f32_16x16x32_bf16 v[58:61], v[142:145], v[202:205], v[58:61]
	v_mfma_f32_16x16x32_bf16 v[38:41], v[134:137], v[210:213], v[38:41]
	v_mfma_f32_16x16x32_bf16 v[34:37], v[142:145], v[210:213], v[34:37]
	v_mfma_f32_16x16x32_bf16 v[22:25], v[134:137], v[218:221], v[22:25]
	v_mfma_f32_16x16x32_bf16 v[18:21], v[142:145], v[218:221], v[18:21]
	v_mfma_f32_16x16x32_bf16 v[6:9], v[134:137], v[226:229], v[6:9]
	v_mfma_f32_16x16x32_bf16 v[2:5], v[142:145], v[226:229], v[2:5]
	s_setprio 0
	s_setprio 1
	v_mfma_f32_16x16x32_bf16 v[54:57], v[146:149], v[198:201], v[54:57]
	v_mfma_f32_16x16x32_bf16 v[50:53], v[154:157], v[198:201], v[50:53]
	v_mfma_f32_16x16x32_bf16 v[42:45], v[146:149], v[206:209], v[42:45]
	v_mfma_f32_16x16x32_bf16 v[46:49], v[154:157], v[206:209], v[46:49]
	v_mfma_f32_16x16x32_bf16 v[26:29], v[146:149], v[214:217], v[26:29]
	v_mfma_f32_16x16x32_bf16 v[30:33], v[154:157], v[214:217], v[30:33]
	v_mfma_f32_16x16x32_bf16 v[10:13], v[146:149], v[222:225], v[10:13]
	v_mfma_f32_16x16x32_bf16 v[14:17], v[154:157], v[222:225], v[14:17]
	v_mfma_f32_16x16x32_bf16 v[54:57], v[150:153], v[202:205], v[54:57]
	v_mfma_f32_16x16x32_bf16 v[50:53], v[158:161], v[202:205], v[50:53]
	v_mfma_f32_16x16x32_bf16 v[42:45], v[150:153], v[210:213], v[42:45]
	v_mfma_f32_16x16x32_bf16 v[46:49], v[158:161], v[210:213], v[46:49]
	v_mfma_f32_16x16x32_bf16 v[26:29], v[150:153], v[218:221], v[26:29]
	v_mfma_f32_16x16x32_bf16 v[30:33], v[158:161], v[218:221], v[30:33]
	v_mfma_f32_16x16x32_bf16 v[10:13], v[150:153], v[226:229], v[10:13]
	v_mfma_f32_16x16x32_bf16 v[14:17], v[158:161], v[226:229], v[14:17]
	s_setprio 0
	s_barrier
; #define PG8_STAGE(bufoff, gbase, voff) do { _Pragma("unroll") for (int _i = 0; _i < 2; ++_i) \
;         __builtin_amdgcn_global_load_lds((const unsigned*)((const char*)(gbase) + (voff)[_i]), (LAS unsigned*)(lds + (bufoff) + ldsw + _i * 8192), 16, 0, 0); } while (0)
; #define PG8_LDA(dst, b, h) do { _Pragma("unroll") for (int m = 0; m < 4; ++m) _Pragma("unroll") for (int k = 0; k < 2; ++k) dst[m][k] = *(const LAS bf16x8*)(lds + PG8_SA(b, h) + aoff + m * 2048 + k * 1024); } while (0)
; #define PG8_LDB(dst, b, h) do { _Pragma("unroll") for (int n = 0; n < 2; ++n) _Pragma("unroll") for (int k = 0; k < 2; ++k) dst[n][k] = *(const LAS bf16x8*)(lds + PG8_SB(b, h) + boff + n * 2048 + k * 1024); } while (0)
; #define PG8_MMA(ai, bj, At, Bt) do { __builtin_amdgcn_s_setprio(1); _Pragma("unroll") for (int m = 0; m < 4; ++m) _Pragma("unroll") for (int n = 0; n < 2; ++n) _Pragma("unroll") for (int k = 0; k < 2; ++k) \
;         acc[ai][bj][m][n] = __builtin_amdgcn_mfma_f32_16x16x32_bf16(Bt[n][k], At[m][k], acc[ai][bj][m][n], 0, 0, 0); __builtin_amdgcn_s_setprio(0); } while (0)
; #define PG8_WAIT_V(n) asm volatile("s_waitcnt vmcnt(" #n ")" ::: "memory")
; #define PG8_WAIT_L(n) asm volatile("s_waitcnt lgkmcnt(" #n ")" ::: "memory")
; #define PG8_BAR __builtin_amdgcn_s_barrier()
; #define PG8_SCHED __builtin_amdgcn_sched_barrier(0)
; template <class Epi, bool ALIGN_EPI, bool SPLITA>
; __device__ __forceinline__ void gemm_phase(LAS unsigned char* lds, const Gemm g, const StaticOrder& S, const Epi& E) {
;     ...
;             PG8_WAIT_V(8); PG8_WAIT_L(0); PG8_BAR; PG8_MMA(1, 0, At, B0); PG8_MMA(1, 1, At, B1); PG8_BAR; PG8_SCHED;
;             PG8_LDB(B0, 1, 0); PG8_LDB(B1, 1, 1); PG8_SCHED; PG8_LDA(At, 1, 0); PG8_STAGE(PG8_SA(0, 1), a2h, vo2);
;             PG8_WAIT_V(8); PG8_WAIT_L(0); PG8_BAR; PG8_MMA(0, 0, At, B0); PG8_MMA(0, 1, At, B1); PG8_BAR; PG8_SCHED;
;             PG8_LDA(At, 1, 1); PG8_STAGE(PG8_SB(1, 0), b3, voffB); PG8_STAGE(PG8_SB(1, 1), b3 + hstepB, voffB); PG8_STAGE(PG8_SA(1, 0), a3, vo2);
;             PG8_WAIT_V(8); PG8_WAIT_L(0); PG8_BAR; PG8_MMA(1, 0, At, B0); PG8_MMA(1, 1, At, B1); PG8_BAR; PG8_SCHED;
;         }
	s_add_i32 s78, 0, 0x18000
	s_add_i32 s89, 0, 0x1c000
	v_add_u32_e32 v142, s78, v163
	v_add_u32_e32 v158, s89, v163
	ds_read_b128 v[130:133], v142
	ds_read_b128 v[134:137], v142 offset:1024
	ds_read_b128 v[138:141], v142 offset:2048
	ds_read_b128 v[142:145], v142 offset:3072
	ds_read_b128 v[146:149], v158
	ds_read_b128 v[150:153], v158 offset:1024
	ds_read_b128 v[154:157], v158 offset:2048
	ds_read_b128 v[158:161], v158 offset:3072
	s_add_u32 s0, s46, 0x40000
	s_addc_u32 s1, s47, 0
	s_mov_b32 m0, s90
	ds_read_b128 v[198:201], v193 offset:32768
	ds_read_b128 v[202:205], v193 offset:33792
	ds_read_b128 v[206:209], v193 offset:34816
	ds_read_b128 v[210:213], v193 offset:35840
	ds_read_b128 v[214:217], v193 offset:36864
	ds_read_b128 v[218:221], v193 offset:37888
	ds_read_b128 v[222:225], v193 offset:38912
	ds_read_b128 v[226:229], v193 offset:39936
	global_load_lds_dwordx4 v170, s[0:1]
	s_mov_b32 m0, s91
	s_nop 0
	global_load_lds_dwordx4 v166, s[0:1]
	s_waitcnt vmcnt(8)
	s_waitcnt lgkmcnt(0)
	s_barrier
	s_setprio 1
	s_waitcnt lgkmcnt(0)
	v_mfma_f32_16x16x32_bf16 v[126:129], v[130:133], v[198:201], v[126:129]
	v_mfma_f32_16x16x32_bf16 v[122:125], v[138:141], v[198:201], v[122:125]
	v_mfma_f32_16x16x32_bf16 v[110:113], v[130:133], v[206:209], v[110:113]
	v_mfma_f32_16x16x32_bf16 v[106:109], v[138:141], v[206:209], v[106:109]
	v_mfma_f32_16x16x32_bf16 v[94:97], v[130:133], v[214:217], v[94:97]
	v_mfma_f32_16x16x32_bf16 v[90:93], v[138:141], v[214:217], v[90:93]
	v_mfma_f32_16x16x32_bf16 v[78:81], v[130:133], v[222:225], v[78:81]
	v_mfma_f32_16x16x32_bf16 v[74:77], v[138:141], v[222:225], v[74:77]
	v_mfma_f32_16x16x32_bf16 v[126:129], v[134:137], v[202:205], v[126:129]
	v_mfma_f32_16x16x32_bf16 v[122:125], v[142:145], v[202:205], v[122:125]
	v_mfma_f32_16x16x32_bf16 v[110:113], v[134:137], v[210:213], v[110:113]
	v_mfma_f32_16x16x32_bf16 v[106:109], v[142:145], v[210:213], v[106:109]
	v_mfma_f32_16x16x32_bf16 v[94:97], v[134:137], v[218:221], v[94:97]
	v_mfma_f32_16x16x32_bf16 v[90:93], v[142:145], v[218:221], v[90:93]
	v_mfma_f32_16x16x32_bf16 v[78:81], v[134:137], v[226:229], v[78:81]
	v_mfma_f32_16x16x32_bf16 v[74:77], v[142:145], v[226:229], v[74:77]
	s_setprio 0
	s_setprio 1
	v_mfma_f32_16x16x32_bf16 v[118:121], v[146:149], v[198:201], v[118:121]
	v_mfma_f32_16x16x32_bf16 v[114:117], v[154:157], v[198:201], v[114:117]
	v_mfma_f32_16x16x32_bf16 v[102:105], v[146:149], v[206:209], v[102:105]
	v_mfma_f32_16x16x32_bf16 v[98:101], v[154:157], v[206:209], v[98:101]
	v_mfma_f32_16x16x32_bf16 v[86:89], v[146:149], v[214:217], v[86:89]
	v_mfma_f32_16x16x32_bf16 v[82:85], v[154:157], v[214:217], v[82:85]
	v_mfma_f32_16x16x32_bf16 v[70:73], v[146:149], v[222:225], v[70:73]
	v_mfma_f32_16x16x32_bf16 v[66:69], v[154:157], v[222:225], v[66:69]
	v_mfma_f32_16x16x32_bf16 v[118:121], v[150:153], v[202:205], v[118:121]
	v_mfma_f32_16x16x32_bf16 v[114:117], v[158:161], v[202:205], v[114:117]
	v_mfma_f32_16x16x32_bf16 v[102:105], v[150:153], v[210:213], v[102:105]
	v_mfma_f32_16x16x32_bf16 v[98:101], v[158:161], v[210:213], v[98:101]
	v_mfma_f32_16x16x32_bf16 v[86:89], v[150:153], v[218:221], v[86:89]
	v_mfma_f32_16x16x32_bf16 v[82:85], v[158:161], v[218:221], v[82:85]
	v_mfma_f32_16x16x32_bf16 v[70:73], v[150:153], v[226:229], v[70:73]
	v_mfma_f32_16x16x32_bf16 v[66:69], v[158:161], v[226:229], v[66:69]
	s_setprio 0
	s_barrier
	s_add_i32 s0, s78, s80
	s_mov_b32 m0, s0
	ds_read_b128 v[198:201], v193 offset:49152
	ds_read_b128 v[202:205], v193 offset:50176
	ds_read_b128 v[206:209], v193 offset:51200
	ds_read_b128 v[210:213], v193 offset:52224
	ds_read_b128 v[214:217], v193 offset:53248
	ds_read_b128 v[218:221], v193 offset:54272
	ds_read_b128 v[222:225], v193 offset:55296
	ds_read_b128 v[226:229], v193 offset:56320
	global_load_lds_dwordx4 v168, s[98:99]
	s_add_i32 m0, s0, 0x2000
	s_add_u32 s0, s44, 0x40080
	s_addc_u32 s1, s45, 0
	s_add_i32 s44, s89, s80
	global_load_lds_dwordx4 v164, s[98:99]
	s_mov_b32 m0, s44
	s_nop 0
	global_load_lds_dwordx4 v168, s[0:1]
	s_add_i32 m0, s44, 0x2000
	s_nop 0
	global_load_lds_dwordx4 v164, s[0:1]
	s_mov_b32 m0, s94
	s_nop 0
	global_load_lds_dwordx4 v170, s[100:101]
	s_mov_b32 m0, s95
	s_nop 0
	global_load_lds_dwordx4 v166, s[100:101]
	s_waitcnt vmcnt(8)
	s_waitcnt lgkmcnt(0)
	s_barrier
	s_setprio 1
	s_waitcnt lgkmcnt(0)
	v_mfma_f32_16x16x32_bf16 v[62:65], v[130:133], v[198:201], v[62:65]
	v_mfma_f32_16x16x32_bf16 v[58:61], v[138:141], v[198:201], v[58:61]
	v_mfma_f32_16x16x32_bf16 v[38:41], v[130:133], v[206:209], v[38:41]
	v_mfma_f32_16x16x32_bf16 v[34:37], v[138:141], v[206:209], v[34:37]
	v_mfma_f32_16x16x32_bf16 v[22:25], v[130:133], v[214:217], v[22:25]
	v_mfma_f32_16x16x32_bf16 v[18:21], v[138:141], v[214:217], v[18:21]
	v_mfma_f32_16x16x32_bf16 v[6:9], v[130:133], v[222:225], v[6:9]
	v_mfma_f32_16x16x32_bf16 v[2:5], v[138:141], v[222:225], v[2:5]
	v_mfma_f32_16x16x32_bf16 v[62:65], v[134:137], v[202:205], v[62:65]
	v_mfma_f32_16x16x32_bf16 v[58:61], v[142:145], v[202:205], v[58:61]
	v_mfma_f32_16x16x32_bf16 v[38:41], v[134:137], v[210:213], v[38:41]
	v_mfma_f32_16x16x32_bf16 v[34:37], v[142:145], v[210:213], v[34:37]
	v_mfma_f32_16x16x32_bf16 v[22:25], v[134:137], v[218:221], v[22:25]
	v_mfma_f32_16x16x32_bf16 v[18:21], v[142:145], v[218:221], v[18:21]
	v_mfma_f32_16x16x32_bf16 v[6:9], v[134:137], v[226:229], v[6:9]
	v_mfma_f32_16x16x32_bf16 v[2:5], v[142:145], v[226:229], v[2:5]
	s_setprio 0
	s_setprio 1
	v_mfma_f32_16x16x32_bf16 v[54:57], v[146:149], v[198:201], v[54:57]
	v_mfma_f32_16x16x32_bf16 v[50:53], v[154:157], v[198:201], v[50:53]
	v_mfma_f32_16x16x32_bf16 v[42:45], v[146:149], v[206:209], v[42:45]
	v_mfma_f32_16x16x32_bf16 v[46:49], v[154:157], v[206:209], v[46:49]
	v_mfma_f32_16x16x32_bf16 v[26:29], v[146:149], v[214:217], v[26:29]
	v_mfma_f32_16x16x32_bf16 v[30:33], v[154:157], v[214:217], v[30:33]
	v_mfma_f32_16x16x32_bf16 v[10:13], v[146:149], v[222:225], v[10:13]
	v_mfma_f32_16x16x32_bf16 v[14:17], v[154:157], v[222:225], v[14:17]
	v_mfma_f32_16x16x32_bf16 v[54:57], v[150:153], v[202:205], v[54:57]
	v_mfma_f32_16x16x32_bf16 v[50:53], v[158:161], v[202:205], v[50:53]
	v_mfma_f32_16x16x32_bf16 v[42:45], v[150:153], v[210:213], v[42:45]
	v_mfma_f32_16x16x32_bf16 v[46:49], v[158:161], v[210:213], v[46:49]
	v_mfma_f32_16x16x32_bf16 v[26:29], v[150:153], v[218:221], v[26:29]
	v_mfma_f32_16x16x32_bf16 v[30:33], v[158:161], v[218:221], v[30:33]
	v_mfma_f32_16x16x32_bf16 v[10:13], v[150:153], v[226:229], v[10:13]
	v_mfma_f32_16x16x32_bf16 v[14:17], v[158:161], v[226:229], v[14:17]
	s_setprio 0
	s_barrier
	s_add_i32 vcc_hi, vcc_hi, 2
	s_add_u32 s42, s42, 0x100
	s_addc_u32 s43, s43, 0
	s_add_u32 s61, s61, 0x100
	s_addc_u32 vcc_lo, vcc_lo, 0
	s_cmp_gt_u32 vcc_hi, 13
	s_cbranch_scc0 .LBB0_229
	s_and_b64 vcc, exec, s[12:13]
	s_cbranch_vccz .LBB0_232
	s_barrier

; #define PG8_STAGE(bufoff, gbase, voff) do { _Pragma("unroll") for (int _i = 0; _i < 2; ++_i) \
;         __builtin_amdgcn_global_load_lds((const unsigned*)((const char*)(gbase) + (voff)[_i]), (LAS unsigned*)(lds + (bufoff) + ldsw + _i * 8192), 16, 0, 0); } while (0)
; #define PG8_LDA(dst, b, h) do { _Pragma("unroll") for (int m = 0; m < 4; ++m) _Pragma("unroll") for (int k = 0; k < 2; ++k) dst[m][k] = *(const LAS bf16x8*)(lds + PG8_SA(b, h) + aoff + m * 2048 + k * 1024); } while (0)
; #define PG8_LDB(dst, b, h) do { _Pragma("unroll") for (int n = 0; n < 2; ++n) _Pragma("unroll") for (int k = 0; k < 2; ++k) dst[n][k] = *(const LAS bf16x8*)(lds + PG8_SB(b, h) + boff + n * 2048 + k * 1024); } while (0)
; template <class Epi, bool ALIGN_EPI, bool SPLITA>
; __device__ __forceinline__ void gemm_phase(LAS unsigned char* lds, const Gemm g, const StaticOrder& S, const Epi& E) {
;     ...
;                 a1 = (t + 1 < g.ksplit) ? cA + (size_t)(t + 1) * kstep : cA2 + (size_t)(t + 1 - g.ksplit) * 2048;
;                 a2 = last ? nA : ((t + 2 < g.ksplit) ? cA + (size_t)(t + 2) * kstep : cA2 + (size_t)(t + 2 - g.ksplit) * 2048);
;             } else { a1 = cA + kofs(t + 1); a2 = last ? nA : cA + kofs(t + 2); }
;             const char* b2 = last ? nB : cB + (size_t)(t + 2) * kstepB;
;             const bool s2a = SPLITA && (t + 1 >= g.ksplit), s2b = SPLITA && !last && (t + 2 >= g.ksplit);
;             const char* a3 = a2 + ((Epi::KSUB || s2b) ? (size_t)2048 : kstep); const char* b3 = b2 + kstepB;
;             const bool m1 = SPLITA && mirC && (t + 1 < g.ksplit), m2 = SPLITA && (last ? mirN : (mirC && (t + 2 < g.ksplit)));
;             const unsigned vo1[2] = {s2a ? voffA2[0] : m1 ? voffAm[0] : voffA[0], s2a ? voffA2[1] : m1 ? voffAm[1] : voffA[1]}, vo2[2] = {s2b ? voffA2[0] : m2 ? voffAm[0] : voffA[0], s2b ? voffA2[1] : m2 ? voffAm[1] : voffA[1]};
;             const char* a1h = m1 ? a1 - hstepA : a1 + hstepA; const char* a2h = m2 ? a2 - hstepA : a2 + hstepA;
;             PG8_LDB(B0, 0, 0); PG8_LDB(B1, 0, 1); PG8_SCHED; PG8_LDA(At, 0, 0); PG8_STAGE(PG8_SA(1, 1), a1h, vo1);
;             PG8_WAIT_V(8); PG8_WAIT_L(0); PG8_BAR; PG8_MMA(0, 0, At, B0); PG8_MMA(0, 1, At, B1); PG8_BAR; PG8_SCHED;
;             PG8_LDA(At, 0, 1); PG8_STAGE(PG8_SB(0, 0), b2, voffB); PG8_STAGE(PG8_SB(0, 1), b2 + hstepB, voffB); PG8_STAGE(PG8_SA(0, 0), a2, vo2);
.LBB0_265:
	ds_read_b128 v[146:149], v152
	ds_read_b128 v[156:159], v152 offset:1024
	ds_read_b128 v[164:167], v152 offset:2048
	ds_read_b128 v[168:171], v152 offset:3072
	ds_read_b128 v[172:175], v153
	ds_read_b128 v[176:179], v153 offset:1024
	ds_read_b128 v[180:183], v153 offset:2048
	ds_read_b128 v[184:187], v153 offset:3072
	s_add_u32 s44, s0, 0xfffc0080
	s_addc_u32 s45, s1, -1
	s_cmp_eq_u32 s91, 12
	s_cselect_b32 s47, s13, s45
	s_cselect_b32 s46, s27, s44
	s_cselect_b32 s45, s39, s90
	s_cselect_b32 s44, s38, s29
	s_add_i32 m0, s43, 0xc000
	ds_read_b128 v[188:191], v154
	ds_read_b128 v[192:195], v154 offset:1024
	ds_read_b128 v[196:199], v154 offset:2048
	ds_read_b128 v[200:203], v154 offset:3072
	ds_read_b128 v[204:207], v154 offset:4096
	ds_read_b128 v[208:211], v154 offset:5120
	ds_read_b128 v[212:215], v154 offset:6144
	ds_read_b128 v[216:219], v154 offset:7168
	global_load_lds_dwordx4 v138, s[0:1]
	s_add_i32 m0, s43, 0xe000
	s_nop 0
	global_load_lds_dwordx4 v140, s[0:1]
	s_waitcnt vmcnt(8)
	s_waitcnt lgkmcnt(0)
	s_barrier
	s_setprio 1
	s_waitcnt lgkmcnt(0)
	v_mfma_f32_16x16x32_bf16 v[126:129], v[146:149], v[188:191], v[126:129]
	v_mfma_f32_16x16x32_bf16 v[122:125], v[164:167], v[188:191], v[122:125]
	v_mfma_f32_16x16x32_bf16 v[110:113], v[146:149], v[196:199], v[110:113]
	v_mfma_f32_16x16x32_bf16 v[106:109], v[164:167], v[196:199], v[106:109]
	v_mfma_f32_16x16x32_bf16 v[94:97], v[146:149], v[204:207], v[94:97]
	v_mfma_f32_16x16x32_bf16 v[90:93], v[164:167], v[204:207], v[90:93]
	v_mfma_f32_16x16x32_bf16 v[78:81], v[146:149], v[212:215], v[78:81]
	v_mfma_f32_16x16x32_bf16 v[74:77], v[164:167], v[212:215], v[74:77]
	v_mfma_f32_16x16x32_bf16 v[126:129], v[156:159], v[192:195], v[126:129]
	v_mfma_f32_16x16x32_bf16 v[122:125], v[168:171], v[192:195], v[122:125]
	v_mfma_f32_16x16x32_bf16 v[110:113], v[156:159], v[200:203], v[110:113]
	v_mfma_f32_16x16x32_bf16 v[106:109], v[168:171], v[200:203], v[106:109]
	v_mfma_f32_16x16x32_bf16 v[94:97], v[156:159], v[208:211], v[94:97]
	v_mfma_f32_16x16x32_bf16 v[90:93], v[168:171], v[208:211], v[90:93]
	v_mfma_f32_16x16x32_bf16 v[78:81], v[156:159], v[216:219], v[78:81]
	v_mfma_f32_16x16x32_bf16 v[74:77], v[168:171], v[216:219], v[74:77]
	s_setprio 0
	s_setprio 1
	v_mfma_f32_16x16x32_bf16 v[118:121], v[172:175], v[188:191], v[118:121]
	v_mfma_f32_16x16x32_bf16 v[114:117], v[180:183], v[188:191], v[114:117]
	v_mfma_f32_16x16x32_bf16 v[102:105], v[172:175], v[196:199], v[102:105]
	v_mfma_f32_16x16x32_bf16 v[98:101], v[180:183], v[196:199], v[98:101]
	v_mfma_f32_16x16x32_bf16 v[86:89], v[172:175], v[204:207], v[86:89]
	v_mfma_f32_16x16x32_bf16 v[82:85], v[180:183], v[204:207], v[82:85]
	v_mfma_f32_16x16x32_bf16 v[70:73], v[172:175], v[212:215], v[70:73]
	v_mfma_f32_16x16x32_bf16 v[66:69], v[180:183], v[212:215], v[66:69]
	v_mfma_f32_16x16x32_bf16 v[118:121], v[176:179], v[192:195], v[118:121]
	v_mfma_f32_16x16x32_bf16 v[114:117], v[184:187], v[192:195], v[114:117]
	v_mfma_f32_16x16x32_bf16 v[102:105], v[176:179], v[200:203], v[102:105]
	v_mfma_f32_16x16x32_bf16 v[98:101], v[184:187], v[200:203], v[98:101]
	v_mfma_f32_16x16x32_bf16 v[86:89], v[176:179], v[208:211], v[86:89]
	v_mfma_f32_16x16x32_bf16 v[82:85], v[184:187], v[208:211], v[82:85]
	v_mfma_f32_16x16x32_bf16 v[70:73], v[176:179], v[216:219], v[70:73]
	v_mfma_f32_16x16x32_bf16 v[66:69], v[184:187], v[216:219], v[66:69]
	s_setprio 0
	s_barrier
	s_add_u32 s98, s44, s8
	s_addc_u32 s99, s45, s9
	s_add_u32 s100, s46, s8
	s_addc_u32 s101, s47, s9
	s_add_i32 s89, s79, s33
	s_mov_b32 m0, s89
	ds_read_b128 v[188:191], v154 offset:16384
	ds_read_b128 v[192:195], v154 offset:17408
	ds_read_b128 v[196:199], v154 offset:18432
	ds_read_b128 v[200:203], v154 offset:19456
	ds_read_b128 v[204:207], v154 offset:20480
	ds_read_b128 v[208:211], v154 offset:21504
	ds_read_b128 v[212:215], v154 offset:22528
	ds_read_b128 v[216:219], v154 offset:23552
	global_load_lds_dwordx4 v134, s[44:45]
	s_add_i32 m0, s89, 0x2000
	s_add_u32 s92, s44, 0x200000
	s_addc_u32 s93, s45, 0
	s_add_i32 s89, s80, s33
	global_load_lds_dwordx4 v130, s[44:45]
	s_mov_b32 m0, s89
	s_nop 0
	global_load_lds_dwordx4 v134, s[92:93]
	s_add_i32 m0, s89, 0x2000
	s_nop 0
	global_load_lds_dwordx4 v130, s[92:93]
	s_mov_b32 m0, s43
	s_nop 0
	global_load_lds_dwordx4 v136, s[46:47]
	s_mov_b32 m0, s60
	s_nop 0
	global_load_lds_dwordx4 v132, s[46:47]
	s_waitcnt vmcnt(8)
	s_waitcnt lgkmcnt(0)
	s_barrier
	s_setprio 1
	s_waitcnt lgkmcnt(0)
	v_mfma_f32_16x16x32_bf16 v[54:57], v[146:149], v[188:191], v[54:57]
	v_mfma_f32_16x16x32_bf16 v[50:53], v[164:167], v[188:191], v[50:53]
	v_mfma_f32_16x16x32_bf16 v[22:25], v[146:149], v[196:199], v[22:25]
	v_mfma_f32_16x16x32_bf16 v[18:21], v[164:167], v[196:199], v[18:21]
	v_mfma_f32_16x16x32_bf16 v[14:17], v[146:149], v[204:207], v[14:17]
	v_mfma_f32_16x16x32_bf16 v[10:13], v[164:167], v[204:207], v[10:13]
	v_mfma_f32_16x16x32_bf16 v[6:9], v[146:149], v[212:215], v[6:9]
	v_mfma_f32_16x16x32_bf16 v[2:5], v[164:167], v[212:215], v[2:5]
	v_mfma_f32_16x16x32_bf16 v[54:57], v[156:159], v[192:195], v[54:57]
	v_mfma_f32_16x16x32_bf16 v[50:53], v[168:171], v[192:195], v[50:53]
	v_mfma_f32_16x16x32_bf16 v[22:25], v[156:159], v[200:203], v[22:25]
	v_mfma_f32_16x16x32_bf16 v[18:21], v[168:171], v[200:203], v[18:21]
	v_mfma_f32_16x16x32_bf16 v[14:17], v[156:159], v[208:211], v[14:17]
	v_mfma_f32_16x16x32_bf16 v[10:13], v[168:171], v[208:211], v[10:13]
	v_mfma_f32_16x16x32_bf16 v[6:9], v[156:159], v[216:219], v[6:9]
	v_mfma_f32_16x16x32_bf16 v[2:5], v[168:171], v[216:219], v[2:5]
	s_setprio 0
	s_setprio 1
	v_mfma_f32_16x16x32_bf16 v[38:41], v[172:175], v[188:191], v[38:41]
	v_mfma_f32_16x16x32_bf16 v[34:37], v[180:183], v[188:191], v[34:37]
	v_mfma_f32_16x16x32_bf16 v[58:61], v[172:175], v[196:199], v[58:61]
	v_mfma_f32_16x16x32_bf16 v[62:65], v[180:183], v[196:199], v[62:65]
	v_mfma_f32_16x16x32_bf16 v[42:45], v[172:175], v[204:207], v[42:45]
	v_mfma_f32_16x16x32_bf16 v[46:49], v[180:183], v[204:207], v[46:49]
	v_mfma_f32_16x16x32_bf16 v[26:29], v[172:175], v[212:215], v[26:29]
	v_mfma_f32_16x16x32_bf16 v[30:33], v[180:183], v[212:215], v[30:33]
	v_mfma_f32_16x16x32_bf16 v[38:41], v[176:179], v[192:195], v[38:41]
	v_mfma_f32_16x16x32_bf16 v[34:37], v[184:187], v[192:195], v[34:37]
	v_mfma_f32_16x16x32_bf16 v[58:61], v[176:179], v[200:203], v[58:61]
	v_mfma_f32_16x16x32_bf16 v[62:65], v[184:187], v[200:203], v[62:65]
	v_mfma_f32_16x16x32_bf16 v[42:45], v[176:179], v[208:211], v[42:45]
	v_mfma_f32_16x16x32_bf16 v[46:49], v[184:187], v[208:211], v[46:49]
	v_mfma_f32_16x16x32_bf16 v[26:29], v[176:179], v[216:219], v[26:29]
	v_mfma_f32_16x16x32_bf16 v[30:33], v[184:187], v[216:219], v[30:33]
	s_setprio 0
	s_barrier
; #define PG8_STAGE(bufoff, gbase, voff) do { _Pragma("unroll") for (int _i = 0; _i < 2; ++_i) \
;         __builtin_amdgcn_global_load_lds((const unsigned*)((const char*)(gbase) + (voff)[_i]), (LAS unsigned*)(lds + (bufoff) + ldsw + _i * 8192), 16, 0, 0); } while (0)
; #define PG8_LDA(dst, b, h) do { _Pragma("unroll") for (int m = 0; m < 4; ++m) _Pragma("unroll") for (int k = 0; k < 2; ++k) dst[m][k] = *(const LAS bf16x8*)(lds + PG8_SA(b, h) + aoff + m * 2048 + k * 1024); } while (0)
; #define PG8_LDB(dst, b, h) do { _Pragma("unroll") for (int n = 0; n < 2; ++n) _Pragma("unroll") for (int k = 0; k < 2; ++k) dst[n][k] = *(const LAS bf16x8*)(lds + PG8_SB(b, h) + boff + n * 2048 + k * 1024); } while (0)
; #define PG8_MMA(ai, bj, At, Bt) do { __builtin_amdgcn_s_setprio(1); _Pragma("unroll") for (int m = 0; m < 4; ++m) _Pragma("unroll") for (int n = 0; n < 2; ++n) _Pragma("unroll") for (int k = 0; k < 2; ++k) \
;         acc[ai][bj][m][n] = __builtin_amdgcn_mfma_f32_16x16x32_bf16(Bt[n][k], At[m][k], acc[ai][bj][m][n], 0, 0, 0); __builtin_amdgcn_s_setprio(0); } while (0)
; #define PG8_WAIT_V(n) asm volatile("s_waitcnt vmcnt(" #n ")" ::: "memory")
; #define PG8_WAIT_L(n) asm volatile("s_waitcnt lgkmcnt(" #n ")" ::: "memory")
; #define PG8_BAR __builtin_amdgcn_s_barrier()
; #define PG8_SCHED __builtin_amdgcn_sched_barrier(0)
; template <class Epi, bool ALIGN_EPI, bool SPLITA>
; __device__ __forceinline__ void gemm_phase(LAS unsigned char* lds, const Gemm g, const StaticOrder& S, const Epi& E) {
;     ...
;             PG8_WAIT_V(8); PG8_WAIT_L(0); PG8_BAR; PG8_MMA(1, 0, At, B0); PG8_MMA(1, 1, At, B1); PG8_BAR; PG8_SCHED;
;             PG8_LDB(B0, 1, 0); PG8_LDB(B1, 1, 1); PG8_SCHED; PG8_LDA(At, 1, 0); PG8_STAGE(PG8_SA(0, 1), a2h, vo2);
;             PG8_WAIT_V(8); PG8_WAIT_L(0); PG8_BAR; PG8_MMA(0, 0, At, B0); PG8_MMA(0, 1, At, B1); PG8_BAR; PG8_SCHED;
;             PG8_LDA(At, 1, 1); PG8_STAGE(PG8_SB(1, 0), b3, voffB); PG8_STAGE(PG8_SB(1, 1), b3 + hstepB, voffB); PG8_STAGE(PG8_SA(1, 0), a3, vo2);
;             PG8_WAIT_V(8); PG8_WAIT_L(0); PG8_BAR; PG8_MMA(1, 0, At, B0); PG8_MMA(1, 1, At, B1); PG8_BAR; PG8_SCHED;
;         }
	s_add_i32 s89, 0, 0x18000
	v_add_u32_e32 v155, s89, v150
	s_add_i32 s92, 0, 0x1c000
	ds_read_b128 v[146:149], v155
	ds_read_b128 v[156:159], v155 offset:1024
	ds_read_b128 v[164:167], v155 offset:2048
	ds_read_b128 v[168:171], v155 offset:3072
	v_add_u32_e32 v155, s92, v150
	ds_read_b128 v[172:175], v155
	ds_read_b128 v[176:179], v155 offset:1024
	ds_read_b128 v[180:183], v155 offset:2048
	ds_read_b128 v[184:187], v155 offset:3072
	s_add_u32 s46, s46, 0x40000
	s_addc_u32 s47, s47, 0
	s_mov_b32 m0, s61
	ds_read_b128 v[188:191], v154 offset:32768
	ds_read_b128 v[192:195], v154 offset:33792
	ds_read_b128 v[196:199], v154 offset:34816
	ds_read_b128 v[200:203], v154 offset:35840
	ds_read_b128 v[204:207], v154 offset:36864
	ds_read_b128 v[208:211], v154 offset:37888
	ds_read_b128 v[212:215], v154 offset:38912
	ds_read_b128 v[216:219], v154 offset:39936
	global_load_lds_dwordx4 v136, s[46:47]
	s_mov_b32 m0, s64
	s_nop 0
	global_load_lds_dwordx4 v132, s[46:47]
	s_waitcnt vmcnt(8)
	s_waitcnt lgkmcnt(0)
	s_barrier
	s_setprio 1
	s_waitcnt lgkmcnt(0)
	v_mfma_f32_16x16x32_bf16 v[126:129], v[146:149], v[188:191], v[126:129]
	v_mfma_f32_16x16x32_bf16 v[122:125], v[164:167], v[188:191], v[122:125]
	v_mfma_f32_16x16x32_bf16 v[110:113], v[146:149], v[196:199], v[110:113]
	v_mfma_f32_16x16x32_bf16 v[106:109], v[164:167], v[196:199], v[106:109]
	v_mfma_f32_16x16x32_bf16 v[94:97], v[146:149], v[204:207], v[94:97]
	v_mfma_f32_16x16x32_bf16 v[90:93], v[164:167], v[204:207], v[90:93]
	v_mfma_f32_16x16x32_bf16 v[78:81], v[146:149], v[212:215], v[78:81]
	v_mfma_f32_16x16x32_bf16 v[74:77], v[164:167], v[212:215], v[74:77]
	v_mfma_f32_16x16x32_bf16 v[126:129], v[156:159], v[192:195], v[126:129]
	v_mfma_f32_16x16x32_bf16 v[122:125], v[168:171], v[192:195], v[122:125]
	v_mfma_f32_16x16x32_bf16 v[110:113], v[156:159], v[200:203], v[110:113]
	v_mfma_f32_16x16x32_bf16 v[106:109], v[168:171], v[200:203], v[106:109]
	v_mfma_f32_16x16x32_bf16 v[94:97], v[156:159], v[208:211], v[94:97]
	v_mfma_f32_16x16x32_bf16 v[90:93], v[168:171], v[208:211], v[90:93]
	v_mfma_f32_16x16x32_bf16 v[78:81], v[156:159], v[216:219], v[78:81]
	v_mfma_f32_16x16x32_bf16 v[74:77], v[168:171], v[216:219], v[74:77]
	s_setprio 0
	s_setprio 1
	v_mfma_f32_16x16x32_bf16 v[118:121], v[172:175], v[188:191], v[118:121]
	v_mfma_f32_16x16x32_bf16 v[114:117], v[180:183], v[188:191], v[114:117]
	v_mfma_f32_16x16x32_bf16 v[102:105], v[172:175], v[196:199], v[102:105]
	v_mfma_f32_16x16x32_bf16 v[98:101], v[180:183], v[196:199], v[98:101]
	v_mfma_f32_16x16x32_bf16 v[86:89], v[172:175], v[204:207], v[86:89]
	v_mfma_f32_16x16x32_bf16 v[82:85], v[180:183], v[204:207], v[82:85]
	v_mfma_f32_16x16x32_bf16 v[70:73], v[172:175], v[212:215], v[70:73]
	v_mfma_f32_16x16x32_bf16 v[66:69], v[180:183], v[212:215], v[66:69]
	v_mfma_f32_16x16x32_bf16 v[118:121], v[176:179], v[192:195], v[118:121]
	v_mfma_f32_16x16x32_bf16 v[114:117], v[184:187], v[192:195], v[114:117]
	v_mfma_f32_16x16x32_bf16 v[102:105], v[176:179], v[200:203], v[102:105]
	v_mfma_f32_16x16x32_bf16 v[98:101], v[184:187], v[200:203], v[98:101]
	v_mfma_f32_16x16x32_bf16 v[86:89], v[176:179], v[208:211], v[86:89]
	v_mfma_f32_16x16x32_bf16 v[82:85], v[184:187], v[208:211], v[82:85]
	v_mfma_f32_16x16x32_bf16 v[70:73], v[176:179], v[216:219], v[70:73]
	v_mfma_f32_16x16x32_bf16 v[66:69], v[184:187], v[216:219], v[66:69]
	s_setprio 0
	s_barrier
	s_add_i32 s46, s89, s33
	s_mov_b32 m0, s46
	ds_read_b128 v[188:191], v154 offset:49152
	ds_read_b128 v[192:195], v154 offset:50176
	ds_read_b128 v[196:199], v154 offset:51200
	ds_read_b128 v[200:203], v154 offset:52224
	ds_read_b128 v[204:207], v154 offset:53248
	ds_read_b128 v[208:211], v154 offset:54272
	ds_read_b128 v[212:215], v154 offset:55296
	ds_read_b128 v[216:219], v154 offset:56320
	global_load_lds_dwordx4 v134, s[98:99]
	s_add_i32 m0, s46, 0x2000
	s_add_u32 s44, s44, 0x200080
	s_addc_u32 s45, s45, 0
	s_add_i32 s46, s92, s33
	global_load_lds_dwordx4 v130, s[98:99]
	s_mov_b32 m0, s46
	s_nop 0
	global_load_lds_dwordx4 v134, s[44:45]
	s_add_i32 m0, s46, 0x2000
	s_nop 0
	global_load_lds_dwordx4 v130, s[44:45]
	s_mov_b32 m0, s72
	s_nop 0
	global_load_lds_dwordx4 v136, s[100:101]
	s_mov_b32 m0, s73
	s_nop 0
	global_load_lds_dwordx4 v132, s[100:101]
	s_waitcnt vmcnt(8)
	s_waitcnt lgkmcnt(0)
	s_barrier
	s_setprio 1
	s_waitcnt lgkmcnt(0)
	v_mfma_f32_16x16x32_bf16 v[54:57], v[146:149], v[188:191], v[54:57]
	v_mfma_f32_16x16x32_bf16 v[50:53], v[164:167], v[188:191], v[50:53]
	v_mfma_f32_16x16x32_bf16 v[22:25], v[146:149], v[196:199], v[22:25]
	v_mfma_f32_16x16x32_bf16 v[18:21], v[164:167], v[196:199], v[18:21]
	v_mfma_f32_16x16x32_bf16 v[14:17], v[146:149], v[204:207], v[14:17]
	v_mfma_f32_16x16x32_bf16 v[10:13], v[164:167], v[204:207], v[10:13]
	v_mfma_f32_16x16x32_bf16 v[6:9], v[146:149], v[212:215], v[6:9]
	v_mfma_f32_16x16x32_bf16 v[2:5], v[164:167], v[212:215], v[2:5]
	v_mfma_f32_16x16x32_bf16 v[54:57], v[156:159], v[192:195], v[54:57]
	v_mfma_f32_16x16x32_bf16 v[50:53], v[168:171], v[192:195], v[50:53]
	v_mfma_f32_16x16x32_bf16 v[22:25], v[156:159], v[200:203], v[22:25]
	v_mfma_f32_16x16x32_bf16 v[18:21], v[168:171], v[200:203], v[18:21]
	v_mfma_f32_16x16x32_bf16 v[14:17], v[156:159], v[208:211], v[14:17]
	v_mfma_f32_16x16x32_bf16 v[10:13], v[168:171], v[208:211], v[10:13]
	v_mfma_f32_16x16x32_bf16 v[6:9], v[156:159], v[216:219], v[6:9]
	v_mfma_f32_16x16x32_bf16 v[2:5], v[168:171], v[216:219], v[2:5]
	s_setprio 0
	s_setprio 1
	v_mfma_f32_16x16x32_bf16 v[38:41], v[172:175], v[188:191], v[38:41]
	v_mfma_f32_16x16x32_bf16 v[34:37], v[180:183], v[188:191], v[34:37]
	v_mfma_f32_16x16x32_bf16 v[58:61], v[172:175], v[196:199], v[58:61]
	v_mfma_f32_16x16x32_bf16 v[62:65], v[180:183], v[196:199], v[62:65]
	v_mfma_f32_16x16x32_bf16 v[42:45], v[172:175], v[204:207], v[42:45]
	v_mfma_f32_16x16x32_bf16 v[46:49], v[180:183], v[204:207], v[46:49]
	v_mfma_f32_16x16x32_bf16 v[26:29], v[172:175], v[212:215], v[26:29]
	v_mfma_f32_16x16x32_bf16 v[30:33], v[180:183], v[212:215], v[30:33]
	v_mfma_f32_16x16x32_bf16 v[38:41], v[176:179], v[192:195], v[38:41]
	v_mfma_f32_16x16x32_bf16 v[34:37], v[184:187], v[192:195], v[34:37]
	v_mfma_f32_16x16x32_bf16 v[58:61], v[176:179], v[200:203], v[58:61]
	v_mfma_f32_16x16x32_bf16 v[62:65], v[184:187], v[200:203], v[62:65]
	v_mfma_f32_16x16x32_bf16 v[42:45], v[176:179], v[208:211], v[42:45]
	v_mfma_f32_16x16x32_bf16 v[46:49], v[184:187], v[208:211], v[46:49]
	v_mfma_f32_16x16x32_bf16 v[26:29], v[176:179], v[216:219], v[26:29]
	v_mfma_f32_16x16x32_bf16 v[30:33], v[184:187], v[216:219], v[30:33]
	s_setprio 0
	s_barrier
	s_add_i32 s91, s91, 2
	s_add_u32 s0, s0, 0x100
	s_addc_u32 s1, s1, 0
	s_add_u32 s29, s29, 0x100
	s_addc_u32 s90, s90, 0
	s_cmp_gt_u32 s91, 13
	s_cbranch_scc0 .LBB0_265
	s_and_b64 vcc, exec, s[10:11]
	s_cbranch_vccz .LBB0_268
	s_barrier

; #define PG8_STAGE(bufoff, gbase, voff) do { _Pragma("unroll") for (int _i = 0; _i < 2; ++_i) \
;         __builtin_amdgcn_global_load_lds((const unsigned*)((const char*)(gbase) + (voff)[_i]), (LAS unsigned*)(lds + (bufoff) + ldsw + _i * 8192), 16, 0, 0); } while (0)
; #define PG8_LDA(dst, b, h) do { _Pragma("unroll") for (int m = 0; m < 4; ++m) _Pragma("unroll") for (int k = 0; k < 2; ++k) dst[m][k] = *(const LAS bf16x8*)(lds + PG8_SA(b, h) + aoff + m * 2048 + k * 1024); } while (0)
; #define PG8_LDB(dst, b, h) do { _Pragma("unroll") for (int n = 0; n < 2; ++n) _Pragma("unroll") for (int k = 0; k < 2; ++k) dst[n][k] = *(const LAS bf16x8*)(lds + PG8_SB(b, h) + boff + n * 2048 + k * 1024); } while (0)
; template <class Epi, bool ALIGN_EPI, bool SPLITA>
; __device__ __forceinline__ void gemm_phase(LAS unsigned char* lds, const Gemm g, const StaticOrder& S, const Epi& E) {
;     ...
;                 a1 = (t + 1 < g.ksplit) ? cA + (size_t)(t + 1) * kstep : cA2 + (size_t)(t + 1 - g.ksplit) * 2048;
;                 a2 = last ? nA : ((t + 2 < g.ksplit) ? cA + (size_t)(t + 2) * kstep : cA2 + (size_t)(t + 2 - g.ksplit) * 2048);
;             } else { a1 = cA + kofs(t + 1); a2 = last ? nA : cA + kofs(t + 2); }
;             const char* b2 = last ? nB : cB + (size_t)(t + 2) * kstepB;
;             const bool s2a = SPLITA && (t + 1 >= g.ksplit), s2b = SPLITA && !last && (t + 2 >= g.ksplit);
;             const char* a3 = a2 + ((Epi::KSUB || s2b) ? (size_t)2048 : kstep); const char* b3 = b2 + kstepB;
;             const bool m1 = SPLITA && mirC && (t + 1 < g.ksplit), m2 = SPLITA && (last ? mirN : (mirC && (t + 2 < g.ksplit)));
;             const unsigned vo1[2] = {s2a ? voffA2[0] : m1 ? voffAm[0] : voffA[0], s2a ? voffA2[1] : m1 ? voffAm[1] : voffA[1]}, vo2[2] = {s2b ? voffA2[0] : m2 ? voffAm[0] : voffA[0], s2b ? voffA2[1] : m2 ? voffAm[1] : voffA[1]};
;             const char* a1h = m1 ? a1 - hstepA : a1 + hstepA; const char* a2h = m2 ? a2 - hstepA : a2 + hstepA;
;             PG8_LDB(B0, 0, 0); PG8_LDB(B1, 0, 1); PG8_SCHED; PG8_LDA(At, 0, 0); PG8_STAGE(PG8_SA(1, 1), a1h, vo1);
;             PG8_WAIT_V(8); PG8_WAIT_L(0); PG8_BAR; PG8_MMA(0, 0, At, B0); PG8_MMA(0, 1, At, B1); PG8_BAR; PG8_SCHED;
;             PG8_LDA(At, 0, 1); PG8_STAGE(PG8_SB(0, 0), b2, voffB); PG8_STAGE(PG8_SB(0, 1), b2 + hstepB, voffB); PG8_STAGE(PG8_SA(0, 0), a2, vo2);
.LBB0_415:
	ds_read_b128 v[146:149], v156
	ds_read_b128 v[150:153], v156 offset:1024
	ds_read_b128 v[160:163], v156 offset:2048
	ds_read_b128 v[164:167], v156 offset:3072
	ds_read_b128 v[168:171], v157
	ds_read_b128 v[172:175], v157 offset:1024
	ds_read_b128 v[176:179], v157 offset:2048
	ds_read_b128 v[180:183], v157 offset:3072
	s_add_u32 s12, s48, 0xfffc0080
	s_addc_u32 s13, s49, -1
	s_cmp_eq_u32 s31, 12
	s_cselect_b32 s53, s1, s13
	s_cselect_b32 s52, s0, s12
	s_cselect_b32 s51, s47, s11
	s_cselect_b32 s50, s46, s5
	s_add_i32 m0, s54, 0xc000
	ds_read_b128 v[184:187], v158
	ds_read_b128 v[188:191], v158 offset:1024
	ds_read_b128 v[192:195], v158 offset:2048
	ds_read_b128 v[196:199], v158 offset:3072
	ds_read_b128 v[200:203], v158 offset:4096
	ds_read_b128 v[204:207], v158 offset:5120
	ds_read_b128 v[208:211], v158 offset:6144
	ds_read_b128 v[212:215], v158 offset:7168
	global_load_lds_dwordx4 v138, s[48:49]
	s_add_i32 m0, s54, 0xe000
	s_nop 0
	global_load_lds_dwordx4 v140, s[48:49]
	s_waitcnt vmcnt(8)
	s_waitcnt lgkmcnt(0)
	s_barrier
	s_setprio 1
	s_waitcnt lgkmcnt(0)
	v_mfma_f32_16x16x32_bf16 v[126:129], v[146:149], v[184:187], v[126:129]
	v_mfma_f32_16x16x32_bf16 v[122:125], v[160:163], v[184:187], v[122:125]
	v_mfma_f32_16x16x32_bf16 v[110:113], v[146:149], v[192:195], v[110:113]
	v_mfma_f32_16x16x32_bf16 v[106:109], v[160:163], v[192:195], v[106:109]
	v_mfma_f32_16x16x32_bf16 v[94:97], v[146:149], v[200:203], v[94:97]
	v_mfma_f32_16x16x32_bf16 v[90:93], v[160:163], v[200:203], v[90:93]
	v_mfma_f32_16x16x32_bf16 v[78:81], v[146:149], v[208:211], v[78:81]
	v_mfma_f32_16x16x32_bf16 v[74:77], v[160:163], v[208:211], v[74:77]
	v_mfma_f32_16x16x32_bf16 v[126:129], v[150:153], v[188:191], v[126:129]
	v_mfma_f32_16x16x32_bf16 v[122:125], v[164:167], v[188:191], v[122:125]
	v_mfma_f32_16x16x32_bf16 v[110:113], v[150:153], v[196:199], v[110:113]
	v_mfma_f32_16x16x32_bf16 v[106:109], v[164:167], v[196:199], v[106:109]
	v_mfma_f32_16x16x32_bf16 v[94:97], v[150:153], v[204:207], v[94:97]
	v_mfma_f32_16x16x32_bf16 v[90:93], v[164:167], v[204:207], v[90:93]
	v_mfma_f32_16x16x32_bf16 v[78:81], v[150:153], v[212:215], v[78:81]
	v_mfma_f32_16x16x32_bf16 v[74:77], v[164:167], v[212:215], v[74:77]
	s_setprio 0
	s_setprio 1
	v_mfma_f32_16x16x32_bf16 v[118:121], v[168:171], v[184:187], v[118:121]
	v_mfma_f32_16x16x32_bf16 v[114:117], v[176:179], v[184:187], v[114:117]
	v_mfma_f32_16x16x32_bf16 v[102:105], v[168:171], v[192:195], v[102:105]
	v_mfma_f32_16x16x32_bf16 v[98:101], v[176:179], v[192:195], v[98:101]
	v_mfma_f32_16x16x32_bf16 v[86:89], v[168:171], v[200:203], v[86:89]
	v_mfma_f32_16x16x32_bf16 v[82:85], v[176:179], v[200:203], v[82:85]
	v_mfma_f32_16x16x32_bf16 v[70:73], v[168:171], v[208:211], v[70:73]
	v_mfma_f32_16x16x32_bf16 v[66:69], v[176:179], v[208:211], v[66:69]
	v_mfma_f32_16x16x32_bf16 v[118:121], v[172:175], v[188:191], v[118:121]
	v_mfma_f32_16x16x32_bf16 v[114:117], v[180:183], v[188:191], v[114:117]
	v_mfma_f32_16x16x32_bf16 v[102:105], v[172:175], v[196:199], v[102:105]
	v_mfma_f32_16x16x32_bf16 v[98:101], v[180:183], v[196:199], v[98:101]
	v_mfma_f32_16x16x32_bf16 v[86:89], v[172:175], v[204:207], v[86:89]
	v_mfma_f32_16x16x32_bf16 v[82:85], v[180:183], v[204:207], v[82:85]
	v_mfma_f32_16x16x32_bf16 v[70:73], v[172:175], v[212:215], v[70:73]
	v_mfma_f32_16x16x32_bf16 v[66:69], v[180:183], v[212:215], v[66:69]
	s_setprio 0
	s_barrier
	s_add_u32 s98, s50, s18
	s_addc_u32 s99, s51, s19
	s_add_u32 s100, s52, s18
	s_addc_u32 s101, s53, s19
	s_add_i32 s12, s65, s33
	s_mov_b32 m0, s12
	ds_read_b128 v[184:187], v158 offset:16384
	ds_read_b128 v[188:191], v158 offset:17408
	ds_read_b128 v[192:195], v158 offset:18432
	ds_read_b128 v[196:199], v158 offset:19456
	ds_read_b128 v[200:203], v158 offset:20480
	ds_read_b128 v[204:207], v158 offset:21504
	ds_read_b128 v[208:211], v158 offset:22528
	ds_read_b128 v[212:215], v158 offset:23552
	global_load_lds_dwordx4 v132, s[50:51]
	s_add_i32 m0, s12, 0x2000
	s_add_u32 s76, s50, 0xc00000
	s_addc_u32 s77, s51, 0
	s_add_i32 s12, s72, s33
	global_load_lds_dwordx4 v136, s[50:51]
	s_mov_b32 m0, s12
	s_nop 0
	global_load_lds_dwordx4 v132, s[76:77]
	s_add_i32 m0, s12, 0x2000
	s_nop 0
	global_load_lds_dwordx4 v136, s[76:77]
	s_mov_b32 m0, s54
	s_nop 0
	global_load_lds_dwordx4 v130, s[52:53]
	s_mov_b32 m0, s55
	s_nop 0
	global_load_lds_dwordx4 v134, s[52:53]
	s_waitcnt vmcnt(8)
	s_waitcnt lgkmcnt(0)
	s_barrier
	s_setprio 1
	s_waitcnt lgkmcnt(0)
	v_mfma_f32_16x16x32_bf16 v[62:65], v[146:149], v[184:187], v[62:65]
	v_mfma_f32_16x16x32_bf16 v[58:61], v[160:163], v[184:187], v[58:61]
	v_mfma_f32_16x16x32_bf16 v[38:41], v[146:149], v[192:195], v[38:41]
	v_mfma_f32_16x16x32_bf16 v[34:37], v[160:163], v[192:195], v[34:37]
	v_mfma_f32_16x16x32_bf16 v[22:25], v[146:149], v[200:203], v[22:25]
	v_mfma_f32_16x16x32_bf16 v[18:21], v[160:163], v[200:203], v[18:21]
	v_mfma_f32_16x16x32_bf16 v[6:9], v[146:149], v[208:211], v[6:9]
	v_mfma_f32_16x16x32_bf16 v[2:5], v[160:163], v[208:211], v[2:5]
	v_mfma_f32_16x16x32_bf16 v[62:65], v[150:153], v[188:191], v[62:65]
	v_mfma_f32_16x16x32_bf16 v[58:61], v[164:167], v[188:191], v[58:61]
	v_mfma_f32_16x16x32_bf16 v[38:41], v[150:153], v[196:199], v[38:41]
	v_mfma_f32_16x16x32_bf16 v[34:37], v[164:167], v[196:199], v[34:37]
	v_mfma_f32_16x16x32_bf16 v[22:25], v[150:153], v[204:207], v[22:25]
	v_mfma_f32_16x16x32_bf16 v[18:21], v[164:167], v[204:207], v[18:21]
	v_mfma_f32_16x16x32_bf16 v[6:9], v[150:153], v[212:215], v[6:9]
	v_mfma_f32_16x16x32_bf16 v[2:5], v[164:167], v[212:215], v[2:5]
	s_setprio 0
	s_setprio 1
	v_mfma_f32_16x16x32_bf16 v[54:57], v[168:171], v[184:187], v[54:57]
	v_mfma_f32_16x16x32_bf16 v[50:53], v[176:179], v[184:187], v[50:53]
	v_mfma_f32_16x16x32_bf16 v[42:45], v[168:171], v[192:195], v[42:45]
	v_mfma_f32_16x16x32_bf16 v[46:49], v[176:179], v[192:195], v[46:49]
	v_mfma_f32_16x16x32_bf16 v[26:29], v[168:171], v[200:203], v[26:29]
	v_mfma_f32_16x16x32_bf16 v[30:33], v[176:179], v[200:203], v[30:33]
	v_mfma_f32_16x16x32_bf16 v[10:13], v[168:171], v[208:211], v[10:13]
	v_mfma_f32_16x16x32_bf16 v[14:17], v[176:179], v[208:211], v[14:17]
	v_mfma_f32_16x16x32_bf16 v[54:57], v[172:175], v[188:191], v[54:57]
	v_mfma_f32_16x16x32_bf16 v[50:53], v[180:183], v[188:191], v[50:53]
	v_mfma_f32_16x16x32_bf16 v[42:45], v[172:175], v[196:199], v[42:45]
	v_mfma_f32_16x16x32_bf16 v[46:49], v[180:183], v[196:199], v[46:49]
	v_mfma_f32_16x16x32_bf16 v[26:29], v[172:175], v[204:207], v[26:29]
	v_mfma_f32_16x16x32_bf16 v[30:33], v[180:183], v[204:207], v[30:33]
	v_mfma_f32_16x16x32_bf16 v[10:13], v[172:175], v[212:215], v[10:13]
	v_mfma_f32_16x16x32_bf16 v[14:17], v[180:183], v[212:215], v[14:17]
	s_setprio 0
	s_barrier
; #define PG8_STAGE(bufoff, gbase, voff) do { _Pragma("unroll") for (int _i = 0; _i < 2; ++_i) \
;         __builtin_amdgcn_global_load_lds((const unsigned*)((const char*)(gbase) + (voff)[_i]), (LAS unsigned*)(lds + (bufoff) + ldsw + _i * 8192), 16, 0, 0); } while (0)
; #define PG8_LDA(dst, b, h) do { _Pragma("unroll") for (int m = 0; m < 4; ++m) _Pragma("unroll") for (int k = 0; k < 2; ++k) dst[m][k] = *(const LAS bf16x8*)(lds + PG8_SA(b, h) + aoff + m * 2048 + k * 1024); } while (0)
; #define PG8_LDB(dst, b, h) do { _Pragma("unroll") for (int n = 0; n < 2; ++n) _Pragma("unroll") for (int k = 0; k < 2; ++k) dst[n][k] = *(const LAS bf16x8*)(lds + PG8_SB(b, h) + boff + n * 2048 + k * 1024); } while (0)
; #define PG8_MMA(ai, bj, At, Bt) do { __builtin_amdgcn_s_setprio(1); _Pragma("unroll") for (int m = 0; m < 4; ++m) _Pragma("unroll") for (int n = 0; n < 2; ++n) _Pragma("unroll") for (int k = 0; k < 2; ++k) \
;         acc[ai][bj][m][n] = __builtin_amdgcn_mfma_f32_16x16x32_bf16(Bt[n][k], At[m][k], acc[ai][bj][m][n], 0, 0, 0); __builtin_amdgcn_s_setprio(0); } while (0)
; #define PG8_WAIT_V(n) asm volatile("s_waitcnt vmcnt(" #n ")" ::: "memory")
; #define PG8_WAIT_L(n) asm volatile("s_waitcnt lgkmcnt(" #n ")" ::: "memory")
; #define PG8_BAR __builtin_amdgcn_s_barrier()
; #define PG8_SCHED __builtin_amdgcn_sched_barrier(0)
; template <class Epi, bool ALIGN_EPI, bool SPLITA>
; __device__ __forceinline__ void gemm_phase(LAS unsigned char* lds, const Gemm g, const StaticOrder& S, const Epi& E) {
;     ...
;             PG8_WAIT_V(8); PG8_WAIT_L(0); PG8_BAR; PG8_MMA(1, 0, At, B0); PG8_MMA(1, 1, At, B1); PG8_BAR; PG8_SCHED;
;             PG8_LDB(B0, 1, 0); PG8_LDB(B1, 1, 1); PG8_SCHED; PG8_LDA(At, 1, 0); PG8_STAGE(PG8_SA(0, 1), a2h, vo2);
;             PG8_WAIT_V(8); PG8_WAIT_L(0); PG8_BAR; PG8_MMA(0, 0, At, B0); PG8_MMA(0, 1, At, B1); PG8_BAR; PG8_SCHED;
;             PG8_LDA(At, 1, 1); PG8_STAGE(PG8_SB(1, 0), b3, voffB); PG8_STAGE(PG8_SB(1, 1), b3 + hstepB, voffB); PG8_STAGE(PG8_SA(1, 0), a3, vo2);
;             PG8_WAIT_V(8); PG8_WAIT_L(0); PG8_BAR; PG8_MMA(1, 0, At, B0); PG8_MMA(1, 1, At, B1); PG8_BAR; PG8_SCHED;
;         }
	s_add_i32 s12, 0, 0x18000
	v_add_u32_e32 v159, s12, v154
	s_add_i32 s13, 0, 0x1c000
	ds_read_b128 v[146:149], v159
	ds_read_b128 v[150:153], v159 offset:1024
	ds_read_b128 v[160:163], v159 offset:2048
	ds_read_b128 v[164:167], v159 offset:3072
	v_add_u32_e32 v159, s13, v154
	ds_read_b128 v[168:171], v159
	ds_read_b128 v[172:175], v159 offset:1024
	ds_read_b128 v[176:179], v159 offset:2048
	ds_read_b128 v[180:183], v159 offset:3072
	s_add_u32 s52, s52, 0x40000
	s_addc_u32 s53, s53, 0
	s_mov_b32 m0, s56
	ds_read_b128 v[184:187], v158 offset:32768
	ds_read_b128 v[188:191], v158 offset:33792
	ds_read_b128 v[192:195], v158 offset:34816
	ds_read_b128 v[196:199], v158 offset:35840
	ds_read_b128 v[200:203], v158 offset:36864
	ds_read_b128 v[204:207], v158 offset:37888
	ds_read_b128 v[208:211], v158 offset:38912
	ds_read_b128 v[212:215], v158 offset:39936
	global_load_lds_dwordx4 v130, s[52:53]
	s_mov_b32 m0, s57
	s_nop 0
	global_load_lds_dwordx4 v134, s[52:53]
	s_waitcnt vmcnt(8)
	s_waitcnt lgkmcnt(0)
	s_barrier
	s_setprio 1
	s_waitcnt lgkmcnt(0)
	v_mfma_f32_16x16x32_bf16 v[126:129], v[146:149], v[184:187], v[126:129]
	v_mfma_f32_16x16x32_bf16 v[122:125], v[160:163], v[184:187], v[122:125]
	v_mfma_f32_16x16x32_bf16 v[110:113], v[146:149], v[192:195], v[110:113]
	v_mfma_f32_16x16x32_bf16 v[106:109], v[160:163], v[192:195], v[106:109]
	v_mfma_f32_16x16x32_bf16 v[94:97], v[146:149], v[200:203], v[94:97]
	v_mfma_f32_16x16x32_bf16 v[90:93], v[160:163], v[200:203], v[90:93]
	v_mfma_f32_16x16x32_bf16 v[78:81], v[146:149], v[208:211], v[78:81]
	v_mfma_f32_16x16x32_bf16 v[74:77], v[160:163], v[208:211], v[74:77]
	v_mfma_f32_16x16x32_bf16 v[126:129], v[150:153], v[188:191], v[126:129]
	v_mfma_f32_16x16x32_bf16 v[122:125], v[164:167], v[188:191], v[122:125]
	v_mfma_f32_16x16x32_bf16 v[110:113], v[150:153], v[196:199], v[110:113]
	v_mfma_f32_16x16x32_bf16 v[106:109], v[164:167], v[196:199], v[106:109]
	v_mfma_f32_16x16x32_bf16 v[94:97], v[150:153], v[204:207], v[94:97]
	v_mfma_f32_16x16x32_bf16 v[90:93], v[164:167], v[204:207], v[90:93]
	v_mfma_f32_16x16x32_bf16 v[78:81], v[150:153], v[212:215], v[78:81]
	v_mfma_f32_16x16x32_bf16 v[74:77], v[164:167], v[212:215], v[74:77]
	s_setprio 0
	s_setprio 1
	v_mfma_f32_16x16x32_bf16 v[118:121], v[168:171], v[184:187], v[118:121]
	v_mfma_f32_16x16x32_bf16 v[114:117], v[176:179], v[184:187], v[114:117]
	v_mfma_f32_16x16x32_bf16 v[102:105], v[168:171], v[192:195], v[102:105]
	v_mfma_f32_16x16x32_bf16 v[98:101], v[176:179], v[192:195], v[98:101]
	v_mfma_f32_16x16x32_bf16 v[86:89], v[168:171], v[200:203], v[86:89]
	v_mfma_f32_16x16x32_bf16 v[82:85], v[176:179], v[200:203], v[82:85]
	v_mfma_f32_16x16x32_bf16 v[70:73], v[168:171], v[208:211], v[70:73]
	v_mfma_f32_16x16x32_bf16 v[66:69], v[176:179], v[208:211], v[66:69]
	v_mfma_f32_16x16x32_bf16 v[118:121], v[172:175], v[188:191], v[118:121]
	v_mfma_f32_16x16x32_bf16 v[114:117], v[180:183], v[188:191], v[114:117]
	v_mfma_f32_16x16x32_bf16 v[102:105], v[172:175], v[196:199], v[102:105]
	v_mfma_f32_16x16x32_bf16 v[98:101], v[180:183], v[196:199], v[98:101]
	v_mfma_f32_16x16x32_bf16 v[86:89], v[172:175], v[204:207], v[86:89]
	v_mfma_f32_16x16x32_bf16 v[82:85], v[180:183], v[204:207], v[82:85]
	v_mfma_f32_16x16x32_bf16 v[70:73], v[172:175], v[212:215], v[70:73]
	v_mfma_f32_16x16x32_bf16 v[66:69], v[180:183], v[212:215], v[66:69]
	s_setprio 0
	s_barrier
	s_add_i32 s12, s12, s33
	s_mov_b32 m0, s12
	ds_read_b128 v[184:187], v158 offset:49152
	ds_read_b128 v[188:191], v158 offset:50176
	ds_read_b128 v[192:195], v158 offset:51200
	ds_read_b128 v[196:199], v158 offset:52224
	ds_read_b128 v[200:203], v158 offset:53248
	ds_read_b128 v[204:207], v158 offset:54272
	ds_read_b128 v[208:211], v158 offset:55296
	ds_read_b128 v[212:215], v158 offset:56320
	global_load_lds_dwordx4 v132, s[98:99]
	s_add_i32 m0, s12, 0x2000
	s_add_u32 s50, s50, 0xc00080
	s_addc_u32 s51, s51, 0
	s_add_i32 s12, s13, s33
	global_load_lds_dwordx4 v136, s[98:99]
	s_mov_b32 m0, s12
	s_nop 0
	global_load_lds_dwordx4 v132, s[50:51]
	s_add_i32 m0, s12, 0x2000
	s_nop 0
	global_load_lds_dwordx4 v136, s[50:51]
	s_mov_b32 m0, s61
	s_nop 0
	global_load_lds_dwordx4 v130, s[100:101]
	s_mov_b32 m0, s64
	s_nop 0
	global_load_lds_dwordx4 v134, s[100:101]
	s_waitcnt vmcnt(8)
	s_waitcnt lgkmcnt(0)
	s_barrier
	s_setprio 1
	s_waitcnt lgkmcnt(0)
	v_mfma_f32_16x16x32_bf16 v[62:65], v[146:149], v[184:187], v[62:65]
	v_mfma_f32_16x16x32_bf16 v[58:61], v[160:163], v[184:187], v[58:61]
	v_mfma_f32_16x16x32_bf16 v[38:41], v[146:149], v[192:195], v[38:41]
	v_mfma_f32_16x16x32_bf16 v[34:37], v[160:163], v[192:195], v[34:37]
	v_mfma_f32_16x16x32_bf16 v[22:25], v[146:149], v[200:203], v[22:25]
	v_mfma_f32_16x16x32_bf16 v[18:21], v[160:163], v[200:203], v[18:21]
	v_mfma_f32_16x16x32_bf16 v[6:9], v[146:149], v[208:211], v[6:9]
	v_mfma_f32_16x16x32_bf16 v[2:5], v[160:163], v[208:211], v[2:5]
	v_mfma_f32_16x16x32_bf16 v[62:65], v[150:153], v[188:191], v[62:65]
	v_mfma_f32_16x16x32_bf16 v[58:61], v[164:167], v[188:191], v[58:61]
	v_mfma_f32_16x16x32_bf16 v[38:41], v[150:153], v[196:199], v[38:41]
	v_mfma_f32_16x16x32_bf16 v[34:37], v[164:167], v[196:199], v[34:37]
	v_mfma_f32_16x16x32_bf16 v[22:25], v[150:153], v[204:207], v[22:25]
	v_mfma_f32_16x16x32_bf16 v[18:21], v[164:167], v[204:207], v[18:21]
	v_mfma_f32_16x16x32_bf16 v[6:9], v[150:153], v[212:215], v[6:9]
	v_mfma_f32_16x16x32_bf16 v[2:5], v[164:167], v[212:215], v[2:5]
	s_setprio 0
	s_setprio 1
	v_mfma_f32_16x16x32_bf16 v[54:57], v[168:171], v[184:187], v[54:57]
	v_mfma_f32_16x16x32_bf16 v[50:53], v[176:179], v[184:187], v[50:53]
	v_mfma_f32_16x16x32_bf16 v[42:45], v[168:171], v[192:195], v[42:45]
	v_mfma_f32_16x16x32_bf16 v[46:49], v[176:179], v[192:195], v[46:49]
	v_mfma_f32_16x16x32_bf16 v[26:29], v[168:171], v[200:203], v[26:29]
	v_mfma_f32_16x16x32_bf16 v[30:33], v[176:179], v[200:203], v[30:33]
	v_mfma_f32_16x16x32_bf16 v[10:13], v[168:171], v[208:211], v[10:13]
	v_mfma_f32_16x16x32_bf16 v[14:17], v[176:179], v[208:211], v[14:17]
	v_mfma_f32_16x16x32_bf16 v[54:57], v[172:175], v[188:191], v[54:57]
	v_mfma_f32_16x16x32_bf16 v[50:53], v[180:183], v[188:191], v[50:53]
	v_mfma_f32_16x16x32_bf16 v[42:45], v[172:175], v[196:199], v[42:45]
	v_mfma_f32_16x16x32_bf16 v[46:49], v[180:183], v[196:199], v[46:49]
	v_mfma_f32_16x16x32_bf16 v[26:29], v[172:175], v[204:207], v[26:29]
	v_mfma_f32_16x16x32_bf16 v[30:33], v[180:183], v[204:207], v[30:33]
	v_mfma_f32_16x16x32_bf16 v[10:13], v[172:175], v[212:215], v[10:13]
	v_mfma_f32_16x16x32_bf16 v[14:17], v[180:183], v[212:215], v[14:17]
	s_setprio 0
	s_barrier
	s_add_i32 s31, s31, 2
	s_add_u32 s48, s48, 0x100
	s_addc_u32 s49, s49, 0
	s_add_u32 s5, s5, 0x100
	s_addc_u32 s11, s11, 0
	s_cmp_gt_u32 s31, 13
	s_cbranch_scc0 .LBB0_415
	s_and_b64 vcc, exec, s[20:21]
	s_cbranch_vccz .LBB0_418
	s_barrier

; #define PG8_STAGE(bufoff, gbase, voff) do { _Pragma("unroll") for (int _i = 0; _i < 2; ++_i) \
;         __builtin_amdgcn_global_load_lds((const unsigned*)((const char*)(gbase) + (voff)[_i]), (LAS unsigned*)(lds + (bufoff) + ldsw + _i * 8192), 16, 0, 0); } while (0)
; #define PG8_LDA(dst, b, h) do { _Pragma("unroll") for (int m = 0; m < 4; ++m) _Pragma("unroll") for (int k = 0; k < 2; ++k) dst[m][k] = *(const LAS bf16x8*)(lds + PG8_SA(b, h) + aoff + m * 2048 + k * 1024); } while (0)
; #define PG8_WAIT_V(n) asm volatile("s_waitcnt vmcnt(" #n ")" ::: "memory")
; #define PG8_WAIT_L(n) asm volatile("s_waitcnt lgkmcnt(" #n ")" ::: "memory")
; #define PG8_BAR __builtin_amdgcn_s_barrier()
; template <class Epi, bool ALIGN_EPI, bool SPLITA>
; __device__ __forceinline__ void gemm_phase(LAS unsigned char* lds, const Gemm g, const StaticOrder& S, const Epi& E) {
;     ...
;             if constexpr (SPLITA) {
;                 a1 = (t + 1 < g.ksplit) ? cA + (size_t)(t + 1) * kstep : cA2 + (size_t)(t + 1 - g.ksplit) * 2048;
;                 a2 = last ? nA : ((t + 2 < g.ksplit) ? cA + (size_t)(t + 2) * kstep : cA2 + (size_t)(t + 2 - g.ksplit) * 2048);
;             } else { a1 = cA + kofs(t + 1); a2 = last ? nA : cA + kofs(t + 2); }
;             const char* b2 = last ? nB : cB + (size_t)(t + 2) * kstepB;
;             const bool s2a = SPLITA && (t + 1 >= g.ksplit), s2b = SPLITA && !last && (t + 2 >= g.ksplit);
;             const char* a3 = a2 + ((Epi::KSUB || s2b) ? (size_t)2048 : kstep); const char* b3 = b2 + kstepB;
;             const bool m1 = SPLITA && mirC && (t + 1 < g.ksplit), m2 = SPLITA && (last ? mirN : (mirC && (t + 2 < g.ksplit)));
;             const unsigned vo1[2] = {s2a ? voffA2[0] : m1 ? voffAm[0] : voffA[0], s2a ? voffA2[1] : m1 ? voffAm[1] : voffA[1]}, vo2[2] = {s2b ? voffA2[0] : m2 ? voffAm[0] : voffA[0], s2b ? voffA2[1] : m2 ? voffAm[1] : voffA[1]};
;             const char* a1h = m1 ? a1 - hstepA : a1 + hstepA; const char* a2h = m2 ? a2 - hstepA : a2 + hstepA;
;             PG8_LDB(B0, 0, 0); PG8_LDB(B1, 0, 1); PG8_SCHED; PG8_LDA(At, 0, 0); PG8_STAGE(PG8_SA(1, 1), a1h, vo1);
;             PG8_WAIT_V(8); PG8_WAIT_L(0); PG8_BAR; PG8_MMA(0, 0, At, B0); PG8_MMA(0, 1, At, B1); PG8_BAR; PG8_SCHED;
;             PG8_LDA(At, 0, 1); PG8_STAGE(PG8_SB(0, 0), b2, voffB); PG8_STAGE(PG8_SB(0, 1), b2 + hstepB, voffB); PG8_STAGE(PG8_SA(0, 0), a2, vo2);
.LBB0_626:
	s_cmp_lt_u32 s37, 16
	s_cselect_b64 vcc, -1, 0
	s_and_b64 s[0:1], vcc, exec
	s_cselect_b32 s0, 0, -16
	s_add_i32 s0, s0, s72
	s_add_i32 s10, s0, 15
	s_and_b64 s[0:1], vcc, exec
	s_cselect_b32 s0, 7, 11
	s_cselect_b32 s8, s51, s19
	s_cselect_b32 s9, s50, s17
	s_lshl_b64 s[0:1], s[10:11], s0
	s_add_u32 s10, s9, s0
	s_addc_u32 s43, s8, s1
	s_add_u32 s73, s52, s74
	s_addc_u32 s88, s53, s75
	s_cmp_gt_u32 s37, 13
	s_cselect_b64 s[0:1], -1, 0
	s_and_b64 s[0:1], s[80:81], s[0:1]
	s_and_b64 s[78:79], s[0:1], exec
	s_movk_i32 s8, 0x800
	s_cselect_b32 s8, s8, 0x80
	s_add_u32 s78, s76, s8
	s_addc_u32 s79, s77, 0
	s_and_b64 s[8:9], s[54:55], vcc
	s_cmp_lt_u32 s37, 14
	s_cselect_b64 s[12:13], -1, 0
	s_and_b64 s[12:13], s[54:55], s[12:13]
	v_cndmask_b32_e64 v132, 0, 1, s[12:13]
	v_cndmask_b32_e64 v133, 0, 1, s[4:5]
	s_and_b64 s[12:13], s[80:81], exec
	v_readfirstlane_b32 s12, v132
	v_readfirstlane_b32 s13, v133
	s_cselect_b32 s12, s12, s13
	s_and_b32 s12, 1, s12
	s_and_b64 s[8:9], s[8:9], exec
	s_cselect_b32 s8, s7, 0x40000
	s_cselect_b32 s9, -1, 0
	s_cmp_eq_u32 s12, 1
	v_cndmask_b32_e32 v2, v197, v193, vcc
	v_cndmask_b32_e32 v203, v198, v202, vcc
	s_cselect_b64 vcc, -1, 0
	v_cndmask_b32_e32 v132, v1, v195, vcc
	v_cndmask_b32_e64 v226, v132, v197, s[0:1]
	v_cndmask_b32_e32 v132, v194, v196, vcc
	v_add_u32_e32 v144, s97, v200
	v_add_u32_e32 v160, s33, v200
	v_cndmask_b32_e64 v227, v132, v198, s[0:1]
	ds_read_b128 v[132:135], v144
	ds_read_b128 v[136:139], v144 offset:1024
	ds_read_b128 v[140:143], v144 offset:2048
	ds_read_b128 v[144:147], v144 offset:3072
	ds_read_b128 v[148:151], v160
	ds_read_b128 v[152:155], v160 offset:1024
	ds_read_b128 v[156:159], v160 offset:2048
	ds_read_b128 v[160:163], v160 offset:3072
	s_and_b64 s[0:1], vcc, exec
	s_cselect_b32 s12, -1, 0
	s_cselect_b32 s13, s7, 0x40000
	s_and_b64 s[0:1], s[80:81], exec
	s_cselect_b32 s1, s88, s47
	s_cselect_b32 s0, s73, s46
	s_add_u32 s8, s10, s8
	s_addc_u32 s9, s43, s9
	s_add_i32 m0, s31, 0xc000
	ds_read_b128 v[164:167], v201
	ds_read_b128 v[168:171], v201 offset:1024
	ds_read_b128 v[172:175], v201 offset:2048
	ds_read_b128 v[176:179], v201 offset:3072
	ds_read_b128 v[204:207], v201 offset:4096
	ds_read_b128 v[208:211], v201 offset:5120
	ds_read_b128 v[212:215], v201 offset:6144
	ds_read_b128 v[216:219], v201 offset:7168
	global_load_lds_dwordx4 v2, s[8:9]
	s_add_i32 m0, s31, 0xe000
	s_nop 0
	global_load_lds_dwordx4 v203, s[8:9]
	s_waitcnt vmcnt(8)
	s_waitcnt lgkmcnt(0)
	s_barrier
	s_setprio 1
	s_waitcnt lgkmcnt(0)
	v_mfma_f32_16x16x32_bf16 v[128:131], v[132:135], v[164:167], v[128:131]
	v_mfma_f32_16x16x32_bf16 v[124:127], v[140:143], v[164:167], v[124:127]
	v_mfma_f32_16x16x32_bf16 v[112:115], v[132:135], v[172:175], v[112:115]
	v_mfma_f32_16x16x32_bf16 v[108:111], v[140:143], v[172:175], v[108:111]
	v_mfma_f32_16x16x32_bf16 v[96:99], v[132:135], v[204:207], v[96:99]
	v_mfma_f32_16x16x32_bf16 v[92:95], v[140:143], v[204:207], v[92:95]
	v_mfma_f32_16x16x32_bf16 v[80:83], v[132:135], v[212:215], v[80:83]
	v_mfma_f32_16x16x32_bf16 v[76:79], v[140:143], v[212:215], v[76:79]
	v_mfma_f32_16x16x32_bf16 v[128:131], v[136:139], v[168:171], v[128:131]
	v_mfma_f32_16x16x32_bf16 v[124:127], v[144:147], v[168:171], v[124:127]
	v_mfma_f32_16x16x32_bf16 v[112:115], v[136:139], v[176:179], v[112:115]
	v_mfma_f32_16x16x32_bf16 v[108:111], v[144:147], v[176:179], v[108:111]
	v_mfma_f32_16x16x32_bf16 v[96:99], v[136:139], v[208:211], v[96:99]
	v_mfma_f32_16x16x32_bf16 v[92:95], v[144:147], v[208:211], v[92:95]
	v_mfma_f32_16x16x32_bf16 v[80:83], v[136:139], v[216:219], v[80:83]
	v_mfma_f32_16x16x32_bf16 v[76:79], v[144:147], v[216:219], v[76:79]
	s_setprio 0
	s_setprio 1
	v_mfma_f32_16x16x32_bf16 v[120:123], v[148:151], v[164:167], v[120:123]
	v_mfma_f32_16x16x32_bf16 v[116:119], v[156:159], v[164:167], v[116:119]
	v_mfma_f32_16x16x32_bf16 v[104:107], v[148:151], v[172:175], v[104:107]
	v_mfma_f32_16x16x32_bf16 v[100:103], v[156:159], v[172:175], v[100:103]
	v_mfma_f32_16x16x32_bf16 v[88:91], v[148:151], v[204:207], v[88:91]
	v_mfma_f32_16x16x32_bf16 v[84:87], v[156:159], v[204:207], v[84:87]
	v_mfma_f32_16x16x32_bf16 v[72:75], v[148:151], v[212:215], v[72:75]
	v_mfma_f32_16x16x32_bf16 v[68:71], v[156:159], v[212:215], v[68:71]
	v_mfma_f32_16x16x32_bf16 v[120:123], v[152:155], v[168:171], v[120:123]
	v_mfma_f32_16x16x32_bf16 v[116:119], v[160:163], v[168:171], v[116:119]
	v_mfma_f32_16x16x32_bf16 v[104:107], v[152:155], v[176:179], v[104:107]
	v_mfma_f32_16x16x32_bf16 v[100:103], v[160:163], v[176:179], v[100:103]
	v_mfma_f32_16x16x32_bf16 v[88:91], v[152:155], v[208:211], v[88:91]
	v_mfma_f32_16x16x32_bf16 v[84:87], v[160:163], v[208:211], v[84:87]
	v_mfma_f32_16x16x32_bf16 v[72:75], v[152:155], v[216:219], v[72:75]
	v_mfma_f32_16x16x32_bf16 v[68:71], v[160:163], v[216:219], v[68:71]
	s_setprio 0
	s_barrier
	s_add_u32 s98, s0, s22
	s_addc_u32 s99, s1, s23
	s_add_i32 s8, s97, s6
	s_mov_b32 m0, s8
	ds_read_b128 v[164:167], v201 offset:16384
	ds_read_b128 v[168:171], v201 offset:17408
	ds_read_b128 v[172:175], v201 offset:18432
	ds_read_b128 v[176:179], v201 offset:19456
	ds_read_b128 v[204:207], v201 offset:20480
	ds_read_b128 v[208:211], v201 offset:21504
	ds_read_b128 v[212:215], v201 offset:22528
	ds_read_b128 v[216:219], v201 offset:23552
	global_load_lds_dwordx4 v180, s[0:1]
	s_add_i32 m0, s8, 0x2000
	s_add_u32 s8, s0, 0x80000
	s_addc_u32 s9, s1, 0
	s_add_i32 s10, s33, s6
	global_load_lds_dwordx4 v182, s[0:1]
	s_mov_b32 m0, s10
	s_nop 0
	global_load_lds_dwordx4 v180, s[8:9]
	s_add_i32 m0, s10, 0x2000
	s_nop 0
	global_load_lds_dwordx4 v182, s[8:9]
	s_mov_b32 m0, s31
	s_nop 0
	global_load_lds_dwordx4 v226, s[76:77]
	s_mov_b32 m0, s64
	s_nop 0
	global_load_lds_dwordx4 v227, s[76:77]
	s_waitcnt vmcnt(8)
	s_waitcnt lgkmcnt(0)
	s_barrier
; #define PG8_STAGE(bufoff, gbase, voff) do { _Pragma("unroll") for (int _i = 0; _i < 2; ++_i) \
;         __builtin_amdgcn_global_load_lds((const unsigned*)((const char*)(gbase) + (voff)[_i]), (LAS unsigned*)(lds + (bufoff) + ldsw + _i * 8192), 16, 0, 0); } while (0)
; #define PG8_LDA(dst, b, h) do { _Pragma("unroll") for (int m = 0; m < 4; ++m) _Pragma("unroll") for (int k = 0; k < 2; ++k) dst[m][k] = *(const LAS bf16x8*)(lds + PG8_SA(b, h) + aoff + m * 2048 + k * 1024); } while (0)
; #define PG8_LDB(dst, b, h) do { _Pragma("unroll") for (int n = 0; n < 2; ++n) _Pragma("unroll") for (int k = 0; k < 2; ++k) dst[n][k] = *(const LAS bf16x8*)(lds + PG8_SB(b, h) + boff + n * 2048 + k * 1024); } while (0)
; #define PG8_MMA(ai, bj, At, Bt) do { __builtin_amdgcn_s_setprio(1); _Pragma("unroll") for (int m = 0; m < 4; ++m) _Pragma("unroll") for (int n = 0; n < 2; ++n) _Pragma("unroll") for (int k = 0; k < 2; ++k) \
;         acc[ai][bj][m][n] = __builtin_amdgcn_mfma_f32_16x16x32_bf16(Bt[n][k], At[m][k], acc[ai][bj][m][n], 0, 0, 0); __builtin_amdgcn_s_setprio(0); } while (0)
; #define PG8_WAIT_V(n) asm volatile("s_waitcnt vmcnt(" #n ")" ::: "memory")
; #define PG8_WAIT_L(n) asm volatile("s_waitcnt lgkmcnt(" #n ")" ::: "memory")
; #define PG8_BAR __builtin_amdgcn_s_barrier()
; #define PG8_SCHED __builtin_amdgcn_sched_barrier(0)
; template <class Epi, bool ALIGN_EPI, bool SPLITA>
; __device__ __forceinline__ void gemm_phase(LAS unsigned char* lds, const Gemm g, const StaticOrder& S, const Epi& E) {
;     ...
;             PG8_WAIT_V(8); PG8_WAIT_L(0); PG8_BAR; PG8_MMA(1, 0, At, B0); PG8_MMA(1, 1, At, B1); PG8_BAR; PG8_SCHED;
;             PG8_LDB(B0, 1, 0); PG8_LDB(B1, 1, 1); PG8_SCHED; PG8_LDA(At, 1, 0); PG8_STAGE(PG8_SA(0, 1), a2h, vo2);
;             PG8_WAIT_V(8); PG8_WAIT_L(0); PG8_BAR; PG8_MMA(0, 0, At, B0); PG8_MMA(0, 1, At, B1); PG8_BAR; PG8_SCHED;
	s_setprio 1
	s_waitcnt lgkmcnt(0)
	v_mfma_f32_16x16x32_bf16 v[64:67], v[132:135], v[164:167], v[64:67]
	v_mfma_f32_16x16x32_bf16 v[60:63], v[140:143], v[164:167], v[60:63]
	v_mfma_f32_16x16x32_bf16 v[48:51], v[132:135], v[172:175], v[48:51]
	v_mfma_f32_16x16x32_bf16 v[44:47], v[140:143], v[172:175], v[44:47]
	v_mfma_f32_16x16x32_bf16 v[32:35], v[132:135], v[204:207], v[32:35]
	v_mfma_f32_16x16x32_bf16 v[28:31], v[140:143], v[204:207], v[28:31]
	v_mfma_f32_16x16x32_bf16 v[16:19], v[132:135], v[212:215], v[16:19]
	v_mfma_f32_16x16x32_bf16 v[8:11], v[140:143], v[212:215], v[8:11]
	v_mfma_f32_16x16x32_bf16 v[64:67], v[136:139], v[168:171], v[64:67]
	v_mfma_f32_16x16x32_bf16 v[60:63], v[144:147], v[168:171], v[60:63]
	v_mfma_f32_16x16x32_bf16 v[48:51], v[136:139], v[176:179], v[48:51]
	v_mfma_f32_16x16x32_bf16 v[44:47], v[144:147], v[176:179], v[44:47]
	v_mfma_f32_16x16x32_bf16 v[32:35], v[136:139], v[208:211], v[32:35]
	v_mfma_f32_16x16x32_bf16 v[28:31], v[144:147], v[208:211], v[28:31]
	v_mfma_f32_16x16x32_bf16 v[16:19], v[136:139], v[216:219], v[16:19]
	v_mfma_f32_16x16x32_bf16 v[8:11], v[144:147], v[216:219], v[8:11]
	s_setprio 0
	s_setprio 1
	v_mfma_f32_16x16x32_bf16 v[56:59], v[148:151], v[164:167], v[56:59]
	v_mfma_f32_16x16x32_bf16 v[52:55], v[156:159], v[164:167], v[52:55]
	v_mfma_f32_16x16x32_bf16 v[40:43], v[148:151], v[172:175], v[40:43]
	v_mfma_f32_16x16x32_bf16 v[36:39], v[156:159], v[172:175], v[36:39]
	v_mfma_f32_16x16x32_bf16 v[24:27], v[148:151], v[204:207], v[24:27]
	v_mfma_f32_16x16x32_bf16 v[20:23], v[156:159], v[204:207], v[20:23]
	v_mfma_f32_16x16x32_bf16 v[12:15], v[148:151], v[212:215], v[12:15]
	v_mfma_f32_16x16x32_bf16 v[4:7], v[156:159], v[212:215], v[4:7]
	v_mfma_f32_16x16x32_bf16 v[56:59], v[152:155], v[168:171], v[56:59]
	v_mfma_f32_16x16x32_bf16 v[52:55], v[160:163], v[168:171], v[52:55]
	v_mfma_f32_16x16x32_bf16 v[40:43], v[152:155], v[176:179], v[40:43]
	v_mfma_f32_16x16x32_bf16 v[36:39], v[160:163], v[176:179], v[36:39]
	v_mfma_f32_16x16x32_bf16 v[24:27], v[152:155], v[208:211], v[24:27]
	v_mfma_f32_16x16x32_bf16 v[20:23], v[160:163], v[208:211], v[20:23]
	v_mfma_f32_16x16x32_bf16 v[12:15], v[152:155], v[216:219], v[12:15]
	v_mfma_f32_16x16x32_bf16 v[4:7], v[160:163], v[216:219], v[4:7]
	s_setprio 0
	s_barrier
	s_add_i32 s10, 0, 0x18000
	v_add_u32_e32 v2, s10, v200
	s_add_i32 s43, 0, 0x1c000
	ds_read_b128 v[132:135], v2
	ds_read_b128 v[136:139], v2 offset:1024
	ds_read_b128 v[140:143], v2 offset:2048
	ds_read_b128 v[144:147], v2 offset:3072
	v_add_u32_e32 v2, s43, v200
	ds_read_b128 v[148:151], v2
	ds_read_b128 v[152:155], v2 offset:1024
	ds_read_b128 v[156:159], v2 offset:2048
	ds_read_b128 v[160:163], v2 offset:3072
	s_add_u32 s8, s76, s13
	s_addc_u32 s9, s77, s12
	s_mov_b32 m0, s65
	ds_read_b128 v[164:167], v201 offset:32768
	ds_read_b128 v[168:171], v201 offset:33792
	ds_read_b128 v[172:175], v201 offset:34816
	ds_read_b128 v[176:179], v201 offset:35840
	ds_read_b128 v[204:207], v201 offset:36864
	ds_read_b128 v[208:211], v201 offset:37888
	ds_read_b128 v[212:215], v201 offset:38912
	ds_read_b128 v[216:219], v201 offset:39936
	global_load_lds_dwordx4 v226, s[8:9]
	s_mov_b32 m0, s86
	s_nop 0
	global_load_lds_dwordx4 v227, s[8:9]
	s_waitcnt vmcnt(8)
	s_waitcnt lgkmcnt(0)
	s_barrier
	s_setprio 1
	s_waitcnt lgkmcnt(0)
	v_mfma_f32_16x16x32_bf16 v[128:131], v[132:135], v[164:167], v[128:131]
	v_mfma_f32_16x16x32_bf16 v[124:127], v[140:143], v[164:167], v[124:127]
	v_mfma_f32_16x16x32_bf16 v[112:115], v[132:135], v[172:175], v[112:115]
	v_mfma_f32_16x16x32_bf16 v[108:111], v[140:143], v[172:175], v[108:111]
	v_mfma_f32_16x16x32_bf16 v[96:99], v[132:135], v[204:207], v[96:99]
	v_mfma_f32_16x16x32_bf16 v[92:95], v[140:143], v[204:207], v[92:95]
	v_mfma_f32_16x16x32_bf16 v[80:83], v[132:135], v[212:215], v[80:83]
	v_mfma_f32_16x16x32_bf16 v[76:79], v[140:143], v[212:215], v[76:79]
	v_mfma_f32_16x16x32_bf16 v[128:131], v[136:139], v[168:171], v[128:131]
	v_mfma_f32_16x16x32_bf16 v[124:127], v[144:147], v[168:171], v[124:127]
	v_mfma_f32_16x16x32_bf16 v[112:115], v[136:139], v[176:179], v[112:115]
	v_mfma_f32_16x16x32_bf16 v[108:111], v[144:147], v[176:179], v[108:111]
	v_mfma_f32_16x16x32_bf16 v[96:99], v[136:139], v[208:211], v[96:99]
	v_mfma_f32_16x16x32_bf16 v[92:95], v[144:147], v[208:211], v[92:95]
	v_mfma_f32_16x16x32_bf16 v[80:83], v[136:139], v[216:219], v[80:83]
	v_mfma_f32_16x16x32_bf16 v[76:79], v[144:147], v[216:219], v[76:79]
	s_setprio 0
	s_setprio 1
	v_mfma_f32_16x16x32_bf16 v[120:123], v[148:151], v[164:167], v[120:123]
	v_mfma_f32_16x16x32_bf16 v[116:119], v[156:159], v[164:167], v[116:119]
	v_mfma_f32_16x16x32_bf16 v[104:107], v[148:151], v[172:175], v[104:107]
	v_mfma_f32_16x16x32_bf16 v[100:103], v[156:159], v[172:175], v[100:103]
	v_mfma_f32_16x16x32_bf16 v[88:91], v[148:151], v[204:207], v[88:91]
	v_mfma_f32_16x16x32_bf16 v[84:87], v[156:159], v[204:207], v[84:87]
	v_mfma_f32_16x16x32_bf16 v[72:75], v[148:151], v[212:215], v[72:75]
	v_mfma_f32_16x16x32_bf16 v[68:71], v[156:159], v[212:215], v[68:71]
	v_mfma_f32_16x16x32_bf16 v[120:123], v[152:155], v[168:171], v[120:123]
	v_mfma_f32_16x16x32_bf16 v[116:119], v[160:163], v[168:171], v[116:119]
	v_mfma_f32_16x16x32_bf16 v[104:107], v[152:155], v[176:179], v[104:107]
	v_mfma_f32_16x16x32_bf16 v[100:103], v[160:163], v[176:179], v[100:103]
	v_mfma_f32_16x16x32_bf16 v[88:91], v[152:155], v[208:211], v[88:91]
	v_mfma_f32_16x16x32_bf16 v[84:87], v[160:163], v[208:211], v[84:87]
	v_mfma_f32_16x16x32_bf16 v[72:75], v[152:155], v[216:219], v[72:75]
	v_mfma_f32_16x16x32_bf16 v[68:71], v[160:163], v[216:219], v[68:71]
	s_setprio 0
	s_barrier
; #define PG8_STAGE(bufoff, gbase, voff) do { _Pragma("unroll") for (int _i = 0; _i < 2; ++_i) \
;         __builtin_amdgcn_global_load_lds((const unsigned*)((const char*)(gbase) + (voff)[_i]), (LAS unsigned*)(lds + (bufoff) + ldsw + _i * 8192), 16, 0, 0); } while (0)
; #define PG8_LDA(dst, b, h) do { _Pragma("unroll") for (int m = 0; m < 4; ++m) _Pragma("unroll") for (int k = 0; k < 2; ++k) dst[m][k] = *(const LAS bf16x8*)(lds + PG8_SA(b, h) + aoff + m * 2048 + k * 1024); } while (0)
; #define PG8_MMA(ai, bj, At, Bt) do { __builtin_amdgcn_s_setprio(1); _Pragma("unroll") for (int m = 0; m < 4; ++m) _Pragma("unroll") for (int n = 0; n < 2; ++n) _Pragma("unroll") for (int k = 0; k < 2; ++k) \
;         acc[ai][bj][m][n] = __builtin_amdgcn_mfma_f32_16x16x32_bf16(Bt[n][k], At[m][k], acc[ai][bj][m][n], 0, 0, 0); __builtin_amdgcn_s_setprio(0); } while (0)
; #define PG8_WAIT_V(n) asm volatile("s_waitcnt vmcnt(" #n ")" ::: "memory")
; #define PG8_WAIT_L(n) asm volatile("s_waitcnt lgkmcnt(" #n ")" ::: "memory")
; #define PG8_BAR __builtin_amdgcn_s_barrier()
; #define PG8_SCHED __builtin_amdgcn_sched_barrier(0)
; template <class Epi, bool ALIGN_EPI, bool SPLITA>
; __device__ __forceinline__ void gemm_phase(LAS unsigned char* lds, const Gemm g, const StaticOrder& S, const Epi& E) {
;     ...
;             PG8_WAIT_V(8); PG8_WAIT_L(0); PG8_BAR; PG8_MMA(0, 0, At, B0); PG8_MMA(0, 1, At, B1); PG8_BAR; PG8_SCHED;
;             PG8_LDA(At, 1, 1); PG8_STAGE(PG8_SB(1, 0), b3, voffB); PG8_STAGE(PG8_SB(1, 1), b3 + hstepB, voffB); PG8_STAGE(PG8_SA(1, 0), a3, vo2);
;             PG8_WAIT_V(8); PG8_WAIT_L(0); PG8_BAR; PG8_MMA(1, 0, At, B0); PG8_MMA(1, 1, At, B1); PG8_BAR; PG8_SCHED;
;         }
	s_add_i32 s8, s10, s6
	s_mov_b32 m0, s8
	ds_read_b128 v[164:167], v201 offset:49152
	ds_read_b128 v[168:171], v201 offset:50176
	ds_read_b128 v[172:175], v201 offset:51200
	ds_read_b128 v[176:179], v201 offset:52224
	ds_read_b128 v[204:207], v201 offset:53248
	ds_read_b128 v[208:211], v201 offset:54272
	ds_read_b128 v[212:215], v201 offset:55296
	ds_read_b128 v[216:219], v201 offset:56320
	global_load_lds_dwordx4 v180, s[98:99]
	s_add_i32 m0, s8, 0x2000
	s_add_u32 s0, s0, 0x80080
	s_addc_u32 s1, s1, 0
	s_add_i32 s8, s43, s6
	global_load_lds_dwordx4 v182, s[98:99]
	s_mov_b32 m0, s8
	s_nop 0
	global_load_lds_dwordx4 v180, s[0:1]
	s_add_i32 m0, s8, 0x2000
	s_nop 0
	global_load_lds_dwordx4 v182, s[0:1]
	s_mov_b32 m0, s95
	s_nop 0
	global_load_lds_dwordx4 v226, s[78:79]
	s_mov_b32 m0, s96
	s_nop 0
	global_load_lds_dwordx4 v227, s[78:79]
	s_waitcnt vmcnt(8)
	s_waitcnt lgkmcnt(0)
	s_barrier
	s_setprio 1
	s_waitcnt lgkmcnt(0)
	v_mfma_f32_16x16x32_bf16 v[64:67], v[132:135], v[164:167], v[64:67]
	v_mfma_f32_16x16x32_bf16 v[60:63], v[140:143], v[164:167], v[60:63]
	v_mfma_f32_16x16x32_bf16 v[48:51], v[132:135], v[172:175], v[48:51]
	v_mfma_f32_16x16x32_bf16 v[44:47], v[140:143], v[172:175], v[44:47]
	v_mfma_f32_16x16x32_bf16 v[32:35], v[132:135], v[204:207], v[32:35]
	v_mfma_f32_16x16x32_bf16 v[28:31], v[140:143], v[204:207], v[28:31]
	v_mfma_f32_16x16x32_bf16 v[16:19], v[132:135], v[212:215], v[16:19]
	v_mfma_f32_16x16x32_bf16 v[8:11], v[140:143], v[212:215], v[8:11]
	v_mfma_f32_16x16x32_bf16 v[64:67], v[136:139], v[168:171], v[64:67]
	v_mfma_f32_16x16x32_bf16 v[60:63], v[144:147], v[168:171], v[60:63]
	v_mfma_f32_16x16x32_bf16 v[48:51], v[136:139], v[176:179], v[48:51]
	v_mfma_f32_16x16x32_bf16 v[44:47], v[144:147], v[176:179], v[44:47]
	v_mfma_f32_16x16x32_bf16 v[32:35], v[136:139], v[208:211], v[32:35]
	v_mfma_f32_16x16x32_bf16 v[28:31], v[144:147], v[208:211], v[28:31]
	v_mfma_f32_16x16x32_bf16 v[16:19], v[136:139], v[216:219], v[16:19]
	v_mfma_f32_16x16x32_bf16 v[8:11], v[144:147], v[216:219], v[8:11]
	s_setprio 0
	s_setprio 1
	v_mfma_f32_16x16x32_bf16 v[56:59], v[148:151], v[164:167], v[56:59]
	v_mfma_f32_16x16x32_bf16 v[52:55], v[156:159], v[164:167], v[52:55]
	v_mfma_f32_16x16x32_bf16 v[40:43], v[148:151], v[172:175], v[40:43]
	v_mfma_f32_16x16x32_bf16 v[36:39], v[156:159], v[172:175], v[36:39]
	v_mfma_f32_16x16x32_bf16 v[24:27], v[148:151], v[204:207], v[24:27]
	v_mfma_f32_16x16x32_bf16 v[20:23], v[156:159], v[204:207], v[20:23]
	v_mfma_f32_16x16x32_bf16 v[12:15], v[148:151], v[212:215], v[12:15]
	v_mfma_f32_16x16x32_bf16 v[4:7], v[156:159], v[212:215], v[4:7]
	v_mfma_f32_16x16x32_bf16 v[56:59], v[152:155], v[168:171], v[56:59]
	v_mfma_f32_16x16x32_bf16 v[52:55], v[160:163], v[168:171], v[52:55]
	v_mfma_f32_16x16x32_bf16 v[40:43], v[152:155], v[176:179], v[40:43]
	v_mfma_f32_16x16x32_bf16 v[36:39], v[160:163], v[176:179], v[36:39]
	v_mfma_f32_16x16x32_bf16 v[24:27], v[152:155], v[208:211], v[24:27]
	v_mfma_f32_16x16x32_bf16 v[20:23], v[160:163], v[208:211], v[20:23]
	v_mfma_f32_16x16x32_bf16 v[12:15], v[152:155], v[216:219], v[12:15]
	v_mfma_f32_16x16x32_bf16 v[4:7], v[160:163], v[216:219], v[4:7]
	s_setprio 0
	s_barrier
	s_add_i32 s72, s72, 2
	s_add_u32 s74, s74, 0x100
	s_addc_u32 s75, s75, 0
	s_cmp_gt_u32 s37, 29
	s_cbranch_scc1 .LBB0_634

; #define PG8_STAGE(bufoff, gbase, voff) do { _Pragma("unroll") for (int _i = 0; _i < 2; ++_i) \
;         __builtin_amdgcn_global_load_lds((const unsigned*)((const char*)(gbase) + (voff)[_i]), (LAS unsigned*)(lds + (bufoff) + ldsw + _i * 8192), 16, 0, 0); } while (0)
; #define PG8_WAIT_V(n) asm volatile("s_waitcnt vmcnt(" #n ")" ::: "memory")
; #define PG8_WAIT_L(n) asm volatile("s_waitcnt lgkmcnt(" #n ")" ::: "memory")
; #define PG8_BAR __builtin_amdgcn_s_barrier()
; template <class Epi, bool ALIGN_EPI, bool SPLITA>
; __device__ __forceinline__ void gemm_phase(LAS unsigned char* lds, const Gemm g, const StaticOrder& S, const Epi& E) {
;     ...
;         for (int t = 0; t < nt; t += 2) {
;             const bool last = (t == nt - 2);
;             if constexpr (Epi::MIDK) { if (t == g.ksplit) E.mid(acc, cur, wr, wc, fr, fq); }
;             const char *a1, *a2;
;             if constexpr (SPLITA) {
;                 a1 = (t + 1 < g.ksplit) ? cA + (size_t)(t + 1) * kstep : cA2 + (size_t)(t + 1 - g.ksplit) * 2048;
;                 a2 = last ? nA : ((t + 2 < g.ksplit) ? cA + (size_t)(t + 2) * kstep : cA2 + (size_t)(t + 2 - g.ksplit) * 2048);
;             } else { a1 = cA + kofs(t + 1); a2 = last ? nA : cA + kofs(t + 2); }
;             const char* b2 = last ? nB : cB + (size_t)(t + 2) * kstepB;
;             const bool s2a = SPLITA && (t + 1 >= g.ksplit), s2b = SPLITA && !last && (t + 2 >= g.ksplit);
;             const char* a3 = a2 + ((Epi::KSUB || s2b) ? (size_t)2048 : kstep); const char* b3 = b2 + kstepB;
;             const bool m1 = SPLITA && mirC && (t + 1 < g.ksplit), m2 = SPLITA && (last ? mirN : (mirC && (t + 2 < g.ksplit)));
;             const unsigned vo1[2] = {s2a ? voffA2[0] : m1 ? voffAm[0] : voffA[0], s2a ? voffA2[1] : m1 ? voffAm[1] : voffA[1]}, vo2[2] = {s2b ? voffA2[0] : m2 ? voffAm[0] : voffA[0], s2b ? voffA2[1] : m2 ? voffAm[1] : voffA[1]};
;             const char* a1h = m1 ? a1 - hstepA : a1 + hstepA; const char* a2h = m2 ? a2 - hstepA : a2 + hstepA;
;             PG8_LDB(B0, 0, 0); PG8_LDB(B1, 0, 1); PG8_SCHED; PG8_LDA(At, 0, 0); PG8_STAGE(PG8_SA(1, 1), a1h, vo1);
;             PG8_WAIT_V(8); PG8_WAIT_L(0); PG8_BAR; PG8_MMA(0, 0, At, B0); PG8_MMA(0, 1, At, B1); PG8_BAR; PG8_SCHED;
;             PG8_LDA(At, 0, 1); PG8_STAGE(PG8_SB(0, 0), b2, voffB); PG8_STAGE(PG8_SB(0, 1), b2 + hstepB, voffB); PG8_STAGE(PG8_SA(0, 0), a2, vo2);
.LBB0_709:
	s_add_i32 s65, s44, 2
	s_lshr_b32 s8, s65, 2
	s_lshl_b64 s[12:13], s[8:9], 17
	s_add_i32 s8, s64, 0xfffff000
	s_and_b32 s8, s8, 0x1000
	s_add_u32 s12, s42, s12
	s_addc_u32 s13, s43, s13
	s_add_u32 s45, s12, s8
	s_addc_u32 s46, s13, 0
	s_add_i32 s8, s44, 4
	ds_read_b128 v[130:133], v189
	ds_read_b128 v[134:137], v189 offset:1024
	ds_read_b128 v[138:141], v189 offset:2048
	ds_read_b128 v[142:145], v189 offset:3072
	ds_read_b128 v[146:149], v192
	ds_read_b128 v[150:153], v192 offset:1024
	ds_read_b128 v[166:169], v192 offset:2048
	ds_read_b128 v[170:173], v192 offset:3072
	s_lshr_b32 s8, s8, 2
	s_lshl_b64 s[12:13], s[8:9], 17
	s_and_b32 s8, s64, 0x1000
	s_add_u32 s12, s42, s12
	s_addc_u32 s13, s43, s13
	s_add_u32 s8, s12, s8
	s_addc_u32 s47, s13, 0
	s_add_u32 s12, s45, 0x10800
	s_addc_u32 s13, s46, 0
	s_cmp_eq_u32 s44, 12
	s_cselect_b32 s44, s57, s60
	s_cselect_b32 s47, s23, s47
	s_cselect_b32 s46, s39, s8
	s_cselect_b32 s45, s25, s61
	s_add_i32 m0, s7, 0xc000
	ds_read_b128 v[178:181], v193
	ds_read_b128 v[184:187], v193 offset:1024
	ds_read_b128 v[194:197], v193 offset:2048
	ds_read_b128 v[198:201], v193 offset:3072
	ds_read_b128 v[202:205], v193 offset:4096
	ds_read_b128 v[206:209], v193 offset:5120
	ds_read_b128 v[210:213], v193 offset:6144
	ds_read_b128 v[214:217], v193 offset:7168
	global_load_lds_dwordx4 v154, s[12:13]
	s_add_i32 m0, s7, 0xe000
	s_nop 0
	global_load_lds_dwordx4 v158, s[12:13]
	s_waitcnt vmcnt(8)
	s_waitcnt lgkmcnt(0)
	s_barrier
	s_setprio 1
	s_waitcnt lgkmcnt(0)
	v_mfma_f32_16x16x32_bf16 v[126:129], v[130:133], v[178:181], v[126:129]
	v_mfma_f32_16x16x32_bf16 v[122:125], v[138:141], v[178:181], v[122:125]
	v_mfma_f32_16x16x32_bf16 v[110:113], v[130:133], v[194:197], v[110:113]
	v_mfma_f32_16x16x32_bf16 v[106:109], v[138:141], v[194:197], v[106:109]
	v_mfma_f32_16x16x32_bf16 v[94:97], v[130:133], v[202:205], v[94:97]
	v_mfma_f32_16x16x32_bf16 v[90:93], v[138:141], v[202:205], v[90:93]
	v_mfma_f32_16x16x32_bf16 v[78:81], v[130:133], v[210:213], v[78:81]
	v_mfma_f32_16x16x32_bf16 v[74:77], v[138:141], v[210:213], v[74:77]
	v_mfma_f32_16x16x32_bf16 v[126:129], v[134:137], v[184:187], v[126:129]
	v_mfma_f32_16x16x32_bf16 v[122:125], v[142:145], v[184:187], v[122:125]
	v_mfma_f32_16x16x32_bf16 v[110:113], v[134:137], v[198:201], v[110:113]
	v_mfma_f32_16x16x32_bf16 v[106:109], v[142:145], v[198:201], v[106:109]
	v_mfma_f32_16x16x32_bf16 v[94:97], v[134:137], v[206:209], v[94:97]
	v_mfma_f32_16x16x32_bf16 v[90:93], v[142:145], v[206:209], v[90:93]
	v_mfma_f32_16x16x32_bf16 v[78:81], v[134:137], v[214:217], v[78:81]
	v_mfma_f32_16x16x32_bf16 v[74:77], v[142:145], v[214:217], v[74:77]
	s_setprio 0
	s_setprio 1
	v_mfma_f32_16x16x32_bf16 v[118:121], v[146:149], v[178:181], v[118:121]
	v_mfma_f32_16x16x32_bf16 v[114:117], v[166:169], v[178:181], v[114:117]
	v_mfma_f32_16x16x32_bf16 v[102:105], v[146:149], v[194:197], v[102:105]
	v_mfma_f32_16x16x32_bf16 v[98:101], v[166:169], v[194:197], v[98:101]
	v_mfma_f32_16x16x32_bf16 v[86:89], v[146:149], v[202:205], v[86:89]
	v_mfma_f32_16x16x32_bf16 v[82:85], v[166:169], v[202:205], v[82:85]
	v_mfma_f32_16x16x32_bf16 v[70:73], v[146:149], v[210:213], v[70:73]
	v_mfma_f32_16x16x32_bf16 v[66:69], v[166:169], v[210:213], v[66:69]
	v_mfma_f32_16x16x32_bf16 v[118:121], v[150:153], v[184:187], v[118:121]
	v_mfma_f32_16x16x32_bf16 v[114:117], v[170:173], v[184:187], v[114:117]
	v_mfma_f32_16x16x32_bf16 v[102:105], v[150:153], v[198:201], v[102:105]
	v_mfma_f32_16x16x32_bf16 v[98:101], v[170:173], v[198:201], v[98:101]
	v_mfma_f32_16x16x32_bf16 v[86:89], v[150:153], v[206:209], v[86:89]
	v_mfma_f32_16x16x32_bf16 v[82:85], v[170:173], v[206:209], v[82:85]
	v_mfma_f32_16x16x32_bf16 v[70:73], v[150:153], v[214:217], v[70:73]
	v_mfma_f32_16x16x32_bf16 v[66:69], v[170:173], v[214:217], v[66:69]
	s_setprio 0
	s_barrier
	s_add_u32 s98, s44, s16
	s_addc_u32 s99, s45, s17
	s_add_u32 s100, s46, s18
	s_addc_u32 s101, s47, s19
	s_add_i32 s8, s54, s6
	s_mov_b32 m0, s8
	ds_read_b128 v[178:181], v193 offset:16384
	ds_read_b128 v[184:187], v193 offset:17408
	ds_read_b128 v[194:197], v193 offset:18432
	ds_read_b128 v[198:201], v193 offset:19456
	ds_read_b128 v[202:205], v193 offset:20480
	ds_read_b128 v[206:209], v193 offset:21504
	ds_read_b128 v[210:213], v193 offset:22528
	ds_read_b128 v[214:217], v193 offset:23552
	global_load_lds_dwordx4 v156, s[44:45]
	s_add_i32 m0, s8, 0x2000
	s_add_u32 s12, s44, 0x40000
	s_addc_u32 s13, s45, 0
	s_add_i32 s8, s55, s6
	global_load_lds_dwordx4 v160, s[44:45]
	s_mov_b32 m0, s8
	s_nop 0
	global_load_lds_dwordx4 v156, s[12:13]
	s_add_i32 m0, s8, 0x2000
	s_nop 0
	global_load_lds_dwordx4 v160, s[12:13]
	s_mov_b32 m0, s7
	s_nop 0
	global_load_lds_dwordx4 v154, s[46:47]
	s_mov_b32 m0, s33
	s_nop 0
	global_load_lds_dwordx4 v158, s[46:47]
	s_waitcnt vmcnt(8)
	s_waitcnt lgkmcnt(0)
	s_barrier
; #define PG8_STAGE(bufoff, gbase, voff) do { _Pragma("unroll") for (int _i = 0; _i < 2; ++_i) \
;         __builtin_amdgcn_global_load_lds((const unsigned*)((const char*)(gbase) + (voff)[_i]), (LAS unsigned*)(lds + (bufoff) + ldsw + _i * 8192), 16, 0, 0); } while (0)
; #define PG8_LDA(dst, b, h) do { _Pragma("unroll") for (int m = 0; m < 4; ++m) _Pragma("unroll") for (int k = 0; k < 2; ++k) dst[m][k] = *(const LAS bf16x8*)(lds + PG8_SA(b, h) + aoff + m * 2048 + k * 1024); } while (0)
; #define PG8_LDB(dst, b, h) do { _Pragma("unroll") for (int n = 0; n < 2; ++n) _Pragma("unroll") for (int k = 0; k < 2; ++k) dst[n][k] = *(const LAS bf16x8*)(lds + PG8_SB(b, h) + boff + n * 2048 + k * 1024); } while (0)
; #define PG8_MMA(ai, bj, At, Bt) do { __builtin_amdgcn_s_setprio(1); _Pragma("unroll") for (int m = 0; m < 4; ++m) _Pragma("unroll") for (int n = 0; n < 2; ++n) _Pragma("unroll") for (int k = 0; k < 2; ++k) \
;         acc[ai][bj][m][n] = __builtin_amdgcn_mfma_f32_16x16x32_bf16(Bt[n][k], At[m][k], acc[ai][bj][m][n], 0, 0, 0); __builtin_amdgcn_s_setprio(0); } while (0)
; #define PG8_WAIT_V(n) asm volatile("s_waitcnt vmcnt(" #n ")" ::: "memory")
; #define PG8_BAR __builtin_amdgcn_s_barrier()
; template <class Epi, bool ALIGN_EPI, bool SPLITA>
; __device__ __forceinline__ void gemm_phase(LAS unsigned char* lds, const Gemm g, const StaticOrder& S, const Epi& E) {
;     ...
;             PG8_LDB(B0, 0, 0); PG8_LDB(B1, 0, 1); PG8_SCHED; PG8_LDA(At, 0, 0); PG8_STAGE(PG8_SA(1, 1), a1h, vo1);
;             PG8_WAIT_V(8); PG8_WAIT_L(0); PG8_BAR; PG8_MMA(0, 0, At, B0); PG8_MMA(0, 1, At, B1); PG8_BAR; PG8_SCHED;
;             PG8_LDA(At, 0, 1); PG8_STAGE(PG8_SB(0, 0), b2, voffB); PG8_STAGE(PG8_SB(0, 1), b2 + hstepB, voffB); PG8_STAGE(PG8_SA(0, 0), a2, vo2);
;             PG8_WAIT_V(8); PG8_WAIT_L(0); PG8_BAR; PG8_MMA(1, 0, At, B0); PG8_MMA(1, 1, At, B1); PG8_BAR; PG8_SCHED;
;             PG8_LDB(B0, 1, 0); PG8_LDB(B1, 1, 1); PG8_SCHED; PG8_LDA(At, 1, 0); PG8_STAGE(PG8_SA(0, 1), a2h, vo2);
;             PG8_WAIT_V(8); PG8_WAIT_L(0); PG8_BAR; PG8_MMA(0, 0, At, B0); PG8_MMA(0, 1, At, B1); PG8_BAR; PG8_SCHED;
;             PG8_LDA(At, 1, 1); PG8_STAGE(PG8_SB(1, 0), b3, voffB); PG8_STAGE(PG8_SB(1, 1), b3 + hstepB, voffB); PG8_STAGE(PG8_SA(1, 0), a3, vo2);
;             PG8_WAIT_V(8); PG8_WAIT_L(0); PG8_BAR; PG8_MMA(1, 0, At, B0); PG8_MMA(1, 1, At, B1); PG8_BAR; PG8_SCHED;
	s_setprio 1
	s_waitcnt lgkmcnt(0)
	v_mfma_f32_16x16x32_bf16 v[62:65], v[130:133], v[178:181], v[62:65]
	v_mfma_f32_16x16x32_bf16 v[58:61], v[138:141], v[178:181], v[58:61]
	v_mfma_f32_16x16x32_bf16 v[38:41], v[130:133], v[194:197], v[38:41]
	v_mfma_f32_16x16x32_bf16 v[34:37], v[138:141], v[194:197], v[34:37]
	v_mfma_f32_16x16x32_bf16 v[22:25], v[130:133], v[202:205], v[22:25]
	v_mfma_f32_16x16x32_bf16 v[18:21], v[138:141], v[202:205], v[18:21]
	v_mfma_f32_16x16x32_bf16 v[6:9], v[130:133], v[210:213], v[6:9]
	v_mfma_f32_16x16x32_bf16 v[2:5], v[138:141], v[210:213], v[2:5]
	v_mfma_f32_16x16x32_bf16 v[62:65], v[134:137], v[184:187], v[62:65]
	v_mfma_f32_16x16x32_bf16 v[58:61], v[142:145], v[184:187], v[58:61]
	v_mfma_f32_16x16x32_bf16 v[38:41], v[134:137], v[198:201], v[38:41]
	v_mfma_f32_16x16x32_bf16 v[34:37], v[142:145], v[198:201], v[34:37]
	v_mfma_f32_16x16x32_bf16 v[22:25], v[134:137], v[206:209], v[22:25]
	v_mfma_f32_16x16x32_bf16 v[18:21], v[142:145], v[206:209], v[18:21]
	v_mfma_f32_16x16x32_bf16 v[6:9], v[134:137], v[214:217], v[6:9]
	v_mfma_f32_16x16x32_bf16 v[2:5], v[142:145], v[214:217], v[2:5]
	s_setprio 0
	s_setprio 1
	v_mfma_f32_16x16x32_bf16 v[54:57], v[146:149], v[178:181], v[54:57]
	v_mfma_f32_16x16x32_bf16 v[46:49], v[166:169], v[178:181], v[46:49]
	v_mfma_f32_16x16x32_bf16 v[50:53], v[146:149], v[194:197], v[50:53]
	v_mfma_f32_16x16x32_bf16 v[42:45], v[166:169], v[194:197], v[42:45]
	v_mfma_f32_16x16x32_bf16 v[30:33], v[146:149], v[202:205], v[30:33]
	v_mfma_f32_16x16x32_bf16 v[26:29], v[166:169], v[202:205], v[26:29]
	v_mfma_f32_16x16x32_bf16 v[14:17], v[146:149], v[210:213], v[14:17]
	v_mfma_f32_16x16x32_bf16 v[10:13], v[166:169], v[210:213], v[10:13]
	v_mfma_f32_16x16x32_bf16 v[54:57], v[150:153], v[184:187], v[54:57]
	v_mfma_f32_16x16x32_bf16 v[46:49], v[170:173], v[184:187], v[46:49]
	v_mfma_f32_16x16x32_bf16 v[50:53], v[150:153], v[198:201], v[50:53]
	v_mfma_f32_16x16x32_bf16 v[42:45], v[170:173], v[198:201], v[42:45]
	v_mfma_f32_16x16x32_bf16 v[30:33], v[150:153], v[206:209], v[30:33]
	v_mfma_f32_16x16x32_bf16 v[26:29], v[170:173], v[206:209], v[26:29]
	v_mfma_f32_16x16x32_bf16 v[14:17], v[150:153], v[214:217], v[14:17]
	v_mfma_f32_16x16x32_bf16 v[10:13], v[170:173], v[214:217], v[10:13]
	s_setprio 0
	s_barrier
	s_add_i32 s8, 0, 0x18000
	s_add_i32 s70, 0, 0x1c000
	v_add_u32_e32 v142, s8, v177
	v_add_u32_e32 v170, s70, v177
	ds_read_b128 v[130:133], v142
	ds_read_b128 v[134:137], v142 offset:1024
	ds_read_b128 v[138:141], v142 offset:2048
	ds_read_b128 v[142:145], v142 offset:3072
	ds_read_b128 v[146:149], v170
	ds_read_b128 v[150:153], v170 offset:1024
	ds_read_b128 v[166:169], v170 offset:2048
	ds_read_b128 v[170:173], v170 offset:3072
	s_add_u32 s12, s46, 0x10000
	s_addc_u32 s13, s47, 0
	s_mov_b32 m0, s41
	ds_read_b128 v[178:181], v193 offset:32768
	ds_read_b128 v[184:187], v193 offset:33792
	ds_read_b128 v[194:197], v193 offset:34816
	ds_read_b128 v[198:201], v193 offset:35840
	ds_read_b128 v[202:205], v193 offset:36864
	ds_read_b128 v[206:209], v193 offset:37888
	ds_read_b128 v[210:213], v193 offset:38912
	ds_read_b128 v[214:217], v193 offset:39936
	global_load_lds_dwordx4 v154, s[12:13]
	s_mov_b32 m0, s48
	s_nop 0
	global_load_lds_dwordx4 v158, s[12:13]
	s_waitcnt vmcnt(8)
	s_waitcnt lgkmcnt(0)
	s_barrier
	s_setprio 1
	s_waitcnt lgkmcnt(0)
	v_mfma_f32_16x16x32_bf16 v[126:129], v[130:133], v[178:181], v[126:129]
	v_mfma_f32_16x16x32_bf16 v[122:125], v[138:141], v[178:181], v[122:125]
	v_mfma_f32_16x16x32_bf16 v[110:113], v[130:133], v[194:197], v[110:113]
	v_mfma_f32_16x16x32_bf16 v[106:109], v[138:141], v[194:197], v[106:109]
	v_mfma_f32_16x16x32_bf16 v[94:97], v[130:133], v[202:205], v[94:97]
	v_mfma_f32_16x16x32_bf16 v[90:93], v[138:141], v[202:205], v[90:93]
	v_mfma_f32_16x16x32_bf16 v[78:81], v[130:133], v[210:213], v[78:81]
	v_mfma_f32_16x16x32_bf16 v[74:77], v[138:141], v[210:213], v[74:77]
	v_mfma_f32_16x16x32_bf16 v[126:129], v[134:137], v[184:187], v[126:129]
	v_mfma_f32_16x16x32_bf16 v[122:125], v[142:145], v[184:187], v[122:125]
	v_mfma_f32_16x16x32_bf16 v[110:113], v[134:137], v[198:201], v[110:113]
	v_mfma_f32_16x16x32_bf16 v[106:109], v[142:145], v[198:201], v[106:109]
	v_mfma_f32_16x16x32_bf16 v[94:97], v[134:137], v[206:209], v[94:97]
	v_mfma_f32_16x16x32_bf16 v[90:93], v[142:145], v[206:209], v[90:93]
	v_mfma_f32_16x16x32_bf16 v[78:81], v[134:137], v[214:217], v[78:81]
	v_mfma_f32_16x16x32_bf16 v[74:77], v[142:145], v[214:217], v[74:77]
	s_setprio 0
	s_setprio 1
	v_mfma_f32_16x16x32_bf16 v[118:121], v[146:149], v[178:181], v[118:121]
	v_mfma_f32_16x16x32_bf16 v[114:117], v[166:169], v[178:181], v[114:117]
	v_mfma_f32_16x16x32_bf16 v[102:105], v[146:149], v[194:197], v[102:105]
	v_mfma_f32_16x16x32_bf16 v[98:101], v[166:169], v[194:197], v[98:101]
	v_mfma_f32_16x16x32_bf16 v[86:89], v[146:149], v[202:205], v[86:89]
	v_mfma_f32_16x16x32_bf16 v[82:85], v[166:169], v[202:205], v[82:85]
	v_mfma_f32_16x16x32_bf16 v[70:73], v[146:149], v[210:213], v[70:73]
	v_mfma_f32_16x16x32_bf16 v[66:69], v[166:169], v[210:213], v[66:69]
	v_mfma_f32_16x16x32_bf16 v[118:121], v[150:153], v[184:187], v[118:121]
	v_mfma_f32_16x16x32_bf16 v[114:117], v[170:173], v[184:187], v[114:117]
	v_mfma_f32_16x16x32_bf16 v[102:105], v[150:153], v[198:201], v[102:105]
	v_mfma_f32_16x16x32_bf16 v[98:101], v[170:173], v[198:201], v[98:101]
	v_mfma_f32_16x16x32_bf16 v[86:89], v[150:153], v[206:209], v[86:89]
	v_mfma_f32_16x16x32_bf16 v[82:85], v[170:173], v[206:209], v[82:85]
	v_mfma_f32_16x16x32_bf16 v[70:73], v[150:153], v[214:217], v[70:73]
	v_mfma_f32_16x16x32_bf16 v[66:69], v[170:173], v[214:217], v[66:69]
	s_setprio 0
	s_barrier
; #define PG8_STAGE(bufoff, gbase, voff) do { _Pragma("unroll") for (int _i = 0; _i < 2; ++_i) \
;         __builtin_amdgcn_global_load_lds((const unsigned*)((const char*)(gbase) + (voff)[_i]), (LAS unsigned*)(lds + (bufoff) + ldsw + _i * 8192), 16, 0, 0); } while (0)
; #define PG8_LDA(dst, b, h) do { _Pragma("unroll") for (int m = 0; m < 4; ++m) _Pragma("unroll") for (int k = 0; k < 2; ++k) dst[m][k] = *(const LAS bf16x8*)(lds + PG8_SA(b, h) + aoff + m * 2048 + k * 1024); } while (0)
; #define PG8_MMA(ai, bj, At, Bt) do { __builtin_amdgcn_s_setprio(1); _Pragma("unroll") for (int m = 0; m < 4; ++m) _Pragma("unroll") for (int n = 0; n < 2; ++n) _Pragma("unroll") for (int k = 0; k < 2; ++k) \
;         acc[ai][bj][m][n] = __builtin_amdgcn_mfma_f32_16x16x32_bf16(Bt[n][k], At[m][k], acc[ai][bj][m][n], 0, 0, 0); __builtin_amdgcn_s_setprio(0); } while (0)
; #define PG8_WAIT_V(n) asm volatile("s_waitcnt vmcnt(" #n ")" ::: "memory")
; #define PG8_WAIT_L(n) asm volatile("s_waitcnt lgkmcnt(" #n ")" ::: "memory")
; #define PG8_BAR __builtin_amdgcn_s_barrier()
; #define PG8_SCHED __builtin_amdgcn_sched_barrier(0)
; template <class Epi, bool ALIGN_EPI, bool SPLITA>
; __device__ __forceinline__ void gemm_phase(LAS unsigned char* lds, const Gemm g, const StaticOrder& S, const Epi& E) {
;     ...
;         for (int t = 0; t < nt; t += 2) {
;             const bool last = (t == nt - 2);
;     ...
;             PG8_LDA(At, 1, 1); PG8_STAGE(PG8_SB(1, 0), b3, voffB); PG8_STAGE(PG8_SB(1, 1), b3 + hstepB, voffB); PG8_STAGE(PG8_SA(1, 0), a3, vo2);
;             PG8_WAIT_V(8); PG8_WAIT_L(0); PG8_BAR; PG8_MMA(1, 0, At, B0); PG8_MMA(1, 1, At, B1); PG8_BAR; PG8_SCHED;
	s_add_i32 s8, s8, s6
	s_mov_b32 m0, s8
	ds_read_b128 v[178:181], v193 offset:49152
	ds_read_b128 v[184:187], v193 offset:50176
	ds_read_b128 v[194:197], v193 offset:51200
	ds_read_b128 v[198:201], v193 offset:52224
	ds_read_b128 v[202:205], v193 offset:53248
	ds_read_b128 v[206:209], v193 offset:54272
	ds_read_b128 v[210:213], v193 offset:55296
	ds_read_b128 v[214:217], v193 offset:56320
	global_load_lds_dwordx4 v156, s[98:99]
	s_add_i32 m0, s8, 0x2000
	s_add_u32 s12, s44, 0x40080
	s_addc_u32 s13, s45, 0
	s_add_i32 s8, s70, s6
	global_load_lds_dwordx4 v160, s[98:99]
	s_mov_b32 m0, s8
	s_nop 0
	global_load_lds_dwordx4 v156, s[12:13]
	s_add_i32 m0, s8, 0x2000
	s_nop 0
	global_load_lds_dwordx4 v160, s[12:13]
	s_mov_b32 m0, s49
	s_nop 0
	global_load_lds_dwordx4 v154, s[100:101]
	s_mov_b32 m0, s50
	s_nop 0
	global_load_lds_dwordx4 v158, s[100:101]
	s_waitcnt vmcnt(8)
	s_waitcnt lgkmcnt(0)
	s_barrier
	s_setprio 1
	s_waitcnt lgkmcnt(0)
	v_mfma_f32_16x16x32_bf16 v[62:65], v[130:133], v[178:181], v[62:65]
	v_mfma_f32_16x16x32_bf16 v[58:61], v[138:141], v[178:181], v[58:61]
	v_mfma_f32_16x16x32_bf16 v[38:41], v[130:133], v[194:197], v[38:41]
	v_mfma_f32_16x16x32_bf16 v[34:37], v[138:141], v[194:197], v[34:37]
	v_mfma_f32_16x16x32_bf16 v[22:25], v[130:133], v[202:205], v[22:25]
	v_mfma_f32_16x16x32_bf16 v[18:21], v[138:141], v[202:205], v[18:21]
	v_mfma_f32_16x16x32_bf16 v[6:9], v[130:133], v[210:213], v[6:9]
	v_mfma_f32_16x16x32_bf16 v[2:5], v[138:141], v[210:213], v[2:5]
	v_mfma_f32_16x16x32_bf16 v[62:65], v[134:137], v[184:187], v[62:65]
	v_mfma_f32_16x16x32_bf16 v[58:61], v[142:145], v[184:187], v[58:61]
	v_mfma_f32_16x16x32_bf16 v[38:41], v[134:137], v[198:201], v[38:41]
	v_mfma_f32_16x16x32_bf16 v[34:37], v[142:145], v[198:201], v[34:37]
	v_mfma_f32_16x16x32_bf16 v[22:25], v[134:137], v[206:209], v[22:25]
	v_mfma_f32_16x16x32_bf16 v[18:21], v[142:145], v[206:209], v[18:21]
	v_mfma_f32_16x16x32_bf16 v[6:9], v[134:137], v[214:217], v[6:9]
	v_mfma_f32_16x16x32_bf16 v[2:5], v[142:145], v[214:217], v[2:5]
	s_setprio 0
	s_setprio 1
	v_mfma_f32_16x16x32_bf16 v[54:57], v[146:149], v[178:181], v[54:57]
	v_mfma_f32_16x16x32_bf16 v[46:49], v[166:169], v[178:181], v[46:49]
	v_mfma_f32_16x16x32_bf16 v[50:53], v[146:149], v[194:197], v[50:53]
	v_mfma_f32_16x16x32_bf16 v[42:45], v[166:169], v[194:197], v[42:45]
	v_mfma_f32_16x16x32_bf16 v[30:33], v[146:149], v[202:205], v[30:33]
	v_mfma_f32_16x16x32_bf16 v[26:29], v[166:169], v[202:205], v[26:29]
	v_mfma_f32_16x16x32_bf16 v[14:17], v[146:149], v[210:213], v[14:17]
	v_mfma_f32_16x16x32_bf16 v[10:13], v[166:169], v[210:213], v[10:13]
	v_mfma_f32_16x16x32_bf16 v[54:57], v[150:153], v[184:187], v[54:57]
	v_mfma_f32_16x16x32_bf16 v[46:49], v[170:173], v[184:187], v[46:49]
	v_mfma_f32_16x16x32_bf16 v[50:53], v[150:153], v[198:201], v[50:53]
	v_mfma_f32_16x16x32_bf16 v[42:45], v[170:173], v[198:201], v[42:45]
	v_mfma_f32_16x16x32_bf16 v[30:33], v[150:153], v[206:209], v[30:33]
	v_mfma_f32_16x16x32_bf16 v[26:29], v[170:173], v[206:209], v[26:29]
	v_mfma_f32_16x16x32_bf16 v[14:17], v[150:153], v[214:217], v[14:17]
	v_mfma_f32_16x16x32_bf16 v[10:13], v[170:173], v[214:217], v[10:13]
	s_setprio 0
	s_barrier
	s_add_u32 s60, s60, 0x100
	s_addc_u32 s61, s61, 0
	s_addk_i32 s64, 0x1000
	s_cmp_gt_u32 s65, 13
	s_mov_b32 s44, s65
	s_cbranch_scc0 .LBB0_709
	s_and_b64 vcc, exec, s[20:21]
	s_cbranch_vccz .LBB0_712
	s_barrier

; #define PG8_STAGE(bufoff, gbase, voff) do { _Pragma("unroll") for (int _i = 0; _i < 2; ++_i) \
;         __builtin_amdgcn_global_load_lds((const unsigned*)((const char*)(gbase) + (voff)[_i]), (LAS unsigned*)(lds + (bufoff) + ldsw + _i * 8192), 16, 0, 0); } while (0)
; #define PG8_LDA(dst, b, h) do { _Pragma("unroll") for (int m = 0; m < 4; ++m) _Pragma("unroll") for (int k = 0; k < 2; ++k) dst[m][k] = *(const LAS bf16x8*)(lds + PG8_SA(b, h) + aoff + m * 2048 + k * 1024); } while (0)
; #define PG8_LDB(dst, b, h) do { _Pragma("unroll") for (int n = 0; n < 2; ++n) _Pragma("unroll") for (int k = 0; k < 2; ++k) dst[n][k] = *(const LAS bf16x8*)(lds + PG8_SB(b, h) + boff + n * 2048 + k * 1024); } while (0)
; #define PG8_MMA(ai, bj, At, Bt) do { __builtin_amdgcn_s_setprio(1); _Pragma("unroll") for (int m = 0; m < 4; ++m) _Pragma("unroll") for (int n = 0; n < 2; ++n) _Pragma("unroll") for (int k = 0; k < 2; ++k) \
;         acc[ai][bj][m][n] = __builtin_amdgcn_mfma_f32_16x16x32_bf16(Bt[n][k], At[m][k], acc[ai][bj][m][n], 0, 0, 0); __builtin_amdgcn_s_setprio(0); } while (0)
; #define PG8_WAIT_V(n) asm volatile("s_waitcnt vmcnt(" #n ")" ::: "memory")
; #define PG8_WAIT_L(n) asm volatile("s_waitcnt lgkmcnt(" #n ")" ::: "memory")
; #define PG8_BAR __builtin_amdgcn_s_barrier()
; #define PG8_SCHED __builtin_amdgcn_sched_barrier(0)
; template <class Epi, bool ALIGN_EPI, bool SPLITA>
; __device__ __forceinline__ void gemm_phase(LAS unsigned char* lds, const Gemm g, const StaticOrder& S, const Epi& E) {
;     ...
;             PG8_LDB(B0, 0, 0); PG8_LDB(B1, 0, 1); PG8_SCHED; PG8_LDA(At, 0, 0); PG8_STAGE(PG8_SA(1, 1), a1h, vo1);
;             PG8_WAIT_V(8); PG8_WAIT_L(0); PG8_BAR; PG8_MMA(0, 0, At, B0); PG8_MMA(0, 1, At, B1); PG8_BAR; PG8_SCHED;
;             PG8_LDA(At, 0, 1); PG8_STAGE(PG8_SB(0, 0), b2, voffB); PG8_STAGE(PG8_SB(0, 1), b2 + hstepB, voffB); PG8_STAGE(PG8_SA(0, 0), a2, vo2);
;             PG8_WAIT_V(8); PG8_WAIT_L(0); PG8_BAR; PG8_MMA(1, 0, At, B0); PG8_MMA(1, 1, At, B1); PG8_BAR; PG8_SCHED;
;     __device__ __forceinline__ void operator()(const Acc& acc, const Unit& u, int wr, int wc, int fr, int fq) const {
;     ...
;                 const int row = row0 + ai * HALF + m * 16; const float rinv = __builtin_amdgcn_rsqf(ssq[row] * (1.0f / DM) + EPS);
.LBB0_796:
	ds_read_b128 v[150:153], v155
	ds_read_b128 v[160:163], v155 offset:1024
	ds_read_b128 v[164:167], v155 offset:2048
	ds_read_b128 v[168:171], v155 offset:3072
	ds_read_b128 v[172:175], v156
	ds_read_b128 v[176:179], v156 offset:1024
	ds_read_b128 v[180:183], v156 offset:2048
	ds_read_b128 v[184:187], v156 offset:3072
	s_add_u32 s12, s36, 0xfffc0080
	s_addc_u32 s13, s37, -1
	s_cmp_eq_u32 s57, 12
	s_cselect_b32 s41, s19, s13
	s_cselect_b32 s40, s29, s12
	s_cselect_b32 s39, s21, s56
	s_cselect_b32 s38, s31, s55
	s_add_i32 m0, s42, 0xc000
	ds_read_b128 v[188:191], v157
	ds_read_b128 v[192:195], v157 offset:1024
	ds_read_b128 v[196:199], v157 offset:2048
	ds_read_b128 v[200:203], v157 offset:3072
	ds_read_b128 v[204:207], v157 offset:4096
	ds_read_b128 v[208:211], v157 offset:5120
	ds_read_b128 v[212:215], v157 offset:6144
	ds_read_b128 v[216:219], v157 offset:7168
	global_load_lds_dwordx4 v140, s[36:37]
	s_add_i32 m0, s42, 0xe000
	s_nop 0
	global_load_lds_dwordx4 v142, s[36:37]
	s_waitcnt vmcnt(8)
	s_waitcnt lgkmcnt(0)
	s_barrier
	s_setprio 1
	s_waitcnt lgkmcnt(0)
	v_mfma_f32_16x16x32_bf16 v[126:129], v[150:153], v[188:191], v[126:129]
	v_mfma_f32_16x16x32_bf16 v[122:125], v[164:167], v[188:191], v[122:125]
	v_mfma_f32_16x16x32_bf16 v[110:113], v[150:153], v[196:199], v[110:113]
	v_mfma_f32_16x16x32_bf16 v[106:109], v[164:167], v[196:199], v[106:109]
	v_mfma_f32_16x16x32_bf16 v[94:97], v[150:153], v[204:207], v[94:97]
	v_mfma_f32_16x16x32_bf16 v[90:93], v[164:167], v[204:207], v[90:93]
	v_mfma_f32_16x16x32_bf16 v[78:81], v[150:153], v[212:215], v[78:81]
	v_mfma_f32_16x16x32_bf16 v[74:77], v[164:167], v[212:215], v[74:77]
	v_mfma_f32_16x16x32_bf16 v[126:129], v[160:163], v[192:195], v[126:129]
	v_mfma_f32_16x16x32_bf16 v[122:125], v[168:171], v[192:195], v[122:125]
	v_mfma_f32_16x16x32_bf16 v[110:113], v[160:163], v[200:203], v[110:113]
	v_mfma_f32_16x16x32_bf16 v[106:109], v[168:171], v[200:203], v[106:109]
	v_mfma_f32_16x16x32_bf16 v[94:97], v[160:163], v[208:211], v[94:97]
	v_mfma_f32_16x16x32_bf16 v[90:93], v[168:171], v[208:211], v[90:93]
	v_mfma_f32_16x16x32_bf16 v[78:81], v[160:163], v[216:219], v[78:81]
	v_mfma_f32_16x16x32_bf16 v[74:77], v[168:171], v[216:219], v[74:77]
	s_setprio 0
	s_setprio 1
	v_mfma_f32_16x16x32_bf16 v[118:121], v[172:175], v[188:191], v[118:121]
	v_mfma_f32_16x16x32_bf16 v[114:117], v[180:183], v[188:191], v[114:117]
	v_mfma_f32_16x16x32_bf16 v[102:105], v[172:175], v[196:199], v[102:105]
	v_mfma_f32_16x16x32_bf16 v[98:101], v[180:183], v[196:199], v[98:101]
	v_mfma_f32_16x16x32_bf16 v[86:89], v[172:175], v[204:207], v[86:89]
	v_mfma_f32_16x16x32_bf16 v[82:85], v[180:183], v[204:207], v[82:85]
	v_mfma_f32_16x16x32_bf16 v[70:73], v[172:175], v[212:215], v[70:73]
	v_mfma_f32_16x16x32_bf16 v[66:69], v[180:183], v[212:215], v[66:69]
	v_mfma_f32_16x16x32_bf16 v[118:121], v[176:179], v[192:195], v[118:121]
	v_mfma_f32_16x16x32_bf16 v[114:117], v[184:187], v[192:195], v[114:117]
	v_mfma_f32_16x16x32_bf16 v[102:105], v[176:179], v[200:203], v[102:105]
	v_mfma_f32_16x16x32_bf16 v[98:101], v[184:187], v[200:203], v[98:101]
	v_mfma_f32_16x16x32_bf16 v[86:89], v[176:179], v[208:211], v[86:89]
	v_mfma_f32_16x16x32_bf16 v[82:85], v[184:187], v[208:211], v[82:85]
	v_mfma_f32_16x16x32_bf16 v[70:73], v[176:179], v[216:219], v[70:73]
	v_mfma_f32_16x16x32_bf16 v[66:69], v[184:187], v[216:219], v[66:69]
	s_setprio 0
	s_barrier
	s_add_u32 s98, s38, s8
	s_addc_u32 s99, s39, s9
	s_add_u32 s100, s40, s10
	s_addc_u32 s101, s41, s11
	s_add_i32 s12, s51, s6
	s_mov_b32 m0, s12
	ds_read_b128 v[188:191], v157 offset:16384
	ds_read_b128 v[192:195], v157 offset:17408
	ds_read_b128 v[196:199], v157 offset:18432
	ds_read_b128 v[200:203], v157 offset:19456
	ds_read_b128 v[204:207], v157 offset:20480
	ds_read_b128 v[208:211], v157 offset:21504
	ds_read_b128 v[212:215], v157 offset:22528
	ds_read_b128 v[216:219], v157 offset:23552
	global_load_lds_dwordx4 v134, s[38:39]
	s_add_i32 m0, s12, 0x2000
	s_add_u32 s12, s38, 0x40000
	s_addc_u32 s13, s39, 0
	s_add_i32 s60, s52, s6
	global_load_lds_dwordx4 v130, s[38:39]
	s_mov_b32 m0, s60
	s_nop 0
	global_load_lds_dwordx4 v134, s[12:13]
	s_add_i32 m0, s60, 0x2000
	s_nop 0
	global_load_lds_dwordx4 v130, s[12:13]
	s_mov_b32 m0, s42
	s_nop 0
	global_load_lds_dwordx4 v136, s[40:41]
	s_mov_b32 m0, s43
	s_nop 0
	global_load_lds_dwordx4 v132, s[40:41]
	s_waitcnt vmcnt(8)
	s_waitcnt lgkmcnt(0)
	s_barrier
	s_setprio 1
	s_waitcnt lgkmcnt(0)
	v_mfma_f32_16x16x32_bf16 v[62:65], v[150:153], v[188:191], v[62:65]
	v_mfma_f32_16x16x32_bf16 v[58:61], v[164:167], v[188:191], v[58:61]
	v_mfma_f32_16x16x32_bf16 v[38:41], v[150:153], v[196:199], v[38:41]
	v_mfma_f32_16x16x32_bf16 v[34:37], v[164:167], v[196:199], v[34:37]
	v_mfma_f32_16x16x32_bf16 v[22:25], v[150:153], v[204:207], v[22:25]
	v_mfma_f32_16x16x32_bf16 v[18:21], v[164:167], v[204:207], v[18:21]
	v_mfma_f32_16x16x32_bf16 v[6:9], v[150:153], v[212:215], v[6:9]
	v_mfma_f32_16x16x32_bf16 v[2:5], v[164:167], v[212:215], v[2:5]
	v_mfma_f32_16x16x32_bf16 v[62:65], v[160:163], v[192:195], v[62:65]
	v_mfma_f32_16x16x32_bf16 v[58:61], v[168:171], v[192:195], v[58:61]
	v_mfma_f32_16x16x32_bf16 v[38:41], v[160:163], v[200:203], v[38:41]
	v_mfma_f32_16x16x32_bf16 v[34:37], v[168:171], v[200:203], v[34:37]
	v_mfma_f32_16x16x32_bf16 v[22:25], v[160:163], v[208:211], v[22:25]
	v_mfma_f32_16x16x32_bf16 v[18:21], v[168:171], v[208:211], v[18:21]
	v_mfma_f32_16x16x32_bf16 v[6:9], v[160:163], v[216:219], v[6:9]
	v_mfma_f32_16x16x32_bf16 v[2:5], v[168:171], v[216:219], v[2:5]
	s_setprio 0
	s_setprio 1
	v_mfma_f32_16x16x32_bf16 v[54:57], v[172:175], v[188:191], v[54:57]
	v_mfma_f32_16x16x32_bf16 v[50:53], v[180:183], v[188:191], v[50:53]
	v_mfma_f32_16x16x32_bf16 v[42:45], v[172:175], v[196:199], v[42:45]
	v_mfma_f32_16x16x32_bf16 v[46:49], v[180:183], v[196:199], v[46:49]
	v_mfma_f32_16x16x32_bf16 v[26:29], v[172:175], v[204:207], v[26:29]
	v_mfma_f32_16x16x32_bf16 v[30:33], v[180:183], v[204:207], v[30:33]
	v_mfma_f32_16x16x32_bf16 v[10:13], v[172:175], v[212:215], v[10:13]
	v_mfma_f32_16x16x32_bf16 v[14:17], v[180:183], v[212:215], v[14:17]
	v_mfma_f32_16x16x32_bf16 v[54:57], v[176:179], v[192:195], v[54:57]
	v_mfma_f32_16x16x32_bf16 v[50:53], v[184:187], v[192:195], v[50:53]
	v_mfma_f32_16x16x32_bf16 v[42:45], v[176:179], v[200:203], v[42:45]
	v_mfma_f32_16x16x32_bf16 v[46:49], v[184:187], v[200:203], v[46:49]
	v_mfma_f32_16x16x32_bf16 v[26:29], v[176:179], v[208:211], v[26:29]
	v_mfma_f32_16x16x32_bf16 v[30:33], v[184:187], v[208:211], v[30:33]
	v_mfma_f32_16x16x32_bf16 v[10:13], v[176:179], v[216:219], v[10:13]
	v_mfma_f32_16x16x32_bf16 v[14:17], v[184:187], v[216:219], v[14:17]
	s_setprio 0
	s_barrier
; #define PG8_STAGE(bufoff, gbase, voff) do { _Pragma("unroll") for (int _i = 0; _i < 2; ++_i) \
;         __builtin_amdgcn_global_load_lds((const unsigned*)((const char*)(gbase) + (voff)[_i]), (LAS unsigned*)(lds + (bufoff) + ldsw + _i * 8192), 16, 0, 0); } while (0)
; #define PG8_LDA(dst, b, h) do { _Pragma("unroll") for (int m = 0; m < 4; ++m) _Pragma("unroll") for (int k = 0; k < 2; ++k) dst[m][k] = *(const LAS bf16x8*)(lds + PG8_SA(b, h) + aoff + m * 2048 + k * 1024); } while (0)
; #define PG8_LDB(dst, b, h) do { _Pragma("unroll") for (int n = 0; n < 2; ++n) _Pragma("unroll") for (int k = 0; k < 2; ++k) dst[n][k] = *(const LAS bf16x8*)(lds + PG8_SB(b, h) + boff + n * 2048 + k * 1024); } while (0)
; #define PG8_MMA(ai, bj, At, Bt) do { __builtin_amdgcn_s_setprio(1); _Pragma("unroll") for (int m = 0; m < 4; ++m) _Pragma("unroll") for (int n = 0; n < 2; ++n) _Pragma("unroll") for (int k = 0; k < 2; ++k) \
;         acc[ai][bj][m][n] = __builtin_amdgcn_mfma_f32_16x16x32_bf16(Bt[n][k], At[m][k], acc[ai][bj][m][n], 0, 0, 0); __builtin_amdgcn_s_setprio(0); } while (0)
; #define PG8_WAIT_V(n) asm volatile("s_waitcnt vmcnt(" #n ")" ::: "memory")
; #define PG8_WAIT_L(n) asm volatile("s_waitcnt lgkmcnt(" #n ")" ::: "memory")
; #define PG8_BAR __builtin_amdgcn_s_barrier()
; #define PG8_SCHED __builtin_amdgcn_sched_barrier(0)
; template <class Epi, bool ALIGN_EPI, bool SPLITA>
; __device__ __forceinline__ void gemm_phase(LAS unsigned char* lds, const Gemm g, const StaticOrder& S, const Epi& E) {
;     ...
;         for (int t = 0; t < nt; t += 2) {
;             const bool last = (t == nt - 2);
;     ...
;             PG8_LDB(B0, 1, 0); PG8_LDB(B1, 1, 1); PG8_SCHED; PG8_LDA(At, 1, 0); PG8_STAGE(PG8_SA(0, 1), a2h, vo2);
;             PG8_WAIT_V(8); PG8_WAIT_L(0); PG8_BAR; PG8_MMA(0, 0, At, B0); PG8_MMA(0, 1, At, B1); PG8_BAR; PG8_SCHED;
;             PG8_LDA(At, 1, 1); PG8_STAGE(PG8_SB(1, 0), b3, voffB); PG8_STAGE(PG8_SB(1, 1), b3 + hstepB, voffB); PG8_STAGE(PG8_SA(1, 0), a3, vo2);
;             PG8_WAIT_V(8); PG8_WAIT_L(0); PG8_BAR; PG8_MMA(1, 0, At, B0); PG8_MMA(1, 1, At, B1); PG8_BAR; PG8_SCHED;
	s_add_i32 s60, 0, 0x18000
	v_add_u32_e32 v149, s60, v154
	s_add_i32 s61, 0, 0x1c000
	ds_read_b128 v[150:153], v149
	ds_read_b128 v[160:163], v149 offset:1024
	ds_read_b128 v[164:167], v149 offset:2048
	ds_read_b128 v[168:171], v149 offset:3072
	v_add_u32_e32 v149, s61, v154
	ds_read_b128 v[172:175], v149
	ds_read_b128 v[176:179], v149 offset:1024
	ds_read_b128 v[180:183], v149 offset:2048
	ds_read_b128 v[184:187], v149 offset:3072
	s_add_u32 s12, s40, 0x40000
	s_addc_u32 s13, s41, 0
	s_mov_b32 m0, s44
	ds_read_b128 v[188:191], v157 offset:32768
	ds_read_b128 v[192:195], v157 offset:33792
	ds_read_b128 v[196:199], v157 offset:34816
	ds_read_b128 v[200:203], v157 offset:35840
	ds_read_b128 v[204:207], v157 offset:36864
	ds_read_b128 v[208:211], v157 offset:37888
	ds_read_b128 v[212:215], v157 offset:38912
	ds_read_b128 v[216:219], v157 offset:39936
	global_load_lds_dwordx4 v136, s[12:13]
	s_mov_b32 m0, s45
	s_nop 0
	global_load_lds_dwordx4 v132, s[12:13]
	s_waitcnt vmcnt(8)
	s_waitcnt lgkmcnt(0)
	s_barrier
	s_setprio 1
	s_waitcnt lgkmcnt(0)
	v_mfma_f32_16x16x32_bf16 v[126:129], v[150:153], v[188:191], v[126:129]
	v_mfma_f32_16x16x32_bf16 v[122:125], v[164:167], v[188:191], v[122:125]
	v_mfma_f32_16x16x32_bf16 v[110:113], v[150:153], v[196:199], v[110:113]
	v_mfma_f32_16x16x32_bf16 v[106:109], v[164:167], v[196:199], v[106:109]
	v_mfma_f32_16x16x32_bf16 v[94:97], v[150:153], v[204:207], v[94:97]
	v_mfma_f32_16x16x32_bf16 v[90:93], v[164:167], v[204:207], v[90:93]
	v_mfma_f32_16x16x32_bf16 v[78:81], v[150:153], v[212:215], v[78:81]
	v_mfma_f32_16x16x32_bf16 v[74:77], v[164:167], v[212:215], v[74:77]
	v_mfma_f32_16x16x32_bf16 v[126:129], v[160:163], v[192:195], v[126:129]
	v_mfma_f32_16x16x32_bf16 v[122:125], v[168:171], v[192:195], v[122:125]
	v_mfma_f32_16x16x32_bf16 v[110:113], v[160:163], v[200:203], v[110:113]
	v_mfma_f32_16x16x32_bf16 v[106:109], v[168:171], v[200:203], v[106:109]
	v_mfma_f32_16x16x32_bf16 v[94:97], v[160:163], v[208:211], v[94:97]
	v_mfma_f32_16x16x32_bf16 v[90:93], v[168:171], v[208:211], v[90:93]
	v_mfma_f32_16x16x32_bf16 v[78:81], v[160:163], v[216:219], v[78:81]
	v_mfma_f32_16x16x32_bf16 v[74:77], v[168:171], v[216:219], v[74:77]
	s_setprio 0
	s_setprio 1
	v_mfma_f32_16x16x32_bf16 v[118:121], v[172:175], v[188:191], v[118:121]
	v_mfma_f32_16x16x32_bf16 v[114:117], v[180:183], v[188:191], v[114:117]
	v_mfma_f32_16x16x32_bf16 v[102:105], v[172:175], v[196:199], v[102:105]
	v_mfma_f32_16x16x32_bf16 v[98:101], v[180:183], v[196:199], v[98:101]
	v_mfma_f32_16x16x32_bf16 v[86:89], v[172:175], v[204:207], v[86:89]
	v_mfma_f32_16x16x32_bf16 v[82:85], v[180:183], v[204:207], v[82:85]
	v_mfma_f32_16x16x32_bf16 v[70:73], v[172:175], v[212:215], v[70:73]
	v_mfma_f32_16x16x32_bf16 v[66:69], v[180:183], v[212:215], v[66:69]
	v_mfma_f32_16x16x32_bf16 v[118:121], v[176:179], v[192:195], v[118:121]
	v_mfma_f32_16x16x32_bf16 v[114:117], v[184:187], v[192:195], v[114:117]
	v_mfma_f32_16x16x32_bf16 v[102:105], v[176:179], v[200:203], v[102:105]
	v_mfma_f32_16x16x32_bf16 v[98:101], v[184:187], v[200:203], v[98:101]
	v_mfma_f32_16x16x32_bf16 v[86:89], v[176:179], v[208:211], v[86:89]
	v_mfma_f32_16x16x32_bf16 v[82:85], v[184:187], v[208:211], v[82:85]
	v_mfma_f32_16x16x32_bf16 v[70:73], v[176:179], v[216:219], v[70:73]
	v_mfma_f32_16x16x32_bf16 v[66:69], v[184:187], v[216:219], v[66:69]
	s_setprio 0
	s_barrier
	s_add_i32 s12, s60, s6
	s_mov_b32 m0, s12
	ds_read_b128 v[188:191], v157 offset:49152
	ds_read_b128 v[192:195], v157 offset:50176
	ds_read_b128 v[196:199], v157 offset:51200
	ds_read_b128 v[200:203], v157 offset:52224
	ds_read_b128 v[204:207], v157 offset:53248
	ds_read_b128 v[208:211], v157 offset:54272
	ds_read_b128 v[212:215], v157 offset:55296
	ds_read_b128 v[216:219], v157 offset:56320
	global_load_lds_dwordx4 v134, s[98:99]
	s_add_i32 m0, s12, 0x2000
	s_add_u32 s12, s38, 0x40800
	s_addc_u32 s13, s39, 0
	s_add_i32 s38, s61, s6
	global_load_lds_dwordx4 v130, s[98:99]
	s_mov_b32 m0, s38
	s_nop 0
	global_load_lds_dwordx4 v134, s[12:13]
	s_add_i32 m0, s38, 0x2000
	s_nop 0
	global_load_lds_dwordx4 v130, s[12:13]
	s_mov_b32 m0, s49
	s_nop 0
	global_load_lds_dwordx4 v136, s[100:101]
	s_mov_b32 m0, s50
	s_nop 0
	global_load_lds_dwordx4 v132, s[100:101]
	s_waitcnt vmcnt(8)
	s_waitcnt lgkmcnt(0)
	s_barrier
	s_setprio 1
	s_waitcnt lgkmcnt(0)
	v_mfma_f32_16x16x32_bf16 v[62:65], v[150:153], v[188:191], v[62:65]
	v_mfma_f32_16x16x32_bf16 v[58:61], v[164:167], v[188:191], v[58:61]
	v_mfma_f32_16x16x32_bf16 v[38:41], v[150:153], v[196:199], v[38:41]
	v_mfma_f32_16x16x32_bf16 v[34:37], v[164:167], v[196:199], v[34:37]
	v_mfma_f32_16x16x32_bf16 v[22:25], v[150:153], v[204:207], v[22:25]
	v_mfma_f32_16x16x32_bf16 v[18:21], v[164:167], v[204:207], v[18:21]
	v_mfma_f32_16x16x32_bf16 v[6:9], v[150:153], v[212:215], v[6:9]
	v_mfma_f32_16x16x32_bf16 v[2:5], v[164:167], v[212:215], v[2:5]
	v_mfma_f32_16x16x32_bf16 v[62:65], v[160:163], v[192:195], v[62:65]
	v_mfma_f32_16x16x32_bf16 v[58:61], v[168:171], v[192:195], v[58:61]
	v_mfma_f32_16x16x32_bf16 v[38:41], v[160:163], v[200:203], v[38:41]
	v_mfma_f32_16x16x32_bf16 v[34:37], v[168:171], v[200:203], v[34:37]
	v_mfma_f32_16x16x32_bf16 v[22:25], v[160:163], v[208:211], v[22:25]
	v_mfma_f32_16x16x32_bf16 v[18:21], v[168:171], v[208:211], v[18:21]
	v_mfma_f32_16x16x32_bf16 v[6:9], v[160:163], v[216:219], v[6:9]
	v_mfma_f32_16x16x32_bf16 v[2:5], v[168:171], v[216:219], v[2:5]
	s_setprio 0
	s_setprio 1
	v_mfma_f32_16x16x32_bf16 v[54:57], v[172:175], v[188:191], v[54:57]
	v_mfma_f32_16x16x32_bf16 v[50:53], v[180:183], v[188:191], v[50:53]
	v_mfma_f32_16x16x32_bf16 v[42:45], v[172:175], v[196:199], v[42:45]
	v_mfma_f32_16x16x32_bf16 v[46:49], v[180:183], v[196:199], v[46:49]
	v_mfma_f32_16x16x32_bf16 v[26:29], v[172:175], v[204:207], v[26:29]
	v_mfma_f32_16x16x32_bf16 v[30:33], v[180:183], v[204:207], v[30:33]
	v_mfma_f32_16x16x32_bf16 v[10:13], v[172:175], v[212:215], v[10:13]
	v_mfma_f32_16x16x32_bf16 v[14:17], v[180:183], v[212:215], v[14:17]
	v_mfma_f32_16x16x32_bf16 v[54:57], v[176:179], v[192:195], v[54:57]
	v_mfma_f32_16x16x32_bf16 v[50:53], v[184:187], v[192:195], v[50:53]
	v_mfma_f32_16x16x32_bf16 v[42:45], v[176:179], v[200:203], v[42:45]
	v_mfma_f32_16x16x32_bf16 v[46:49], v[184:187], v[200:203], v[46:49]
	v_mfma_f32_16x16x32_bf16 v[26:29], v[176:179], v[208:211], v[26:29]
	v_mfma_f32_16x16x32_bf16 v[30:33], v[184:187], v[208:211], v[30:33]
	v_mfma_f32_16x16x32_bf16 v[10:13], v[176:179], v[216:219], v[10:13]
	v_mfma_f32_16x16x32_bf16 v[14:17], v[184:187], v[216:219], v[14:17]
	s_setprio 0
	s_barrier
	s_add_i32 s57, s57, 2
	s_add_u32 s55, s55, 0x1000
	s_addc_u32 s56, s56, 0
	s_add_u32 s36, s36, 0x100
	s_addc_u32 s37, s37, 0
	s_cmp_gt_u32 s57, 13
	s_cbranch_scc0 .LBB0_796
	s_and_b64 vcc, exec, s[16:17]
	s_cbranch_vccz .LBB0_799
	s_barrier

; #define PG8_STAGE(bufoff, gbase, voff) do { _Pragma("unroll") for (int _i = 0; _i < 2; ++_i) \
;         __builtin_amdgcn_global_load_lds((const unsigned*)((const char*)(gbase) + (voff)[_i]), (LAS unsigned*)(lds + (bufoff) + ldsw + _i * 8192), 16, 0, 0); } while (0)
; #define PG8_LDA(dst, b, h) do { _Pragma("unroll") for (int m = 0; m < 4; ++m) _Pragma("unroll") for (int k = 0; k < 2; ++k) dst[m][k] = *(const LAS bf16x8*)(lds + PG8_SA(b, h) + aoff + m * 2048 + k * 1024); } while (0)
; #define PG8_LDB(dst, b, h) do { _Pragma("unroll") for (int n = 0; n < 2; ++n) _Pragma("unroll") for (int k = 0; k < 2; ++k) dst[n][k] = *(const LAS bf16x8*)(lds + PG8_SB(b, h) + boff + n * 2048 + k * 1024); } while (0)
; template <class Epi, bool ALIGN_EPI, bool SPLITA>
; __device__ __forceinline__ void gemm_phase(LAS unsigned char* lds, const Gemm g, const StaticOrder& S, const Epi& E) {
;     ...
;                 a1 = (t + 1 < g.ksplit) ? cA + (size_t)(t + 1) * kstep : cA2 + (size_t)(t + 1 - g.ksplit) * 2048;
;                 a2 = last ? nA : ((t + 2 < g.ksplit) ? cA + (size_t)(t + 2) * kstep : cA2 + (size_t)(t + 2 - g.ksplit) * 2048);
;             } else { a1 = cA + kofs(t + 1); a2 = last ? nA : cA + kofs(t + 2); }
;             const char* b2 = last ? nB : cB + (size_t)(t + 2) * kstepB;
;             const bool s2a = SPLITA && (t + 1 >= g.ksplit), s2b = SPLITA && !last && (t + 2 >= g.ksplit);
;             const char* a3 = a2 + ((Epi::KSUB || s2b) ? (size_t)2048 : kstep); const char* b3 = b2 + kstepB;
;             const bool m1 = SPLITA && mirC && (t + 1 < g.ksplit), m2 = SPLITA && (last ? mirN : (mirC && (t + 2 < g.ksplit)));
;             const unsigned vo1[2] = {s2a ? voffA2[0] : m1 ? voffAm[0] : voffA[0], s2a ? voffA2[1] : m1 ? voffAm[1] : voffA[1]}, vo2[2] = {s2b ? voffA2[0] : m2 ? voffAm[0] : voffA[0], s2b ? voffA2[1] : m2 ? voffAm[1] : voffA[1]};
;             const char* a1h = m1 ? a1 - hstepA : a1 + hstepA; const char* a2h = m2 ? a2 - hstepA : a2 + hstepA;
;             PG8_LDB(B0, 0, 0); PG8_LDB(B1, 0, 1); PG8_SCHED; PG8_LDA(At, 0, 0); PG8_STAGE(PG8_SA(1, 1), a1h, vo1);
;             PG8_WAIT_V(8); PG8_WAIT_L(0); PG8_BAR; PG8_MMA(0, 0, At, B0); PG8_MMA(0, 1, At, B1); PG8_BAR; PG8_SCHED;
;             PG8_LDA(At, 0, 1); PG8_STAGE(PG8_SB(0, 0), b2, voffB); PG8_STAGE(PG8_SB(0, 1), b2 + hstepB, voffB); PG8_STAGE(PG8_SA(0, 0), a2, vo2);
.LBB0_867:
	s_add_i32 s53, s28, 2
	s_lshr_b32 s2, s53, 2
	s_lshl_b64 s[12:13], s[2:3], 17
	s_add_i32 s2, s52, 0xfffff000
	s_and_b32 s2, s2, 0x1000
	s_add_u32 s12, s26, s12
	s_addc_u32 s13, s27, s13
	s_add_u32 s29, s12, s2
	s_addc_u32 s30, s13, 0
	s_add_i32 s2, s28, 4
	ds_read_b128 v[140:143], v151
	ds_read_b128 v[144:147], v151 offset:1024
	ds_read_b128 v[154:157], v151 offset:2048
	ds_read_b128 v[158:161], v151 offset:3072
	ds_read_b128 v[162:165], v152
	ds_read_b128 v[166:169], v152 offset:1024
	ds_read_b128 v[170:173], v152 offset:2048
	ds_read_b128 v[174:177], v152 offset:3072
	s_lshr_b32 s2, s2, 2
	s_lshl_b64 s[12:13], s[2:3], 17
	s_and_b32 s2, s52, 0x1000
	s_add_u32 s12, s26, s12
	s_addc_u32 s13, s27, s13
	s_add_u32 s2, s12, s2
	s_addc_u32 s31, s13, 0
	s_add_u32 s12, s29, 0x10800
	s_addc_u32 s13, s30, 0
	s_cmp_eq_u32 s28, 60
	s_cselect_b32 s28, s49, s50
	s_cselect_b32 s31, s17, s31
	s_cselect_b32 s30, s48, s2
	s_cselect_b32 s29, s19, s51
	s_add_i32 m0, s25, 0xc000
	ds_read_b128 v[178:181], v153
	ds_read_b128 v[182:185], v153 offset:1024
	ds_read_b128 v[186:189], v153 offset:2048
	ds_read_b128 v[190:193], v153 offset:3072
	ds_read_b128 v[194:197], v153 offset:4096
	ds_read_b128 v[198:201], v153 offset:5120
	ds_read_b128 v[202:205], v153 offset:6144
	ds_read_b128 v[206:209], v153 offset:7168
	global_load_lds_dwordx4 v134, s[12:13]
	s_add_i32 m0, s25, 0xe000
	s_nop 0
	global_load_lds_dwordx4 v130, s[12:13]
	s_waitcnt vmcnt(8)
	s_waitcnt lgkmcnt(0)
	s_barrier
	s_setprio 1
	s_waitcnt lgkmcnt(0)
	v_mfma_f32_16x16x32_bf16 v[124:127], v[140:143], v[178:181], v[124:127]
	v_mfma_f32_16x16x32_bf16 v[120:123], v[154:157], v[178:181], v[120:123]
	v_mfma_f32_16x16x32_bf16 v[108:111], v[140:143], v[186:189], v[108:111]
	v_mfma_f32_16x16x32_bf16 v[104:107], v[154:157], v[186:189], v[104:107]
	v_mfma_f32_16x16x32_bf16 v[96:99], v[140:143], v[194:197], v[96:99]
	v_mfma_f32_16x16x32_bf16 v[88:91], v[154:157], v[194:197], v[88:91]
	v_mfma_f32_16x16x32_bf16 v[80:83], v[140:143], v[202:205], v[80:83]
	v_mfma_f32_16x16x32_bf16 v[72:75], v[154:157], v[202:205], v[72:75]
	v_mfma_f32_16x16x32_bf16 v[124:127], v[144:147], v[182:185], v[124:127]
	v_mfma_f32_16x16x32_bf16 v[120:123], v[158:161], v[182:185], v[120:123]
	v_mfma_f32_16x16x32_bf16 v[108:111], v[144:147], v[190:193], v[108:111]
	v_mfma_f32_16x16x32_bf16 v[104:107], v[158:161], v[190:193], v[104:107]
	v_mfma_f32_16x16x32_bf16 v[96:99], v[144:147], v[198:201], v[96:99]
	v_mfma_f32_16x16x32_bf16 v[88:91], v[158:161], v[198:201], v[88:91]
	v_mfma_f32_16x16x32_bf16 v[80:83], v[144:147], v[206:209], v[80:83]
	v_mfma_f32_16x16x32_bf16 v[72:75], v[158:161], v[206:209], v[72:75]
	s_setprio 0
	s_setprio 1
	v_mfma_f32_16x16x32_bf16 v[116:119], v[162:165], v[178:181], v[116:119]
	v_mfma_f32_16x16x32_bf16 v[112:115], v[170:173], v[178:181], v[112:115]
	v_mfma_f32_16x16x32_bf16 v[100:103], v[162:165], v[186:189], v[100:103]
	v_mfma_f32_16x16x32_bf16 v[92:95], v[170:173], v[186:189], v[92:95]
	v_mfma_f32_16x16x32_bf16 v[84:87], v[162:165], v[194:197], v[84:87]
	v_mfma_f32_16x16x32_bf16 v[76:79], v[170:173], v[194:197], v[76:79]
	v_mfma_f32_16x16x32_bf16 v[68:71], v[162:165], v[202:205], v[68:71]
	v_mfma_f32_16x16x32_bf16 v[64:67], v[170:173], v[202:205], v[64:67]
	v_mfma_f32_16x16x32_bf16 v[116:119], v[166:169], v[182:185], v[116:119]
	v_mfma_f32_16x16x32_bf16 v[112:115], v[174:177], v[182:185], v[112:115]
	v_mfma_f32_16x16x32_bf16 v[100:103], v[166:169], v[190:193], v[100:103]
	v_mfma_f32_16x16x32_bf16 v[92:95], v[174:177], v[190:193], v[92:95]
	v_mfma_f32_16x16x32_bf16 v[84:87], v[166:169], v[198:201], v[84:87]
	v_mfma_f32_16x16x32_bf16 v[76:79], v[174:177], v[198:201], v[76:79]
	v_mfma_f32_16x16x32_bf16 v[68:71], v[166:169], v[206:209], v[68:71]
	v_mfma_f32_16x16x32_bf16 v[64:67], v[174:177], v[206:209], v[64:67]
	s_setprio 0
	s_barrier
	s_add_u32 s98, s28, s6
	s_addc_u32 s99, s29, s7
	s_add_u32 s100, s30, s8
	s_addc_u32 s101, s31, s9
	s_add_i32 s2, s44, s33
	s_mov_b32 m0, s2
	ds_read_b128 v[178:181], v153 offset:16384
	ds_read_b128 v[182:185], v153 offset:17408
	ds_read_b128 v[186:189], v153 offset:18432
	ds_read_b128 v[190:193], v153 offset:19456
	ds_read_b128 v[194:197], v153 offset:20480
	ds_read_b128 v[198:201], v153 offset:21504
	ds_read_b128 v[202:205], v153 offset:22528
	ds_read_b128 v[206:209], v153 offset:23552
	global_load_lds_dwordx4 v132, s[28:29]
	s_add_i32 m0, s2, 0x2000
	s_add_u32 s12, s28, 0x100000
	s_addc_u32 s13, s29, 0
	s_add_i32 s2, s45, s33
	global_load_lds_dwordx4 v128, s[28:29]
	s_mov_b32 m0, s2
	s_nop 0
	global_load_lds_dwordx4 v132, s[12:13]
	s_add_i32 m0, s2, 0x2000
	s_nop 0
	global_load_lds_dwordx4 v128, s[12:13]
	s_mov_b32 m0, s25
	s_nop 0
	global_load_lds_dwordx4 v134, s[30:31]
	s_mov_b32 m0, s38
	s_nop 0
	global_load_lds_dwordx4 v130, s[30:31]
	s_waitcnt vmcnt(8)
	s_waitcnt lgkmcnt(0)
	s_barrier
; #define PG8_STAGE(bufoff, gbase, voff) do { _Pragma("unroll") for (int _i = 0; _i < 2; ++_i) \
;         __builtin_amdgcn_global_load_lds((const unsigned*)((const char*)(gbase) + (voff)[_i]), (LAS unsigned*)(lds + (bufoff) + ldsw + _i * 8192), 16, 0, 0); } while (0)
; #define PG8_LDA(dst, b, h) do { _Pragma("unroll") for (int m = 0; m < 4; ++m) _Pragma("unroll") for (int k = 0; k < 2; ++k) dst[m][k] = *(const LAS bf16x8*)(lds + PG8_SA(b, h) + aoff + m * 2048 + k * 1024); } while (0)
; #define PG8_LDB(dst, b, h) do { _Pragma("unroll") for (int n = 0; n < 2; ++n) _Pragma("unroll") for (int k = 0; k < 2; ++k) dst[n][k] = *(const LAS bf16x8*)(lds + PG8_SB(b, h) + boff + n * 2048 + k * 1024); } while (0)
; #define PG8_MMA(ai, bj, At, Bt) do { __builtin_amdgcn_s_setprio(1); _Pragma("unroll") for (int m = 0; m < 4; ++m) _Pragma("unroll") for (int n = 0; n < 2; ++n) _Pragma("unroll") for (int k = 0; k < 2; ++k) \
;         acc[ai][bj][m][n] = __builtin_amdgcn_mfma_f32_16x16x32_bf16(Bt[n][k], At[m][k], acc[ai][bj][m][n], 0, 0, 0); __builtin_amdgcn_s_setprio(0); } while (0)
; #define PG8_WAIT_V(n) asm volatile("s_waitcnt vmcnt(" #n ")" ::: "memory")
; #define PG8_WAIT_L(n) asm volatile("s_waitcnt lgkmcnt(" #n ")" ::: "memory")
; #define PG8_BAR __builtin_amdgcn_s_barrier()
; #define PG8_SCHED __builtin_amdgcn_sched_barrier(0)
; template <class Epi, bool ALIGN_EPI, bool SPLITA>
; __device__ __forceinline__ void gemm_phase(LAS unsigned char* lds, const Gemm g, const StaticOrder& S, const Epi& E) {
;     ...
;             PG8_WAIT_V(8); PG8_WAIT_L(0); PG8_BAR; PG8_MMA(1, 0, At, B0); PG8_MMA(1, 1, At, B1); PG8_BAR; PG8_SCHED;
;             PG8_LDB(B0, 1, 0); PG8_LDB(B1, 1, 1); PG8_SCHED; PG8_LDA(At, 1, 0); PG8_STAGE(PG8_SA(0, 1), a2h, vo2);
;             PG8_WAIT_V(8); PG8_WAIT_L(0); PG8_BAR; PG8_MMA(0, 0, At, B0); PG8_MMA(0, 1, At, B1); PG8_BAR; PG8_SCHED;
	s_setprio 1
	s_waitcnt lgkmcnt(0)
	v_mfma_f32_16x16x32_bf16 v[60:63], v[140:143], v[178:181], v[60:63]
	v_mfma_f32_16x16x32_bf16 v[56:59], v[154:157], v[178:181], v[56:59]
	v_mfma_f32_16x16x32_bf16 v[40:43], v[140:143], v[186:189], v[40:43]
	v_mfma_f32_16x16x32_bf16 v[32:35], v[154:157], v[186:189], v[32:35]
	v_mfma_f32_16x16x32_bf16 v[20:23], v[140:143], v[194:197], v[20:23]
	v_mfma_f32_16x16x32_bf16 v[8:11], v[154:157], v[194:197], v[8:11]
	v_mfma_f32_16x16x32_bf16 v[4:7], v[140:143], v[202:205], v[4:7]
	v_mfma_f32_16x16x32_bf16 v[0:3], v[154:157], v[202:205], v[0:3]
	v_mfma_f32_16x16x32_bf16 v[60:63], v[144:147], v[182:185], v[60:63]
	v_mfma_f32_16x16x32_bf16 v[56:59], v[158:161], v[182:185], v[56:59]
	v_mfma_f32_16x16x32_bf16 v[40:43], v[144:147], v[190:193], v[40:43]
	v_mfma_f32_16x16x32_bf16 v[32:35], v[158:161], v[190:193], v[32:35]
	v_mfma_f32_16x16x32_bf16 v[20:23], v[144:147], v[198:201], v[20:23]
	v_mfma_f32_16x16x32_bf16 v[8:11], v[158:161], v[198:201], v[8:11]
	v_mfma_f32_16x16x32_bf16 v[4:7], v[144:147], v[206:209], v[4:7]
	v_mfma_f32_16x16x32_bf16 v[0:3], v[158:161], v[206:209], v[0:3]
	s_setprio 0
	s_setprio 1
	v_mfma_f32_16x16x32_bf16 v[44:47], v[162:165], v[178:181], v[44:47]
	v_mfma_f32_16x16x32_bf16 v[36:39], v[170:173], v[178:181], v[36:39]
	v_mfma_f32_16x16x32_bf16 v[52:55], v[162:165], v[186:189], v[52:55]
	v_mfma_f32_16x16x32_bf16 v[48:51], v[170:173], v[186:189], v[48:51]
	v_mfma_f32_16x16x32_bf16 v[28:31], v[162:165], v[194:197], v[28:31]
	v_mfma_f32_16x16x32_bf16 v[24:27], v[170:173], v[194:197], v[24:27]
	v_mfma_f32_16x16x32_bf16 v[16:19], v[162:165], v[202:205], v[16:19]
	v_mfma_f32_16x16x32_bf16 v[12:15], v[170:173], v[202:205], v[12:15]
	v_mfma_f32_16x16x32_bf16 v[44:47], v[166:169], v[182:185], v[44:47]
	v_mfma_f32_16x16x32_bf16 v[36:39], v[174:177], v[182:185], v[36:39]
	v_mfma_f32_16x16x32_bf16 v[52:55], v[166:169], v[190:193], v[52:55]
	v_mfma_f32_16x16x32_bf16 v[48:51], v[174:177], v[190:193], v[48:51]
	v_mfma_f32_16x16x32_bf16 v[28:31], v[166:169], v[198:201], v[28:31]
	v_mfma_f32_16x16x32_bf16 v[24:27], v[174:177], v[198:201], v[24:27]
	v_mfma_f32_16x16x32_bf16 v[16:19], v[166:169], v[206:209], v[16:19]
	v_mfma_f32_16x16x32_bf16 v[12:15], v[174:177], v[206:209], v[12:15]
	s_setprio 0
	s_barrier
	s_add_i32 s2, 0, 0x18000
	s_add_i32 s54, 0, 0x1c000
	v_add_u32_e32 v158, s2, v149
	v_add_u32_e32 v174, s54, v149
	ds_read_b128 v[140:143], v158
	ds_read_b128 v[144:147], v158 offset:1024
	ds_read_b128 v[154:157], v158 offset:2048
	ds_read_b128 v[158:161], v158 offset:3072
	ds_read_b128 v[162:165], v174
	ds_read_b128 v[166:169], v174 offset:1024
	ds_read_b128 v[170:173], v174 offset:2048
	ds_read_b128 v[174:177], v174 offset:3072
	s_add_u32 s12, s30, 0x10000
	s_addc_u32 s13, s31, 0
	s_mov_b32 m0, s39
	ds_read_b128 v[178:181], v153 offset:32768
	ds_read_b128 v[182:185], v153 offset:33792
	ds_read_b128 v[186:189], v153 offset:34816
	ds_read_b128 v[190:193], v153 offset:35840
	ds_read_b128 v[194:197], v153 offset:36864
	ds_read_b128 v[198:201], v153 offset:37888
	ds_read_b128 v[202:205], v153 offset:38912
	ds_read_b128 v[206:209], v153 offset:39936
	global_load_lds_dwordx4 v134, s[12:13]
	s_mov_b32 m0, s40
	s_nop 0
	global_load_lds_dwordx4 v130, s[12:13]
	s_waitcnt vmcnt(8)
	s_waitcnt lgkmcnt(0)
	s_barrier
	s_setprio 1
	s_waitcnt lgkmcnt(0)
	v_mfma_f32_16x16x32_bf16 v[124:127], v[140:143], v[178:181], v[124:127]
	v_mfma_f32_16x16x32_bf16 v[120:123], v[154:157], v[178:181], v[120:123]
	v_mfma_f32_16x16x32_bf16 v[108:111], v[140:143], v[186:189], v[108:111]
	v_mfma_f32_16x16x32_bf16 v[104:107], v[154:157], v[186:189], v[104:107]
	v_mfma_f32_16x16x32_bf16 v[96:99], v[140:143], v[194:197], v[96:99]
	v_mfma_f32_16x16x32_bf16 v[88:91], v[154:157], v[194:197], v[88:91]
	v_mfma_f32_16x16x32_bf16 v[80:83], v[140:143], v[202:205], v[80:83]
	v_mfma_f32_16x16x32_bf16 v[72:75], v[154:157], v[202:205], v[72:75]
	v_mfma_f32_16x16x32_bf16 v[124:127], v[144:147], v[182:185], v[124:127]
	v_mfma_f32_16x16x32_bf16 v[120:123], v[158:161], v[182:185], v[120:123]
	v_mfma_f32_16x16x32_bf16 v[108:111], v[144:147], v[190:193], v[108:111]
	v_mfma_f32_16x16x32_bf16 v[104:107], v[158:161], v[190:193], v[104:107]
	v_mfma_f32_16x16x32_bf16 v[96:99], v[144:147], v[198:201], v[96:99]
	v_mfma_f32_16x16x32_bf16 v[88:91], v[158:161], v[198:201], v[88:91]
	v_mfma_f32_16x16x32_bf16 v[80:83], v[144:147], v[206:209], v[80:83]
	v_mfma_f32_16x16x32_bf16 v[72:75], v[158:161], v[206:209], v[72:75]
	s_setprio 0
	s_setprio 1
	v_mfma_f32_16x16x32_bf16 v[116:119], v[162:165], v[178:181], v[116:119]
	v_mfma_f32_16x16x32_bf16 v[112:115], v[170:173], v[178:181], v[112:115]
	v_mfma_f32_16x16x32_bf16 v[100:103], v[162:165], v[186:189], v[100:103]
	v_mfma_f32_16x16x32_bf16 v[92:95], v[170:173], v[186:189], v[92:95]
	v_mfma_f32_16x16x32_bf16 v[84:87], v[162:165], v[194:197], v[84:87]
	v_mfma_f32_16x16x32_bf16 v[76:79], v[170:173], v[194:197], v[76:79]
	v_mfma_f32_16x16x32_bf16 v[68:71], v[162:165], v[202:205], v[68:71]
	v_mfma_f32_16x16x32_bf16 v[64:67], v[170:173], v[202:205], v[64:67]
	v_mfma_f32_16x16x32_bf16 v[116:119], v[166:169], v[182:185], v[116:119]
	v_mfma_f32_16x16x32_bf16 v[112:115], v[174:177], v[182:185], v[112:115]
	v_mfma_f32_16x16x32_bf16 v[100:103], v[166:169], v[190:193], v[100:103]
	v_mfma_f32_16x16x32_bf16 v[92:95], v[174:177], v[190:193], v[92:95]
	v_mfma_f32_16x16x32_bf16 v[84:87], v[166:169], v[198:201], v[84:87]
	v_mfma_f32_16x16x32_bf16 v[76:79], v[174:177], v[198:201], v[76:79]
	v_mfma_f32_16x16x32_bf16 v[68:71], v[166:169], v[206:209], v[68:71]
	v_mfma_f32_16x16x32_bf16 v[64:67], v[174:177], v[206:209], v[64:67]
	s_setprio 0
	s_barrier
; #define PG8_STAGE(bufoff, gbase, voff) do { _Pragma("unroll") for (int _i = 0; _i < 2; ++_i) \
;         __builtin_amdgcn_global_load_lds((const unsigned*)((const char*)(gbase) + (voff)[_i]), (LAS unsigned*)(lds + (bufoff) + ldsw + _i * 8192), 16, 0, 0); } while (0)
; #define PG8_LDA(dst, b, h) do { _Pragma("unroll") for (int m = 0; m < 4; ++m) _Pragma("unroll") for (int k = 0; k < 2; ++k) dst[m][k] = *(const LAS bf16x8*)(lds + PG8_SA(b, h) + aoff + m * 2048 + k * 1024); } while (0)
; #define PG8_MMA(ai, bj, At, Bt) do { __builtin_amdgcn_s_setprio(1); _Pragma("unroll") for (int m = 0; m < 4; ++m) _Pragma("unroll") for (int n = 0; n < 2; ++n) _Pragma("unroll") for (int k = 0; k < 2; ++k) \
;         acc[ai][bj][m][n] = __builtin_amdgcn_mfma_f32_16x16x32_bf16(Bt[n][k], At[m][k], acc[ai][bj][m][n], 0, 0, 0); __builtin_amdgcn_s_setprio(0); } while (0)
; #define PG8_WAIT_V(n) asm volatile("s_waitcnt vmcnt(" #n ")" ::: "memory")
; #define PG8_WAIT_L(n) asm volatile("s_waitcnt lgkmcnt(" #n ")" ::: "memory")
; #define PG8_BAR __builtin_amdgcn_s_barrier()
; #define PG8_SCHED __builtin_amdgcn_sched_barrier(0)
; template <class Epi, bool ALIGN_EPI, bool SPLITA>
; __device__ __forceinline__ void gemm_phase(LAS unsigned char* lds, const Gemm g, const StaticOrder& S, const Epi& E) {
;     ...
;         for (int t = 0; t < nt; t += 2) {
;             const bool last = (t == nt - 2);
;     ...
;             PG8_LDA(At, 1, 1); PG8_STAGE(PG8_SB(1, 0), b3, voffB); PG8_STAGE(PG8_SB(1, 1), b3 + hstepB, voffB); PG8_STAGE(PG8_SA(1, 0), a3, vo2);
;             PG8_WAIT_V(8); PG8_WAIT_L(0); PG8_BAR; PG8_MMA(1, 0, At, B0); PG8_MMA(1, 1, At, B1); PG8_BAR; PG8_SCHED;
	s_add_i32 s2, s2, s33
	s_mov_b32 m0, s2
	ds_read_b128 v[178:181], v153 offset:49152
	ds_read_b128 v[182:185], v153 offset:50176
	ds_read_b128 v[186:189], v153 offset:51200
	ds_read_b128 v[190:193], v153 offset:52224
	ds_read_b128 v[194:197], v153 offset:53248
	ds_read_b128 v[198:201], v153 offset:54272
	ds_read_b128 v[202:205], v153 offset:55296
	ds_read_b128 v[206:209], v153 offset:56320
	global_load_lds_dwordx4 v132, s[98:99]
	s_add_i32 m0, s2, 0x2000
	s_add_u32 s12, s28, 0x100080
	s_addc_u32 s13, s29, 0
	s_add_i32 s2, s54, s33
	global_load_lds_dwordx4 v128, s[98:99]
	s_mov_b32 m0, s2
	s_nop 0
	global_load_lds_dwordx4 v132, s[12:13]
	s_add_i32 m0, s2, 0x2000
	s_nop 0
	global_load_lds_dwordx4 v128, s[12:13]
	s_mov_b32 m0, s41
	s_nop 0
	global_load_lds_dwordx4 v134, s[100:101]
	s_mov_b32 m0, s42
	s_nop 0
	global_load_lds_dwordx4 v130, s[100:101]
	s_waitcnt vmcnt(8)
	s_waitcnt lgkmcnt(0)
	s_barrier
	s_setprio 1
	s_waitcnt lgkmcnt(0)
	v_mfma_f32_16x16x32_bf16 v[60:63], v[140:143], v[178:181], v[60:63]
	v_mfma_f32_16x16x32_bf16 v[56:59], v[154:157], v[178:181], v[56:59]
	v_mfma_f32_16x16x32_bf16 v[40:43], v[140:143], v[186:189], v[40:43]
	v_mfma_f32_16x16x32_bf16 v[32:35], v[154:157], v[186:189], v[32:35]
	v_mfma_f32_16x16x32_bf16 v[20:23], v[140:143], v[194:197], v[20:23]
	v_mfma_f32_16x16x32_bf16 v[8:11], v[154:157], v[194:197], v[8:11]
	v_mfma_f32_16x16x32_bf16 v[4:7], v[140:143], v[202:205], v[4:7]
	v_mfma_f32_16x16x32_bf16 v[0:3], v[154:157], v[202:205], v[0:3]
	v_mfma_f32_16x16x32_bf16 v[60:63], v[144:147], v[182:185], v[60:63]
	v_mfma_f32_16x16x32_bf16 v[56:59], v[158:161], v[182:185], v[56:59]
	v_mfma_f32_16x16x32_bf16 v[40:43], v[144:147], v[190:193], v[40:43]
	v_mfma_f32_16x16x32_bf16 v[32:35], v[158:161], v[190:193], v[32:35]
	v_mfma_f32_16x16x32_bf16 v[20:23], v[144:147], v[198:201], v[20:23]
	v_mfma_f32_16x16x32_bf16 v[8:11], v[158:161], v[198:201], v[8:11]
	v_mfma_f32_16x16x32_bf16 v[4:7], v[144:147], v[206:209], v[4:7]
	v_mfma_f32_16x16x32_bf16 v[0:3], v[158:161], v[206:209], v[0:3]
	s_setprio 0
	s_setprio 1
	v_mfma_f32_16x16x32_bf16 v[44:47], v[162:165], v[178:181], v[44:47]
	v_mfma_f32_16x16x32_bf16 v[36:39], v[170:173], v[178:181], v[36:39]
	v_mfma_f32_16x16x32_bf16 v[52:55], v[162:165], v[186:189], v[52:55]
	v_mfma_f32_16x16x32_bf16 v[48:51], v[170:173], v[186:189], v[48:51]
	v_mfma_f32_16x16x32_bf16 v[28:31], v[162:165], v[194:197], v[28:31]
	v_mfma_f32_16x16x32_bf16 v[24:27], v[170:173], v[194:197], v[24:27]
	v_mfma_f32_16x16x32_bf16 v[16:19], v[162:165], v[202:205], v[16:19]
	v_mfma_f32_16x16x32_bf16 v[12:15], v[170:173], v[202:205], v[12:15]
	v_mfma_f32_16x16x32_bf16 v[44:47], v[166:169], v[182:185], v[44:47]
	v_mfma_f32_16x16x32_bf16 v[36:39], v[174:177], v[182:185], v[36:39]
	v_mfma_f32_16x16x32_bf16 v[52:55], v[166:169], v[190:193], v[52:55]
	v_mfma_f32_16x16x32_bf16 v[48:51], v[174:177], v[190:193], v[48:51]
	v_mfma_f32_16x16x32_bf16 v[28:31], v[166:169], v[198:201], v[28:31]
	v_mfma_f32_16x16x32_bf16 v[24:27], v[174:177], v[198:201], v[24:27]
	v_mfma_f32_16x16x32_bf16 v[16:19], v[166:169], v[206:209], v[16:19]
	v_mfma_f32_16x16x32_bf16 v[12:15], v[174:177], v[206:209], v[12:15]
	s_setprio 0
	s_barrier
	s_add_u32 s50, s50, 0x100
	s_addc_u32 s51, s51, 0
	s_addk_i32 s52, 0x1000
	s_cmp_gt_u32 s53, 61
	s_mov_b32 s28, s53
	s_cbranch_scc0 .LBB0_867
	s_and_b64 vcc, exec, s[10:11]
	s_cbranch_vccz .LBB0_870
	s_barrier
